# K-loop LDS-DMA loads use SGPR-base+32bit-voffset addressing in 8 GEMM loops (removes 16 v_lshl_add_u64 per iteration); plus hoisted ss loads
# speedup vs baseline: 1.0105x; 1.0060x over previous
; #define PG8_STAGE(bufoff, gbase, voff) do { _Pragma("unroll") for (int _i = 0; _i < 2; ++_i) \
;         __builtin_amdgcn_global_load_lds((const unsigned*)((const char*)(gbase) + (voff)[_i]), (LAS unsigned*)(lds + (bufoff) + ldsw + _i * 8192), 16, 0, 0); } while (0)
; #define PG8_LDA(dst, b, h) do { _Pragma("unroll") for (int m = 0; m < 4; ++m) _Pragma("unroll") for (int k = 0; k < 2; ++k) dst[m][k] = *(const LAS bf16x8*)(lds + PG8_SA(b, h) + aoff + m * 2048 + k * 1024); } while (0)
; #define PG8_LDB(dst, b, h) do { _Pragma("unroll") for (int n = 0; n < 2; ++n) _Pragma("unroll") for (int k = 0; k < 2; ++k) dst[n][k] = *(const LAS bf16x8*)(lds + PG8_SB(b, h) + boff + n * 2048 + k * 1024); } while (0)
; #define PG8_WAIT_V(n) asm volatile("s_waitcnt vmcnt(" #n ")" ::: "memory")
; template <class Epi, class Sched, bool SP2 = PG8_SP2>
; __device__ __forceinline__ void gemm_phase(LAS unsigned char* lds, const Gemm g, const Sched& S, const Epi& E) {
;     ...
;         for (int t = 0; t < nt; t += 2) {
;             const bool last = (t == nt - 2);
;             const char* a1 = cA + (size_t)(t + 1) * kstep;
;             const char* a2 = last ? nA : cA + (size_t)(t + 2) * kstep; const char* b2 = last ? nB : cB + (size_t)(t + 2) * kstep;
;             const char* a3 = a2 + kstep; const char* b3 = b2 + kstep;
;             if constexpr (SP2) {
;             PG8_LDB(B0, 0, 0); PG8_LDB(B1, 0, 1); PG8_SCHED; PG8_LDA(At, 0, 0); PG8_STAGE(PG8_SA(1, 1), a1 + hstepA, voffA);
;             PG8_WAIT_V(8); PG8_WAIT_L(0); PG8_BAR; PG8_MMA(0, 0, At, B0); PG8_MMA(0, 1, At, B1); PG8_BAR; PG8_SCHED;
;             PG8_LDA(At, 0, 1); PG8_STAGE(PG8_SB(0, 0), b2, voffB); PG8_STAGE(PG8_SB(0, 1), b2 + hstepB, voffB); PG8_STAGE(PG8_SA(0, 0), a2, voffA);
;             PG8_WAIT_V(8); PG8_WAIT_L(0); PG8_BAR; PG8_MMA(1, 0, At, B0); PG8_MMA(1, 1, At, B1); PG8_BAR; PG8_SCHED;
;             PG8_LDB(B0, 1, 0); PG8_LDB(B1, 1, 1); PG8_SCHED; PG8_LDA(At, 1, 0); PG8_STAGE(PG8_SA(0, 1), a2 + hstepA, voffA);
;             PG8_WAIT_V(8); PG8_WAIT_L(0); PG8_BAR; PG8_MMA(0, 0, At, B0); PG8_MMA(0, 1, At, B1); PG8_BAR; PG8_SCHED;
;             PG8_LDA(At, 1, 1); PG8_STAGE(PG8_SB(1, 0), b3, voffB); PG8_STAGE(PG8_SB(1, 1), b3 + hstepB, voffB); PG8_STAGE(PG8_SA(1, 0), a3, voffA);
;             PG8_WAIT_V(8); PG8_WAIT_L(0); PG8_BAR; PG8_MMA(1, 0, At, B0); PG8_MMA(1, 1, At, B1); PG8_BAR; PG8_SCHED;
.LBB0_153:
	ds_read_b128 v[144:147], v152
	ds_read_b128 v[156:159], v152 offset:1024
	ds_read_b128 v[160:163], v152 offset:2048
	ds_read_b128 v[164:167], v152 offset:3072
	ds_read_b128 v[168:171], v153
	ds_read_b128 v[172:175], v153 offset:1024
	ds_read_b128 v[176:179], v153 offset:2048
	ds_read_b128 v[180:183], v153 offset:3072
	s_add_u32 s3, s0, 0xfff80080
	s_addc_u32 s44, s1, -1
	s_cmp_eq_u32 s67, 28
	s_cselect_b32 s47, s2, s44
	s_cselect_b32 s46, s9, s3
	s_cselect_b32 s45, s35, s66
	s_cselect_b32 s44, s37, s43
	s_add_i32 m0, s53, 0xc000
	ds_read_b128 v[184:187], v154
	ds_read_b128 v[188:191], v154 offset:1024
	ds_read_b128 v[192:195], v154 offset:2048
	ds_read_b128 v[196:199], v154 offset:3072
	ds_read_b128 v[200:203], v154 offset:4096
	ds_read_b128 v[204:207], v154 offset:5120
	ds_read_b128 v[208:211], v154 offset:6144
	ds_read_b128 v[212:215], v154 offset:7168
	global_load_lds_dwordx4 v136, s[0:1]
	s_add_i32 m0, s53, 0xe000
	s_nop 0
	global_load_lds_dwordx4 v138, s[0:1]
	s_waitcnt vmcnt(8)
	s_waitcnt lgkmcnt(0)
	s_barrier
	s_setprio 1
	s_waitcnt lgkmcnt(0)
	v_mfma_f32_16x16x32_bf16 v[124:127], v[144:147], v[184:187], v[124:127]
	v_mfma_f32_16x16x32_bf16 v[120:123], v[160:163], v[184:187], v[120:123]
	v_mfma_f32_16x16x32_bf16 v[108:111], v[144:147], v[192:195], v[108:111]
	v_mfma_f32_16x16x32_bf16 v[104:107], v[160:163], v[192:195], v[104:107]
	v_mfma_f32_16x16x32_bf16 v[92:95], v[144:147], v[200:203], v[92:95]
	v_mfma_f32_16x16x32_bf16 v[88:91], v[160:163], v[200:203], v[88:91]
	v_mfma_f32_16x16x32_bf16 v[76:79], v[144:147], v[208:211], v[76:79]
	v_mfma_f32_16x16x32_bf16 v[72:75], v[160:163], v[208:211], v[72:75]
	v_mfma_f32_16x16x32_bf16 v[124:127], v[156:159], v[188:191], v[124:127]
	v_mfma_f32_16x16x32_bf16 v[120:123], v[164:167], v[188:191], v[120:123]
	v_mfma_f32_16x16x32_bf16 v[108:111], v[156:159], v[196:199], v[108:111]
	v_mfma_f32_16x16x32_bf16 v[104:107], v[164:167], v[196:199], v[104:107]
	v_mfma_f32_16x16x32_bf16 v[92:95], v[156:159], v[204:207], v[92:95]
	v_mfma_f32_16x16x32_bf16 v[88:91], v[164:167], v[204:207], v[88:91]
	v_mfma_f32_16x16x32_bf16 v[76:79], v[156:159], v[212:215], v[76:79]
	v_mfma_f32_16x16x32_bf16 v[72:75], v[164:167], v[212:215], v[72:75]
	s_setprio 0
	s_setprio 1
	v_mfma_f32_16x16x32_bf16 v[116:119], v[168:171], v[184:187], v[116:119]
	v_mfma_f32_16x16x32_bf16 v[112:115], v[176:179], v[184:187], v[112:115]
	v_mfma_f32_16x16x32_bf16 v[100:103], v[168:171], v[192:195], v[100:103]
	v_mfma_f32_16x16x32_bf16 v[96:99], v[176:179], v[192:195], v[96:99]
	v_mfma_f32_16x16x32_bf16 v[84:87], v[168:171], v[200:203], v[84:87]
	v_mfma_f32_16x16x32_bf16 v[80:83], v[176:179], v[200:203], v[80:83]
	v_mfma_f32_16x16x32_bf16 v[68:71], v[168:171], v[208:211], v[68:71]
	v_mfma_f32_16x16x32_bf16 v[64:67], v[176:179], v[208:211], v[64:67]
	v_mfma_f32_16x16x32_bf16 v[116:119], v[172:175], v[188:191], v[116:119]
	v_mfma_f32_16x16x32_bf16 v[112:115], v[180:183], v[188:191], v[112:115]
	v_mfma_f32_16x16x32_bf16 v[100:103], v[172:175], v[196:199], v[100:103]
	v_mfma_f32_16x16x32_bf16 v[96:99], v[180:183], v[196:199], v[96:99]
	v_mfma_f32_16x16x32_bf16 v[84:87], v[172:175], v[204:207], v[84:87]
	v_mfma_f32_16x16x32_bf16 v[80:83], v[180:183], v[204:207], v[80:83]
	v_mfma_f32_16x16x32_bf16 v[68:71], v[172:175], v[212:215], v[68:71]
	v_mfma_f32_16x16x32_bf16 v[64:67], v[180:183], v[212:215], v[64:67]
	s_setprio 0
	s_barrier
	s_add_i32 s3, s62, s52
	s_add_u32 s98, s44, s22
	s_addc_u32 s99, s45, s23
	s_mov_b32 m0, s3
	ds_read_b128 v[184:187], v154 offset:16384
	ds_read_b128 v[188:191], v154 offset:17408
	ds_read_b128 v[192:195], v154 offset:18432
	ds_read_b128 v[196:199], v154 offset:19456
	ds_read_b128 v[200:203], v154 offset:20480
	ds_read_b128 v[204:207], v154 offset:21504
	ds_read_b128 v[208:211], v154 offset:22528
	ds_read_b128 v[212:215], v154 offset:23552
	global_load_lds_dwordx4 v130, s[44:45]
	s_add_i32 m0, s3, 0x2000
	s_add_u32 s68, s44, 0x80000
	s_addc_u32 s69, s45, 0
	s_add_i32 s3, s63, s52
	global_load_lds_dwordx4 v134, s[44:45]
	s_mov_b32 m0, s3
	s_nop 0
	global_load_lds_dwordx4 v130, s[68:69]
	s_add_i32 m0, s3, 0x2000
	s_nop 0
	global_load_lds_dwordx4 v134, s[68:69]
	s_add_u32 s100, s46, s22
	s_addc_u32 s101, s47, s23
	s_mov_b32 m0, s53
	s_nop 0
	global_load_lds_dwordx4 v128, s[46:47]
	s_mov_b32 m0, s54
	s_nop 0
	global_load_lds_dwordx4 v132, s[46:47]
	s_waitcnt vmcnt(8)
	s_waitcnt lgkmcnt(0)
	s_barrier
	s_setprio 1
	s_waitcnt lgkmcnt(0)
	v_mfma_f32_16x16x32_bf16 v[60:63], v[144:147], v[184:187], v[60:63]
	v_mfma_f32_16x16x32_bf16 v[56:59], v[160:163], v[184:187], v[56:59]
	v_mfma_f32_16x16x32_bf16 v[44:47], v[144:147], v[192:195], v[44:47]
	v_mfma_f32_16x16x32_bf16 v[40:43], v[160:163], v[192:195], v[40:43]
	v_mfma_f32_16x16x32_bf16 v[28:31], v[144:147], v[200:203], v[28:31]
	v_mfma_f32_16x16x32_bf16 v[24:27], v[160:163], v[200:203], v[24:27]
	v_mfma_f32_16x16x32_bf16 v[12:15], v[144:147], v[208:211], v[12:15]
	v_mfma_f32_16x16x32_bf16 v[8:11], v[160:163], v[208:211], v[8:11]
	v_mfma_f32_16x16x32_bf16 v[60:63], v[156:159], v[188:191], v[60:63]
	v_mfma_f32_16x16x32_bf16 v[56:59], v[164:167], v[188:191], v[56:59]
	v_mfma_f32_16x16x32_bf16 v[44:47], v[156:159], v[196:199], v[44:47]
	v_mfma_f32_16x16x32_bf16 v[40:43], v[164:167], v[196:199], v[40:43]
	v_mfma_f32_16x16x32_bf16 v[28:31], v[156:159], v[204:207], v[28:31]
	v_mfma_f32_16x16x32_bf16 v[24:27], v[164:167], v[204:207], v[24:27]
	v_mfma_f32_16x16x32_bf16 v[12:15], v[156:159], v[212:215], v[12:15]
	v_mfma_f32_16x16x32_bf16 v[8:11], v[164:167], v[212:215], v[8:11]
	s_setprio 0
	s_setprio 1
	v_mfma_f32_16x16x32_bf16 v[52:55], v[168:171], v[184:187], v[52:55]
	v_mfma_f32_16x16x32_bf16 v[48:51], v[176:179], v[184:187], v[48:51]
	v_mfma_f32_16x16x32_bf16 v[36:39], v[168:171], v[192:195], v[36:39]
	v_mfma_f32_16x16x32_bf16 v[32:35], v[176:179], v[192:195], v[32:35]
	v_mfma_f32_16x16x32_bf16 v[20:23], v[168:171], v[200:203], v[20:23]
	v_mfma_f32_16x16x32_bf16 v[16:19], v[176:179], v[200:203], v[16:19]
	v_mfma_f32_16x16x32_bf16 v[4:7], v[168:171], v[208:211], v[4:7]
	v_mfma_f32_16x16x32_bf16 v[0:3], v[176:179], v[208:211], v[0:3]
	v_mfma_f32_16x16x32_bf16 v[52:55], v[172:175], v[188:191], v[52:55]
	v_mfma_f32_16x16x32_bf16 v[48:51], v[180:183], v[188:191], v[48:51]
	v_mfma_f32_16x16x32_bf16 v[36:39], v[172:175], v[196:199], v[36:39]
	v_mfma_f32_16x16x32_bf16 v[32:35], v[180:183], v[196:199], v[32:35]
	v_mfma_f32_16x16x32_bf16 v[20:23], v[172:175], v[204:207], v[20:23]
	v_mfma_f32_16x16x32_bf16 v[16:19], v[180:183], v[204:207], v[16:19]
	v_mfma_f32_16x16x32_bf16 v[4:7], v[172:175], v[212:215], v[4:7]
	v_mfma_f32_16x16x32_bf16 v[0:3], v[180:183], v[212:215], v[0:3]
	s_setprio 0
	s_barrier
; #define PG8_STAGE(bufoff, gbase, voff) do { _Pragma("unroll") for (int _i = 0; _i < 2; ++_i) \
;         __builtin_amdgcn_global_load_lds((const unsigned*)((const char*)(gbase) + (voff)[_i]), (LAS unsigned*)(lds + (bufoff) + ldsw + _i * 8192), 16, 0, 0); } while (0)
; #define PG8_LDA(dst, b, h) do { _Pragma("unroll") for (int m = 0; m < 4; ++m) _Pragma("unroll") for (int k = 0; k < 2; ++k) dst[m][k] = *(const LAS bf16x8*)(lds + PG8_SA(b, h) + aoff + m * 2048 + k * 1024); } while (0)
; #define PG8_LDB(dst, b, h) do { _Pragma("unroll") for (int n = 0; n < 2; ++n) _Pragma("unroll") for (int k = 0; k < 2; ++k) dst[n][k] = *(const LAS bf16x8*)(lds + PG8_SB(b, h) + boff + n * 2048 + k * 1024); } while (0)
; #define PG8_WAIT_V(n) asm volatile("s_waitcnt vmcnt(" #n ")" ::: "memory")
; template <class Epi, class Sched, bool SP2 = PG8_SP2>
; __device__ __forceinline__ void gemm_phase(LAS unsigned char* lds, const Gemm g, const Sched& S, const Epi& E) {
;     ...
;         for (int t = 0; t < nt; t += 2) {
;             const bool last = (t == nt - 2);
;             const char* a1 = cA + (size_t)(t + 1) * kstep;
;             const char* a2 = last ? nA : cA + (size_t)(t + 2) * kstep; const char* b2 = last ? nB : cB + (size_t)(t + 2) * kstep;
;             const char* a3 = a2 + kstep; const char* b3 = b2 + kstep;
;             if constexpr (SP2) {
;             PG8_LDB(B0, 0, 0); PG8_LDB(B1, 0, 1); PG8_SCHED; PG8_LDA(At, 0, 0); PG8_STAGE(PG8_SA(1, 1), a1 + hstepA, voffA);
;             PG8_WAIT_V(8); PG8_WAIT_L(0); PG8_BAR; PG8_MMA(0, 0, At, B0); PG8_MMA(0, 1, At, B1); PG8_BAR; PG8_SCHED;
;             PG8_LDA(At, 0, 1); PG8_STAGE(PG8_SB(0, 0), b2, voffB); PG8_STAGE(PG8_SB(0, 1), b2 + hstepB, voffB); PG8_STAGE(PG8_SA(0, 0), a2, voffA);
;             PG8_WAIT_V(8); PG8_WAIT_L(0); PG8_BAR; PG8_MMA(1, 0, At, B0); PG8_MMA(1, 1, At, B1); PG8_BAR; PG8_SCHED;
;             PG8_LDB(B0, 1, 0); PG8_LDB(B1, 1, 1); PG8_SCHED; PG8_LDA(At, 1, 0); PG8_STAGE(PG8_SA(0, 1), a2 + hstepA, voffA);
;             PG8_WAIT_V(8); PG8_WAIT_L(0); PG8_BAR; PG8_MMA(0, 0, At, B0); PG8_MMA(0, 1, At, B1); PG8_BAR; PG8_SCHED;
;             PG8_LDA(At, 1, 1); PG8_STAGE(PG8_SB(1, 0), b3, voffB); PG8_STAGE(PG8_SB(1, 1), b3 + hstepB, voffB); PG8_STAGE(PG8_SA(1, 0), a3, voffA);
;             PG8_WAIT_V(8); PG8_WAIT_L(0); PG8_BAR; PG8_MMA(1, 0, At, B0); PG8_MMA(1, 1, At, B1); PG8_BAR; PG8_SCHED;
	s_add_i32 s3, 0, 0x18000
	s_add_i32 s68, 0, 0x1c000
	v_add_u32_e32 v164, s3, v150
	v_add_u32_e32 v180, s68, v150
	ds_read_b128 v[144:147], v164
	ds_read_b128 v[156:159], v164 offset:1024
	ds_read_b128 v[160:163], v164 offset:2048
	ds_read_b128 v[164:167], v164 offset:3072
	ds_read_b128 v[168:171], v180
	ds_read_b128 v[172:175], v180 offset:1024
	ds_read_b128 v[176:179], v180 offset:2048
	ds_read_b128 v[180:183], v180 offset:3072
	s_add_u32 s46, s46, 0x80000
	s_addc_u32 s47, s47, 0
	s_mov_b32 m0, s55
	ds_read_b128 v[184:187], v154 offset:32768
	ds_read_b128 v[188:191], v154 offset:33792
	ds_read_b128 v[192:195], v154 offset:34816
	ds_read_b128 v[196:199], v154 offset:35840
	ds_read_b128 v[200:203], v154 offset:36864
	ds_read_b128 v[204:207], v154 offset:37888
	ds_read_b128 v[208:211], v154 offset:38912
	ds_read_b128 v[212:215], v154 offset:39936
	global_load_lds_dwordx4 v128, s[46:47]
	s_mov_b32 m0, s56
	s_nop 0
	global_load_lds_dwordx4 v132, s[46:47]
	s_waitcnt vmcnt(8)
	s_waitcnt lgkmcnt(0)
	s_barrier
	s_setprio 1
	s_waitcnt lgkmcnt(0)
	v_mfma_f32_16x16x32_bf16 v[124:127], v[144:147], v[184:187], v[124:127]
	v_mfma_f32_16x16x32_bf16 v[120:123], v[160:163], v[184:187], v[120:123]
	v_mfma_f32_16x16x32_bf16 v[108:111], v[144:147], v[192:195], v[108:111]
	v_mfma_f32_16x16x32_bf16 v[104:107], v[160:163], v[192:195], v[104:107]
	v_mfma_f32_16x16x32_bf16 v[92:95], v[144:147], v[200:203], v[92:95]
	v_mfma_f32_16x16x32_bf16 v[88:91], v[160:163], v[200:203], v[88:91]
	v_mfma_f32_16x16x32_bf16 v[76:79], v[144:147], v[208:211], v[76:79]
	v_mfma_f32_16x16x32_bf16 v[72:75], v[160:163], v[208:211], v[72:75]
	v_mfma_f32_16x16x32_bf16 v[124:127], v[156:159], v[188:191], v[124:127]
	v_mfma_f32_16x16x32_bf16 v[120:123], v[164:167], v[188:191], v[120:123]
	v_mfma_f32_16x16x32_bf16 v[108:111], v[156:159], v[196:199], v[108:111]
	v_mfma_f32_16x16x32_bf16 v[104:107], v[164:167], v[196:199], v[104:107]
	v_mfma_f32_16x16x32_bf16 v[92:95], v[156:159], v[204:207], v[92:95]
	v_mfma_f32_16x16x32_bf16 v[88:91], v[164:167], v[204:207], v[88:91]
	v_mfma_f32_16x16x32_bf16 v[76:79], v[156:159], v[212:215], v[76:79]
	v_mfma_f32_16x16x32_bf16 v[72:75], v[164:167], v[212:215], v[72:75]
	s_setprio 0
	s_setprio 1
	v_mfma_f32_16x16x32_bf16 v[116:119], v[168:171], v[184:187], v[116:119]
	v_mfma_f32_16x16x32_bf16 v[112:115], v[176:179], v[184:187], v[112:115]
	v_mfma_f32_16x16x32_bf16 v[100:103], v[168:171], v[192:195], v[100:103]
	v_mfma_f32_16x16x32_bf16 v[96:99], v[176:179], v[192:195], v[96:99]
	v_mfma_f32_16x16x32_bf16 v[84:87], v[168:171], v[200:203], v[84:87]
	v_mfma_f32_16x16x32_bf16 v[80:83], v[176:179], v[200:203], v[80:83]
	v_mfma_f32_16x16x32_bf16 v[68:71], v[168:171], v[208:211], v[68:71]
	v_mfma_f32_16x16x32_bf16 v[64:67], v[176:179], v[208:211], v[64:67]
	v_mfma_f32_16x16x32_bf16 v[116:119], v[172:175], v[188:191], v[116:119]
	v_mfma_f32_16x16x32_bf16 v[112:115], v[180:183], v[188:191], v[112:115]
	v_mfma_f32_16x16x32_bf16 v[100:103], v[172:175], v[196:199], v[100:103]
	v_mfma_f32_16x16x32_bf16 v[96:99], v[180:183], v[196:199], v[96:99]
	v_mfma_f32_16x16x32_bf16 v[84:87], v[172:175], v[204:207], v[84:87]
	v_mfma_f32_16x16x32_bf16 v[80:83], v[180:183], v[204:207], v[80:83]
	v_mfma_f32_16x16x32_bf16 v[68:71], v[172:175], v[212:215], v[68:71]
	v_mfma_f32_16x16x32_bf16 v[64:67], v[180:183], v[212:215], v[64:67]
	s_setprio 0
	s_barrier
	s_add_i32 s3, s3, s52
	s_mov_b32 m0, s3
	ds_read_b128 v[184:187], v154 offset:49152
	ds_read_b128 v[188:191], v154 offset:50176
	ds_read_b128 v[192:195], v154 offset:51200
	ds_read_b128 v[196:199], v154 offset:52224
	ds_read_b128 v[200:203], v154 offset:53248
	ds_read_b128 v[204:207], v154 offset:54272
	ds_read_b128 v[208:211], v154 offset:55296
	ds_read_b128 v[212:215], v154 offset:56320
	global_load_lds_dwordx4 v130, s[98:99]
	s_add_i32 m0, s3, 0x2000
	s_add_u32 s44, s44, 0x80080
	s_addc_u32 s45, s45, 0
	s_add_i32 s3, s68, s52
	global_load_lds_dwordx4 v134, s[98:99]
	s_mov_b32 m0, s3
	s_nop 0
	global_load_lds_dwordx4 v130, s[44:45]
	s_add_i32 m0, s3, 0x2000
	s_nop 0
	global_load_lds_dwordx4 v134, s[44:45]
	s_mov_b32 m0, s58
	s_nop 0
	global_load_lds_dwordx4 v128, s[100:101]
	s_mov_b32 m0, s59
	s_nop 0
	global_load_lds_dwordx4 v132, s[100:101]
	s_waitcnt vmcnt(8)
	s_waitcnt lgkmcnt(0)
	s_barrier
	s_setprio 1
	s_waitcnt lgkmcnt(0)
	v_mfma_f32_16x16x32_bf16 v[60:63], v[144:147], v[184:187], v[60:63]
	v_mfma_f32_16x16x32_bf16 v[56:59], v[160:163], v[184:187], v[56:59]
	v_mfma_f32_16x16x32_bf16 v[44:47], v[144:147], v[192:195], v[44:47]
	v_mfma_f32_16x16x32_bf16 v[40:43], v[160:163], v[192:195], v[40:43]
	v_mfma_f32_16x16x32_bf16 v[28:31], v[144:147], v[200:203], v[28:31]
	v_mfma_f32_16x16x32_bf16 v[24:27], v[160:163], v[200:203], v[24:27]
	v_mfma_f32_16x16x32_bf16 v[12:15], v[144:147], v[208:211], v[12:15]
	v_mfma_f32_16x16x32_bf16 v[8:11], v[160:163], v[208:211], v[8:11]
	v_mfma_f32_16x16x32_bf16 v[60:63], v[156:159], v[188:191], v[60:63]
	v_mfma_f32_16x16x32_bf16 v[56:59], v[164:167], v[188:191], v[56:59]
	v_mfma_f32_16x16x32_bf16 v[44:47], v[156:159], v[196:199], v[44:47]
	v_mfma_f32_16x16x32_bf16 v[40:43], v[164:167], v[196:199], v[40:43]
	v_mfma_f32_16x16x32_bf16 v[28:31], v[156:159], v[204:207], v[28:31]
	v_mfma_f32_16x16x32_bf16 v[24:27], v[164:167], v[204:207], v[24:27]
	v_mfma_f32_16x16x32_bf16 v[12:15], v[156:159], v[212:215], v[12:15]
	v_mfma_f32_16x16x32_bf16 v[8:11], v[164:167], v[212:215], v[8:11]
	s_setprio 0
	s_setprio 1
	v_mfma_f32_16x16x32_bf16 v[52:55], v[168:171], v[184:187], v[52:55]
	v_mfma_f32_16x16x32_bf16 v[48:51], v[176:179], v[184:187], v[48:51]
	v_mfma_f32_16x16x32_bf16 v[36:39], v[168:171], v[192:195], v[36:39]
	v_mfma_f32_16x16x32_bf16 v[32:35], v[176:179], v[192:195], v[32:35]
	v_mfma_f32_16x16x32_bf16 v[20:23], v[168:171], v[200:203], v[20:23]
	v_mfma_f32_16x16x32_bf16 v[16:19], v[176:179], v[200:203], v[16:19]
	v_mfma_f32_16x16x32_bf16 v[4:7], v[168:171], v[208:211], v[4:7]
	v_mfma_f32_16x16x32_bf16 v[0:3], v[176:179], v[208:211], v[0:3]
	v_mfma_f32_16x16x32_bf16 v[52:55], v[172:175], v[188:191], v[52:55]
	v_mfma_f32_16x16x32_bf16 v[48:51], v[180:183], v[188:191], v[48:51]
	v_mfma_f32_16x16x32_bf16 v[36:39], v[172:175], v[196:199], v[36:39]
	v_mfma_f32_16x16x32_bf16 v[32:35], v[180:183], v[196:199], v[32:35]
	v_mfma_f32_16x16x32_bf16 v[20:23], v[172:175], v[204:207], v[20:23]
	v_mfma_f32_16x16x32_bf16 v[16:19], v[180:183], v[204:207], v[16:19]
	v_mfma_f32_16x16x32_bf16 v[4:7], v[172:175], v[212:215], v[4:7]
	v_mfma_f32_16x16x32_bf16 v[0:3], v[180:183], v[212:215], v[0:3]
	s_setprio 0
	s_barrier
	s_add_i32 s67, s67, 2
	s_add_u32 s0, s0, 0x100
	s_addc_u32 s1, s1, 0
	s_add_u32 s43, s43, 0x100
	s_addc_u32 s66, s66, 0
	s_cmp_gt_u32 s67, 29
	s_cbranch_scc0 .LBB0_153
	s_and_b64 vcc, exec, s[24:25]
	s_cbranch_vccz .LBB0_156
	s_barrier

; #define PG8_STAGE(bufoff, gbase, voff) do { _Pragma("unroll") for (int _i = 0; _i < 2; ++_i) \
;         __builtin_amdgcn_global_load_lds((const unsigned*)((const char*)(gbase) + (voff)[_i]), (LAS unsigned*)(lds + (bufoff) + ldsw + _i * 8192), 16, 0, 0); } while (0)
; #define PG8_LDA(dst, b, h) do { _Pragma("unroll") for (int m = 0; m < 4; ++m) _Pragma("unroll") for (int k = 0; k < 2; ++k) dst[m][k] = *(const LAS bf16x8*)(lds + PG8_SA(b, h) + aoff + m * 2048 + k * 1024); } while (0)
; #define PG8_LDB(dst, b, h) do { _Pragma("unroll") for (int n = 0; n < 2; ++n) _Pragma("unroll") for (int k = 0; k < 2; ++k) dst[n][k] = *(const LAS bf16x8*)(lds + PG8_SB(b, h) + boff + n * 2048 + k * 1024); } while (0)
; #define PG8_WAIT_V(n) asm volatile("s_waitcnt vmcnt(" #n ")" ::: "memory")
; template <class Epi, class Sched, bool SP2 = PG8_SP2>
; __device__ __forceinline__ void gemm_phase(LAS unsigned char* lds, const Gemm g, const Sched& S, const Epi& E) {
;     ...
;         for (int t = 0; t < nt; t += 2) {
;             const bool last = (t == nt - 2);
;             const char* a1 = cA + (size_t)(t + 1) * kstep;
;             const char* a2 = last ? nA : cA + (size_t)(t + 2) * kstep; const char* b2 = last ? nB : cB + (size_t)(t + 2) * kstep;
;             const char* a3 = a2 + kstep; const char* b3 = b2 + kstep;
;             if constexpr (SP2) {
;             PG8_LDB(B0, 0, 0); PG8_LDB(B1, 0, 1); PG8_SCHED; PG8_LDA(At, 0, 0); PG8_STAGE(PG8_SA(1, 1), a1 + hstepA, voffA);
;             PG8_WAIT_V(8); PG8_WAIT_L(0); PG8_BAR; PG8_MMA(0, 0, At, B0); PG8_MMA(0, 1, At, B1); PG8_BAR; PG8_SCHED;
;             PG8_LDA(At, 0, 1); PG8_STAGE(PG8_SB(0, 0), b2, voffB); PG8_STAGE(PG8_SB(0, 1), b2 + hstepB, voffB); PG8_STAGE(PG8_SA(0, 0), a2, voffA);
;             PG8_WAIT_V(8); PG8_WAIT_L(0); PG8_BAR; PG8_MMA(1, 0, At, B0); PG8_MMA(1, 1, At, B1); PG8_BAR; PG8_SCHED;
;             PG8_LDB(B0, 1, 0); PG8_LDB(B1, 1, 1); PG8_SCHED; PG8_LDA(At, 1, 0); PG8_STAGE(PG8_SA(0, 1), a2 + hstepA, voffA);
;             PG8_WAIT_V(8); PG8_WAIT_L(0); PG8_BAR; PG8_MMA(0, 0, At, B0); PG8_MMA(0, 1, At, B1); PG8_BAR; PG8_SCHED;
;             PG8_LDA(At, 1, 1); PG8_STAGE(PG8_SB(1, 0), b3, voffB); PG8_STAGE(PG8_SB(1, 1), b3 + hstepB, voffB); PG8_STAGE(PG8_SA(1, 0), a3, voffA);
;             PG8_WAIT_V(8); PG8_WAIT_L(0); PG8_BAR; PG8_MMA(1, 0, At, B0); PG8_MMA(1, 1, At, B1); PG8_BAR; PG8_SCHED;
.LBB0_333:
	ds_read_b128 v[144:147], v168
	ds_read_b128 v[148:151], v168 offset:1024
	ds_read_b128 v[172:175], v168 offset:2048
	ds_read_b128 v[176:179], v168 offset:3072
	ds_read_b128 v[180:183], v169
	ds_read_b128 v[184:187], v169 offset:1024
	ds_read_b128 v[188:191], v169 offset:2048
	ds_read_b128 v[192:195], v169 offset:3072
	s_add_u32 s3, s0, 0xfff80080
	s_addc_u32 s30, s1, -1
	s_cmp_eq_u32 s56, 4
	s_cselect_b32 s35, s2, s30
	s_cselect_b32 s34, s23, s3
	s_cselect_b32 s31, s21, s55
	s_cselect_b32 s30, s53, s54
	s_add_i32 m0, s29, 0xc000
	ds_read_b128 v[196:199], v170
	ds_read_b128 v[200:203], v170 offset:1024
	ds_read_b128 v[204:207], v170 offset:2048
	ds_read_b128 v[208:211], v170 offset:3072
	ds_read_b128 v[212:215], v170 offset:4096
	ds_read_b128 v[216:219], v170 offset:5120
	ds_read_b128 v[224:227], v170 offset:6144
	ds_read_b128 v[228:231], v170 offset:7168
	global_load_lds_dwordx4 v136, s[0:1]
	s_add_i32 m0, s29, 0xe000
	s_nop 0
	global_load_lds_dwordx4 v138, s[0:1]
	s_waitcnt vmcnt(8)
	s_waitcnt lgkmcnt(0)
	s_barrier
	s_setprio 1
	s_waitcnt lgkmcnt(0)
	v_mfma_f32_16x16x32_bf16 v[124:127], v[144:147], v[196:199], v[124:127]
	v_mfma_f32_16x16x32_bf16 v[120:123], v[172:175], v[196:199], v[120:123]
	v_mfma_f32_16x16x32_bf16 v[108:111], v[144:147], v[204:207], v[108:111]
	v_mfma_f32_16x16x32_bf16 v[104:107], v[172:175], v[204:207], v[104:107]
	v_mfma_f32_16x16x32_bf16 v[92:95], v[144:147], v[212:215], v[92:95]
	v_mfma_f32_16x16x32_bf16 v[88:91], v[172:175], v[212:215], v[88:91]
	v_mfma_f32_16x16x32_bf16 v[84:87], v[144:147], v[224:227], v[84:87]
	v_mfma_f32_16x16x32_bf16 v[76:79], v[172:175], v[224:227], v[76:79]
	v_mfma_f32_16x16x32_bf16 v[124:127], v[148:151], v[200:203], v[124:127]
	v_mfma_f32_16x16x32_bf16 v[120:123], v[176:179], v[200:203], v[120:123]
	v_mfma_f32_16x16x32_bf16 v[108:111], v[148:151], v[208:211], v[108:111]
	v_mfma_f32_16x16x32_bf16 v[104:107], v[176:179], v[208:211], v[104:107]
	v_mfma_f32_16x16x32_bf16 v[92:95], v[148:151], v[216:219], v[92:95]
	v_mfma_f32_16x16x32_bf16 v[88:91], v[176:179], v[216:219], v[88:91]
	v_mfma_f32_16x16x32_bf16 v[84:87], v[148:151], v[228:231], v[84:87]
	v_mfma_f32_16x16x32_bf16 v[76:79], v[176:179], v[228:231], v[76:79]
	s_setprio 0
	s_setprio 1
	v_mfma_f32_16x16x32_bf16 v[116:119], v[180:183], v[196:199], v[116:119]
	v_mfma_f32_16x16x32_bf16 v[112:115], v[188:191], v[196:199], v[112:115]
	v_mfma_f32_16x16x32_bf16 v[100:103], v[180:183], v[204:207], v[100:103]
	v_mfma_f32_16x16x32_bf16 v[96:99], v[188:191], v[204:207], v[96:99]
	v_mfma_f32_16x16x32_bf16 v[80:83], v[180:183], v[212:215], v[80:83]
	v_mfma_f32_16x16x32_bf16 v[72:75], v[188:191], v[212:215], v[72:75]
	v_mfma_f32_16x16x32_bf16 v[68:71], v[180:183], v[224:227], v[68:71]
	v_mfma_f32_16x16x32_bf16 v[64:67], v[188:191], v[224:227], v[64:67]
	v_mfma_f32_16x16x32_bf16 v[116:119], v[184:187], v[200:203], v[116:119]
	v_mfma_f32_16x16x32_bf16 v[112:115], v[192:195], v[200:203], v[112:115]
	v_mfma_f32_16x16x32_bf16 v[100:103], v[184:187], v[208:211], v[100:103]
	v_mfma_f32_16x16x32_bf16 v[96:99], v[192:195], v[208:211], v[96:99]
	v_mfma_f32_16x16x32_bf16 v[80:83], v[184:187], v[216:219], v[80:83]
	v_mfma_f32_16x16x32_bf16 v[72:75], v[192:195], v[216:219], v[72:75]
	v_mfma_f32_16x16x32_bf16 v[68:71], v[184:187], v[228:231], v[68:71]
	v_mfma_f32_16x16x32_bf16 v[64:67], v[192:195], v[228:231], v[64:67]
	s_setprio 0
	s_barrier
	s_add_i32 s3, s49, s39
	s_add_u32 s98, s30, s16
	s_addc_u32 s99, s31, s17
	s_mov_b32 m0, s3
	ds_read_b128 v[196:199], v170 offset:16384
	ds_read_b128 v[200:203], v170 offset:17408
	ds_read_b128 v[204:207], v170 offset:18432
	ds_read_b128 v[208:211], v170 offset:19456
	ds_read_b128 v[212:215], v170 offset:20480
	ds_read_b128 v[216:219], v170 offset:21504
	ds_read_b128 v[224:227], v170 offset:22528
	ds_read_b128 v[228:231], v170 offset:23552
	global_load_lds_dwordx4 v134, s[30:31]
	s_add_i32 m0, s3, 0x2000
	s_add_u32 s58, s30, 0x20000
	s_addc_u32 s59, s31, 0
	s_add_i32 s3, s50, s39
	global_load_lds_dwordx4 v132, s[30:31]
	s_mov_b32 m0, s3
	s_nop 0
	global_load_lds_dwordx4 v134, s[58:59]
	s_add_i32 m0, s3, 0x2000
	s_nop 0
	global_load_lds_dwordx4 v132, s[58:59]
	s_add_u32 s100, s34, s16
	s_addc_u32 s101, s35, s17
	s_mov_b32 m0, s29
	s_nop 0
	global_load_lds_dwordx4 v128, s[34:35]
	s_mov_b32 m0, s41
	s_nop 0
	global_load_lds_dwordx4 v130, s[34:35]
	s_waitcnt vmcnt(8)
	s_waitcnt lgkmcnt(0)
	s_barrier
	s_setprio 1
	s_waitcnt lgkmcnt(0)
	v_mfma_f32_16x16x32_bf16 v[60:63], v[144:147], v[196:199], v[60:63]
	v_mfma_f32_16x16x32_bf16 v[56:59], v[172:175], v[196:199], v[56:59]
	v_mfma_f32_16x16x32_bf16 v[44:47], v[144:147], v[204:207], v[44:47]
	v_mfma_f32_16x16x32_bf16 v[40:43], v[172:175], v[204:207], v[40:43]
	v_mfma_f32_16x16x32_bf16 v[28:31], v[144:147], v[212:215], v[28:31]
	v_mfma_f32_16x16x32_bf16 v[24:27], v[172:175], v[212:215], v[24:27]
	v_mfma_f32_16x16x32_bf16 v[12:15], v[144:147], v[224:227], v[12:15]
	v_mfma_f32_16x16x32_bf16 v[8:11], v[172:175], v[224:227], v[8:11]
	v_mfma_f32_16x16x32_bf16 v[60:63], v[148:151], v[200:203], v[60:63]
	v_mfma_f32_16x16x32_bf16 v[56:59], v[176:179], v[200:203], v[56:59]
	v_mfma_f32_16x16x32_bf16 v[44:47], v[148:151], v[208:211], v[44:47]
	v_mfma_f32_16x16x32_bf16 v[40:43], v[176:179], v[208:211], v[40:43]
	v_mfma_f32_16x16x32_bf16 v[28:31], v[148:151], v[216:219], v[28:31]
	v_mfma_f32_16x16x32_bf16 v[24:27], v[176:179], v[216:219], v[24:27]
	v_mfma_f32_16x16x32_bf16 v[12:15], v[148:151], v[228:231], v[12:15]
	v_mfma_f32_16x16x32_bf16 v[8:11], v[176:179], v[228:231], v[8:11]
	s_setprio 0
	s_setprio 1
	v_mfma_f32_16x16x32_bf16 v[52:55], v[180:183], v[196:199], v[52:55]
	v_mfma_f32_16x16x32_bf16 v[48:51], v[188:191], v[196:199], v[48:51]
	v_mfma_f32_16x16x32_bf16 v[36:39], v[180:183], v[204:207], v[36:39]
	v_mfma_f32_16x16x32_bf16 v[32:35], v[188:191], v[204:207], v[32:35]
	v_mfma_f32_16x16x32_bf16 v[20:23], v[180:183], v[212:215], v[20:23]
	v_mfma_f32_16x16x32_bf16 v[16:19], v[188:191], v[212:215], v[16:19]
	v_mfma_f32_16x16x32_bf16 v[4:7], v[180:183], v[224:227], v[4:7]
	v_mfma_f32_16x16x32_bf16 v[0:3], v[188:191], v[224:227], v[0:3]
	v_mfma_f32_16x16x32_bf16 v[52:55], v[184:187], v[200:203], v[52:55]
	v_mfma_f32_16x16x32_bf16 v[48:51], v[192:195], v[200:203], v[48:51]
	v_mfma_f32_16x16x32_bf16 v[36:39], v[184:187], v[208:211], v[36:39]
	v_mfma_f32_16x16x32_bf16 v[32:35], v[192:195], v[208:211], v[32:35]
	v_mfma_f32_16x16x32_bf16 v[20:23], v[184:187], v[216:219], v[20:23]
	v_mfma_f32_16x16x32_bf16 v[16:19], v[192:195], v[216:219], v[16:19]
	v_mfma_f32_16x16x32_bf16 v[4:7], v[184:187], v[228:231], v[4:7]
	v_mfma_f32_16x16x32_bf16 v[0:3], v[192:195], v[228:231], v[0:3]
	s_setprio 0
	s_barrier
; #define PG8_STAGE(bufoff, gbase, voff) do { _Pragma("unroll") for (int _i = 0; _i < 2; ++_i) \
;         __builtin_amdgcn_global_load_lds((const unsigned*)((const char*)(gbase) + (voff)[_i]), (LAS unsigned*)(lds + (bufoff) + ldsw + _i * 8192), 16, 0, 0); } while (0)
; #define PG8_LDA(dst, b, h) do { _Pragma("unroll") for (int m = 0; m < 4; ++m) _Pragma("unroll") for (int k = 0; k < 2; ++k) dst[m][k] = *(const LAS bf16x8*)(lds + PG8_SA(b, h) + aoff + m * 2048 + k * 1024); } while (0)
; #define PG8_LDB(dst, b, h) do { _Pragma("unroll") for (int n = 0; n < 2; ++n) _Pragma("unroll") for (int k = 0; k < 2; ++k) dst[n][k] = *(const LAS bf16x8*)(lds + PG8_SB(b, h) + boff + n * 2048 + k * 1024); } while (0)
; #define PG8_WAIT_V(n) asm volatile("s_waitcnt vmcnt(" #n ")" ::: "memory")
; template <class Epi, class Sched, bool SP2 = PG8_SP2>
; __device__ __forceinline__ void gemm_phase(LAS unsigned char* lds, const Gemm g, const Sched& S, const Epi& E) {
;     ...
;         for (int t = 0; t < nt; t += 2) {
;             const bool last = (t == nt - 2);
;             const char* a1 = cA + (size_t)(t + 1) * kstep;
;             const char* a2 = last ? nA : cA + (size_t)(t + 2) * kstep; const char* b2 = last ? nB : cB + (size_t)(t + 2) * kstep;
;             const char* a3 = a2 + kstep; const char* b3 = b2 + kstep;
;             if constexpr (SP2) {
;             PG8_LDB(B0, 0, 0); PG8_LDB(B1, 0, 1); PG8_SCHED; PG8_LDA(At, 0, 0); PG8_STAGE(PG8_SA(1, 1), a1 + hstepA, voffA);
;             PG8_WAIT_V(8); PG8_WAIT_L(0); PG8_BAR; PG8_MMA(0, 0, At, B0); PG8_MMA(0, 1, At, B1); PG8_BAR; PG8_SCHED;
;             PG8_LDA(At, 0, 1); PG8_STAGE(PG8_SB(0, 0), b2, voffB); PG8_STAGE(PG8_SB(0, 1), b2 + hstepB, voffB); PG8_STAGE(PG8_SA(0, 0), a2, voffA);
;             PG8_WAIT_V(8); PG8_WAIT_L(0); PG8_BAR; PG8_MMA(1, 0, At, B0); PG8_MMA(1, 1, At, B1); PG8_BAR; PG8_SCHED;
;             PG8_LDB(B0, 1, 0); PG8_LDB(B1, 1, 1); PG8_SCHED; PG8_LDA(At, 1, 0); PG8_STAGE(PG8_SA(0, 1), a2 + hstepA, voffA);
;             PG8_WAIT_V(8); PG8_WAIT_L(0); PG8_BAR; PG8_MMA(0, 0, At, B0); PG8_MMA(0, 1, At, B1); PG8_BAR; PG8_SCHED;
;             PG8_LDA(At, 1, 1); PG8_STAGE(PG8_SB(1, 0), b3, voffB); PG8_STAGE(PG8_SB(1, 1), b3 + hstepB, voffB); PG8_STAGE(PG8_SA(1, 0), a3, voffA);
;             PG8_WAIT_V(8); PG8_WAIT_L(0); PG8_BAR; PG8_MMA(1, 0, At, B0); PG8_MMA(1, 1, At, B1); PG8_BAR; PG8_SCHED;
	s_add_i32 s3, 0, 0x18000
	s_add_i32 s57, 0, 0x1c000
	v_add_u32_e32 v176, s3, v166
	v_add_u32_e32 v192, s57, v166
	ds_read_b128 v[144:147], v176
	ds_read_b128 v[148:151], v176 offset:1024
	ds_read_b128 v[172:175], v176 offset:2048
	ds_read_b128 v[176:179], v176 offset:3072
	ds_read_b128 v[180:183], v192
	ds_read_b128 v[184:187], v192 offset:1024
	ds_read_b128 v[188:191], v192 offset:2048
	ds_read_b128 v[192:195], v192 offset:3072
	s_add_u32 s34, s34, 0x80000
	s_addc_u32 s35, s35, 0
	s_mov_b32 m0, s42
	ds_read_b128 v[196:199], v170 offset:32768
	ds_read_b128 v[200:203], v170 offset:33792
	ds_read_b128 v[204:207], v170 offset:34816
	ds_read_b128 v[208:211], v170 offset:35840
	ds_read_b128 v[212:215], v170 offset:36864
	ds_read_b128 v[216:219], v170 offset:37888
	ds_read_b128 v[224:227], v170 offset:38912
	ds_read_b128 v[228:231], v170 offset:39936
	global_load_lds_dwordx4 v128, s[34:35]
	s_mov_b32 m0, s43
	s_nop 0
	global_load_lds_dwordx4 v130, s[34:35]
	s_waitcnt vmcnt(8)
	s_waitcnt lgkmcnt(0)
	s_barrier
	s_setprio 1
	s_waitcnt lgkmcnt(0)
	v_mfma_f32_16x16x32_bf16 v[124:127], v[144:147], v[196:199], v[124:127]
	v_mfma_f32_16x16x32_bf16 v[120:123], v[172:175], v[196:199], v[120:123]
	v_mfma_f32_16x16x32_bf16 v[108:111], v[144:147], v[204:207], v[108:111]
	v_mfma_f32_16x16x32_bf16 v[104:107], v[172:175], v[204:207], v[104:107]
	v_mfma_f32_16x16x32_bf16 v[92:95], v[144:147], v[212:215], v[92:95]
	v_mfma_f32_16x16x32_bf16 v[88:91], v[172:175], v[212:215], v[88:91]
	v_mfma_f32_16x16x32_bf16 v[84:87], v[144:147], v[224:227], v[84:87]
	v_mfma_f32_16x16x32_bf16 v[76:79], v[172:175], v[224:227], v[76:79]
	v_mfma_f32_16x16x32_bf16 v[124:127], v[148:151], v[200:203], v[124:127]
	v_mfma_f32_16x16x32_bf16 v[120:123], v[176:179], v[200:203], v[120:123]
	v_mfma_f32_16x16x32_bf16 v[108:111], v[148:151], v[208:211], v[108:111]
	v_mfma_f32_16x16x32_bf16 v[104:107], v[176:179], v[208:211], v[104:107]
	v_mfma_f32_16x16x32_bf16 v[92:95], v[148:151], v[216:219], v[92:95]
	v_mfma_f32_16x16x32_bf16 v[88:91], v[176:179], v[216:219], v[88:91]
	v_mfma_f32_16x16x32_bf16 v[84:87], v[148:151], v[228:231], v[84:87]
	v_mfma_f32_16x16x32_bf16 v[76:79], v[176:179], v[228:231], v[76:79]
	s_setprio 0
	s_setprio 1
	v_mfma_f32_16x16x32_bf16 v[116:119], v[180:183], v[196:199], v[116:119]
	v_mfma_f32_16x16x32_bf16 v[112:115], v[188:191], v[196:199], v[112:115]
	v_mfma_f32_16x16x32_bf16 v[100:103], v[180:183], v[204:207], v[100:103]
	v_mfma_f32_16x16x32_bf16 v[96:99], v[188:191], v[204:207], v[96:99]
	v_mfma_f32_16x16x32_bf16 v[80:83], v[180:183], v[212:215], v[80:83]
	v_mfma_f32_16x16x32_bf16 v[72:75], v[188:191], v[212:215], v[72:75]
	v_mfma_f32_16x16x32_bf16 v[68:71], v[180:183], v[224:227], v[68:71]
	v_mfma_f32_16x16x32_bf16 v[64:67], v[188:191], v[224:227], v[64:67]
	v_mfma_f32_16x16x32_bf16 v[116:119], v[184:187], v[200:203], v[116:119]
	v_mfma_f32_16x16x32_bf16 v[112:115], v[192:195], v[200:203], v[112:115]
	v_mfma_f32_16x16x32_bf16 v[100:103], v[184:187], v[208:211], v[100:103]
	v_mfma_f32_16x16x32_bf16 v[96:99], v[192:195], v[208:211], v[96:99]
	v_mfma_f32_16x16x32_bf16 v[80:83], v[184:187], v[216:219], v[80:83]
	v_mfma_f32_16x16x32_bf16 v[72:75], v[192:195], v[216:219], v[72:75]
	v_mfma_f32_16x16x32_bf16 v[68:71], v[184:187], v[228:231], v[68:71]
	v_mfma_f32_16x16x32_bf16 v[64:67], v[192:195], v[228:231], v[64:67]
	s_setprio 0
	s_barrier
	s_add_i32 s3, s3, s39
	s_mov_b32 m0, s3
	ds_read_b128 v[196:199], v170 offset:49152
	ds_read_b128 v[200:203], v170 offset:50176
	ds_read_b128 v[204:207], v170 offset:51200
	ds_read_b128 v[208:211], v170 offset:52224
	ds_read_b128 v[212:215], v170 offset:53248
	ds_read_b128 v[216:219], v170 offset:54272
	ds_read_b128 v[224:227], v170 offset:55296
	ds_read_b128 v[228:231], v170 offset:56320
	global_load_lds_dwordx4 v134, s[98:99]
	s_add_i32 m0, s3, 0x2000
	s_add_u32 s30, s30, 0x20080
	s_addc_u32 s31, s31, 0
	s_add_i32 s3, s57, s39
	global_load_lds_dwordx4 v132, s[98:99]
	s_mov_b32 m0, s3
	s_nop 0
	global_load_lds_dwordx4 v134, s[30:31]
	s_add_i32 m0, s3, 0x2000
	s_nop 0
	global_load_lds_dwordx4 v132, s[30:31]
	s_mov_b32 m0, s45
	s_nop 0
	global_load_lds_dwordx4 v128, s[100:101]
	s_mov_b32 m0, s46
	s_nop 0
	global_load_lds_dwordx4 v130, s[100:101]
	s_waitcnt vmcnt(8)
	s_waitcnt lgkmcnt(0)
	s_barrier
	s_setprio 1
	s_waitcnt lgkmcnt(0)
	v_mfma_f32_16x16x32_bf16 v[60:63], v[144:147], v[196:199], v[60:63]
	v_mfma_f32_16x16x32_bf16 v[56:59], v[172:175], v[196:199], v[56:59]
	v_mfma_f32_16x16x32_bf16 v[44:47], v[144:147], v[204:207], v[44:47]
	v_mfma_f32_16x16x32_bf16 v[40:43], v[172:175], v[204:207], v[40:43]
	v_mfma_f32_16x16x32_bf16 v[28:31], v[144:147], v[212:215], v[28:31]
	v_mfma_f32_16x16x32_bf16 v[24:27], v[172:175], v[212:215], v[24:27]
	v_mfma_f32_16x16x32_bf16 v[12:15], v[144:147], v[224:227], v[12:15]
	v_mfma_f32_16x16x32_bf16 v[8:11], v[172:175], v[224:227], v[8:11]
	v_mfma_f32_16x16x32_bf16 v[60:63], v[148:151], v[200:203], v[60:63]
	v_mfma_f32_16x16x32_bf16 v[56:59], v[176:179], v[200:203], v[56:59]
	v_mfma_f32_16x16x32_bf16 v[44:47], v[148:151], v[208:211], v[44:47]
	v_mfma_f32_16x16x32_bf16 v[40:43], v[176:179], v[208:211], v[40:43]
	v_mfma_f32_16x16x32_bf16 v[28:31], v[148:151], v[216:219], v[28:31]
	v_mfma_f32_16x16x32_bf16 v[24:27], v[176:179], v[216:219], v[24:27]
	v_mfma_f32_16x16x32_bf16 v[12:15], v[148:151], v[228:231], v[12:15]
	v_mfma_f32_16x16x32_bf16 v[8:11], v[176:179], v[228:231], v[8:11]
	s_setprio 0
	s_setprio 1
	v_mfma_f32_16x16x32_bf16 v[52:55], v[180:183], v[196:199], v[52:55]
	v_mfma_f32_16x16x32_bf16 v[48:51], v[188:191], v[196:199], v[48:51]
	v_mfma_f32_16x16x32_bf16 v[36:39], v[180:183], v[204:207], v[36:39]
	v_mfma_f32_16x16x32_bf16 v[32:35], v[188:191], v[204:207], v[32:35]
	v_mfma_f32_16x16x32_bf16 v[20:23], v[180:183], v[212:215], v[20:23]
	v_mfma_f32_16x16x32_bf16 v[16:19], v[188:191], v[212:215], v[16:19]
	v_mfma_f32_16x16x32_bf16 v[4:7], v[180:183], v[224:227], v[4:7]
	v_mfma_f32_16x16x32_bf16 v[0:3], v[188:191], v[224:227], v[0:3]
	v_mfma_f32_16x16x32_bf16 v[52:55], v[184:187], v[200:203], v[52:55]
	v_mfma_f32_16x16x32_bf16 v[48:51], v[192:195], v[200:203], v[48:51]
	v_mfma_f32_16x16x32_bf16 v[36:39], v[184:187], v[208:211], v[36:39]
	v_mfma_f32_16x16x32_bf16 v[32:35], v[192:195], v[208:211], v[32:35]
	v_mfma_f32_16x16x32_bf16 v[20:23], v[184:187], v[216:219], v[20:23]
	v_mfma_f32_16x16x32_bf16 v[16:19], v[192:195], v[216:219], v[16:19]
	v_mfma_f32_16x16x32_bf16 v[4:7], v[184:187], v[228:231], v[4:7]
	v_mfma_f32_16x16x32_bf16 v[0:3], v[192:195], v[228:231], v[0:3]
	s_setprio 0
	s_barrier
	s_add_i32 s56, s56, 2
	s_add_u32 s0, s0, 0x100
	s_addc_u32 s1, s1, 0
	s_add_u32 s54, s54, 0x100
	s_addc_u32 s55, s55, 0
	s_cmp_gt_u32 s56, 5
	s_cbranch_scc0 .LBB0_333
	s_and_b64 vcc, exec, s[18:19]
	s_cbranch_vccz .LBB0_336
	s_barrier

; #define PG8_STAGE(bufoff, gbase, voff) do { _Pragma("unroll") for (int _i = 0; _i < 2; ++_i) \
;         __builtin_amdgcn_global_load_lds((const unsigned*)((const char*)(gbase) + (voff)[_i]), (LAS unsigned*)(lds + (bufoff) + ldsw + _i * 8192), 16, 0, 0); } while (0)
; #define PG8_LDA(dst, b, h) do { _Pragma("unroll") for (int m = 0; m < 4; ++m) _Pragma("unroll") for (int k = 0; k < 2; ++k) dst[m][k] = *(const LAS bf16x8*)(lds + PG8_SA(b, h) + aoff + m * 2048 + k * 1024); } while (0)
; #define PG8_LDB(dst, b, h) do { _Pragma("unroll") for (int n = 0; n < 2; ++n) _Pragma("unroll") for (int k = 0; k < 2; ++k) dst[n][k] = *(const LAS bf16x8*)(lds + PG8_SB(b, h) + boff + n * 2048 + k * 1024); } while (0)
; #define PG8_WAIT_V(n) asm volatile("s_waitcnt vmcnt(" #n ")" ::: "memory")
; template <class Epi, class Sched, bool SP2 = PG8_SP2>
; __device__ __forceinline__ void gemm_phase(LAS unsigned char* lds, const Gemm g, const Sched& S, const Epi& E) {
;     ...
;         for (int t = 0; t < nt; t += 2) {
;             const bool last = (t == nt - 2);
;             const char* a1 = cA + (size_t)(t + 1) * kstep;
;             const char* a2 = last ? nA : cA + (size_t)(t + 2) * kstep; const char* b2 = last ? nB : cB + (size_t)(t + 2) * kstep;
;             const char* a3 = a2 + kstep; const char* b3 = b2 + kstep;
;             if constexpr (SP2) {
;             PG8_LDB(B0, 0, 0); PG8_LDB(B1, 0, 1); PG8_SCHED; PG8_LDA(At, 0, 0); PG8_STAGE(PG8_SA(1, 1), a1 + hstepA, voffA);
;             PG8_WAIT_V(8); PG8_WAIT_L(0); PG8_BAR; PG8_MMA(0, 0, At, B0); PG8_MMA(0, 1, At, B1); PG8_BAR; PG8_SCHED;
;             PG8_LDA(At, 0, 1); PG8_STAGE(PG8_SB(0, 0), b2, voffB); PG8_STAGE(PG8_SB(0, 1), b2 + hstepB, voffB); PG8_STAGE(PG8_SA(0, 0), a2, voffA);
;             PG8_WAIT_V(8); PG8_WAIT_L(0); PG8_BAR; PG8_MMA(1, 0, At, B0); PG8_MMA(1, 1, At, B1); PG8_BAR; PG8_SCHED;
;             PG8_LDB(B0, 1, 0); PG8_LDB(B1, 1, 1); PG8_SCHED; PG8_LDA(At, 1, 0); PG8_STAGE(PG8_SA(0, 1), a2 + hstepA, voffA);
;             PG8_WAIT_V(8); PG8_WAIT_L(0); PG8_BAR; PG8_MMA(0, 0, At, B0); PG8_MMA(0, 1, At, B1); PG8_BAR; PG8_SCHED;
;             PG8_LDA(At, 1, 1); PG8_STAGE(PG8_SB(1, 0), b3, voffB); PG8_STAGE(PG8_SB(1, 1), b3 + hstepB, voffB); PG8_STAGE(PG8_SA(1, 0), a3, voffA);
;             PG8_WAIT_V(8); PG8_WAIT_L(0); PG8_BAR; PG8_MMA(1, 0, At, B0); PG8_MMA(1, 1, At, B1); PG8_BAR; PG8_SCHED;
.LBB0_359:
	s_add_u32 s52, s42, s3
	s_addc_u32 s53, s43, 0
	s_add_u32 s48, s52, 0x100
	s_addc_u32 s49, s53, 0
	s_and_b64 s[46:47], s[44:45], exec
	s_cselect_b32 s49, s2, s49
	s_cselect_b32 s48, s31, s48
	s_add_u32 s3, s40, s3
	s_addc_u32 s46, s41, 0
	s_add_u32 s3, s3, 0x100
	s_addc_u32 s46, s46, 0
	s_and_b64 s[44:45], s[44:45], exec
	s_cselect_b32 s51, s29, s46
	s_cselect_b32 s50, s77, s3
	s_add_u32 s54, s52, 0x80080
	ds_read_b128 v[140:143], v149
	ds_read_b128 v[164:167], v149 offset:1024
	ds_read_b128 v[168:171], v149 offset:2048
	ds_read_b128 v[172:175], v149 offset:3072
	ds_read_b128 v[176:179], v150
	ds_read_b128 v[180:183], v150 offset:1024
	ds_read_b128 v[184:187], v150 offset:2048
	ds_read_b128 v[188:191], v150 offset:3072
	s_addc_u32 s55, s53, 0
	s_add_i32 s82, s68, s60
	s_add_i32 m0, s61, 0xc000
	s_add_i32 s85, s61, 0xe000
	s_add_i32 s79, s82, 0x2000
	s_add_u32 s52, s50, 0x10000
	s_addc_u32 s53, s51, 0
	s_add_i32 s81, s69, s60
	s_add_i32 s80, s81, 0x2000
	s_add_i32 s78, 0, 0x18000
	s_add_i32 s73, 0, 0x1c000
	s_add_u32 s46, s48, 0x80000
	s_addc_u32 s47, s49, 0
	s_add_i32 s72, s78, s60
	s_add_i32 s3, s72, 0x2000
	s_add_u32 s44, s50, 0x10080
	s_addc_u32 s45, s51, 0
	s_add_i32 s84, s73, s60
	s_add_i32 s83, s84, 0x2000
	ds_read_b128 v[192:195], v151
	ds_read_b128 v[196:199], v151 offset:1024
	ds_read_b128 v[200:203], v151 offset:2048
	ds_read_b128 v[204:207], v151 offset:3072
	ds_read_b128 v[208:211], v151 offset:4096
	ds_read_b128 v[212:215], v151 offset:5120
	ds_read_b128 v[216:219], v151 offset:6144
	ds_read_b128 v[224:227], v151 offset:7168
	global_load_lds_dwordx4 v128, s[54:55]
	s_mov_b32 m0, s85
	s_nop 0
	global_load_lds_dwordx4 v130, s[54:55]
	s_waitcnt vmcnt(8)
	s_waitcnt lgkmcnt(0)
	s_barrier
	s_setprio 1
	s_waitcnt lgkmcnt(0)
	v_mfma_f32_16x16x32_bf16 v[124:127], v[140:143], v[192:195], v[124:127]
	v_mfma_f32_16x16x32_bf16 v[120:123], v[168:171], v[192:195], v[120:123]
	v_mfma_f32_16x16x32_bf16 v[108:111], v[140:143], v[200:203], v[108:111]
	v_mfma_f32_16x16x32_bf16 v[104:107], v[168:171], v[200:203], v[104:107]
	v_mfma_f32_16x16x32_bf16 v[92:95], v[140:143], v[208:211], v[92:95]
	v_mfma_f32_16x16x32_bf16 v[88:91], v[168:171], v[208:211], v[88:91]
	v_mfma_f32_16x16x32_bf16 v[84:87], v[140:143], v[216:219], v[84:87]
	v_mfma_f32_16x16x32_bf16 v[72:75], v[168:171], v[216:219], v[72:75]
	v_mfma_f32_16x16x32_bf16 v[124:127], v[164:167], v[196:199], v[124:127]
	v_mfma_f32_16x16x32_bf16 v[120:123], v[172:175], v[196:199], v[120:123]
	v_mfma_f32_16x16x32_bf16 v[108:111], v[164:167], v[204:207], v[108:111]
	v_mfma_f32_16x16x32_bf16 v[104:107], v[172:175], v[204:207], v[104:107]
	v_mfma_f32_16x16x32_bf16 v[92:95], v[164:167], v[212:215], v[92:95]
	v_mfma_f32_16x16x32_bf16 v[88:91], v[172:175], v[212:215], v[88:91]
	v_mfma_f32_16x16x32_bf16 v[84:87], v[164:167], v[224:227], v[84:87]
	v_mfma_f32_16x16x32_bf16 v[72:75], v[172:175], v[224:227], v[72:75]
	s_setprio 0
	s_setprio 1
	v_mfma_f32_16x16x32_bf16 v[116:119], v[176:179], v[192:195], v[116:119]
	v_mfma_f32_16x16x32_bf16 v[112:115], v[184:187], v[192:195], v[112:115]
	v_mfma_f32_16x16x32_bf16 v[100:103], v[176:179], v[200:203], v[100:103]
	v_mfma_f32_16x16x32_bf16 v[96:99], v[184:187], v[200:203], v[96:99]
	v_mfma_f32_16x16x32_bf16 v[80:83], v[176:179], v[208:211], v[80:83]
	v_mfma_f32_16x16x32_bf16 v[76:79], v[184:187], v[208:211], v[76:79]
	v_mfma_f32_16x16x32_bf16 v[68:71], v[176:179], v[216:219], v[68:71]
	v_mfma_f32_16x16x32_bf16 v[64:67], v[184:187], v[216:219], v[64:67]
	v_mfma_f32_16x16x32_bf16 v[116:119], v[180:183], v[196:199], v[116:119]
	v_mfma_f32_16x16x32_bf16 v[112:115], v[188:191], v[196:199], v[112:115]
	v_mfma_f32_16x16x32_bf16 v[100:103], v[180:183], v[204:207], v[100:103]
	v_mfma_f32_16x16x32_bf16 v[96:99], v[188:191], v[204:207], v[96:99]
	v_mfma_f32_16x16x32_bf16 v[80:83], v[180:183], v[212:215], v[80:83]
	v_mfma_f32_16x16x32_bf16 v[76:79], v[188:191], v[212:215], v[76:79]
	v_mfma_f32_16x16x32_bf16 v[68:71], v[180:183], v[224:227], v[68:71]
	v_mfma_f32_16x16x32_bf16 v[64:67], v[188:191], v[224:227], v[64:67]
	s_setprio 0
	s_barrier
	s_mov_b32 m0, s82
	s_add_u32 s98, s50, s18
	s_addc_u32 s99, s51, s19
	ds_read_b128 v[192:195], v151 offset:16384
	ds_read_b128 v[196:199], v151 offset:17408
	ds_read_b128 v[200:203], v151 offset:18432
	ds_read_b128 v[204:207], v151 offset:19456
	ds_read_b128 v[208:211], v151 offset:20480
	ds_read_b128 v[212:215], v151 offset:21504
	ds_read_b128 v[216:219], v151 offset:22528
	ds_read_b128 v[224:227], v151 offset:23552
	global_load_lds_dwordx4 v132, s[50:51]
	s_mov_b32 m0, s79
	s_nop 0
	global_load_lds_dwordx4 v134, s[50:51]
	s_mov_b32 m0, s81
	s_nop 0
	global_load_lds_dwordx4 v132, s[52:53]
	s_mov_b32 m0, s80
	s_nop 0
	global_load_lds_dwordx4 v134, s[52:53]
	s_add_u32 s100, s48, s18
	s_addc_u32 s101, s49, s19
	s_mov_b32 m0, s61
	s_nop 0
	global_load_lds_dwordx4 v128, s[48:49]
	s_mov_b32 m0, s62
	s_nop 0
	global_load_lds_dwordx4 v130, s[48:49]
	s_waitcnt vmcnt(8)
	s_waitcnt lgkmcnt(0)
	s_barrier
; #define PG8_STAGE(bufoff, gbase, voff) do { _Pragma("unroll") for (int _i = 0; _i < 2; ++_i) \
;         __builtin_amdgcn_global_load_lds((const unsigned*)((const char*)(gbase) + (voff)[_i]), (LAS unsigned*)(lds + (bufoff) + ldsw + _i * 8192), 16, 0, 0); } while (0)
; #define PG8_LDA(dst, b, h) do { _Pragma("unroll") for (int m = 0; m < 4; ++m) _Pragma("unroll") for (int k = 0; k < 2; ++k) dst[m][k] = *(const LAS bf16x8*)(lds + PG8_SA(b, h) + aoff + m * 2048 + k * 1024); } while (0)
; #define PG8_LDB(dst, b, h) do { _Pragma("unroll") for (int n = 0; n < 2; ++n) _Pragma("unroll") for (int k = 0; k < 2; ++k) dst[n][k] = *(const LAS bf16x8*)(lds + PG8_SB(b, h) + boff + n * 2048 + k * 1024); } while (0)
; #define PG8_WAIT_V(n) asm volatile("s_waitcnt vmcnt(" #n ")" ::: "memory")
; template <class Epi, class Sched, bool SP2 = PG8_SP2>
; __device__ __forceinline__ void gemm_phase(LAS unsigned char* lds, const Gemm g, const Sched& S, const Epi& E) {
;     ...
;         for (int t = 0; t < nt; t += 2) {
;             const bool last = (t == nt - 2);
;             const char* a1 = cA + (size_t)(t + 1) * kstep;
;             const char* a2 = last ? nA : cA + (size_t)(t + 2) * kstep; const char* b2 = last ? nB : cB + (size_t)(t + 2) * kstep;
;             const char* a3 = a2 + kstep; const char* b3 = b2 + kstep;
;             if constexpr (SP2) {
;             PG8_LDB(B0, 0, 0); PG8_LDB(B1, 0, 1); PG8_SCHED; PG8_LDA(At, 0, 0); PG8_STAGE(PG8_SA(1, 1), a1 + hstepA, voffA);
;             PG8_WAIT_V(8); PG8_WAIT_L(0); PG8_BAR; PG8_MMA(0, 0, At, B0); PG8_MMA(0, 1, At, B1); PG8_BAR; PG8_SCHED;
;             PG8_LDA(At, 0, 1); PG8_STAGE(PG8_SB(0, 0), b2, voffB); PG8_STAGE(PG8_SB(0, 1), b2 + hstepB, voffB); PG8_STAGE(PG8_SA(0, 0), a2, voffA);
;             PG8_WAIT_V(8); PG8_WAIT_L(0); PG8_BAR; PG8_MMA(1, 0, At, B0); PG8_MMA(1, 1, At, B1); PG8_BAR; PG8_SCHED;
;             PG8_LDB(B0, 1, 0); PG8_LDB(B1, 1, 1); PG8_SCHED; PG8_LDA(At, 1, 0); PG8_STAGE(PG8_SA(0, 1), a2 + hstepA, voffA);
;             PG8_WAIT_V(8); PG8_WAIT_L(0); PG8_BAR; PG8_MMA(0, 0, At, B0); PG8_MMA(0, 1, At, B1); PG8_BAR; PG8_SCHED;
;             PG8_LDA(At, 1, 1); PG8_STAGE(PG8_SB(1, 0), b3, voffB); PG8_STAGE(PG8_SB(1, 1), b3 + hstepB, voffB); PG8_STAGE(PG8_SA(1, 0), a3, voffA);
;             PG8_WAIT_V(8); PG8_WAIT_L(0); PG8_BAR; PG8_MMA(1, 0, At, B0); PG8_MMA(1, 1, At, B1); PG8_BAR; PG8_SCHED;
	s_setprio 1
	s_waitcnt lgkmcnt(0)
	v_mfma_f32_16x16x32_bf16 v[60:63], v[140:143], v[192:195], v[60:63]
	v_mfma_f32_16x16x32_bf16 v[56:59], v[168:171], v[192:195], v[56:59]
	v_mfma_f32_16x16x32_bf16 v[44:47], v[140:143], v[200:203], v[44:47]
	v_mfma_f32_16x16x32_bf16 v[40:43], v[168:171], v[200:203], v[40:43]
	v_mfma_f32_16x16x32_bf16 v[28:31], v[140:143], v[208:211], v[28:31]
	v_mfma_f32_16x16x32_bf16 v[24:27], v[168:171], v[208:211], v[24:27]
	v_mfma_f32_16x16x32_bf16 v[12:15], v[140:143], v[216:219], v[12:15]
	v_mfma_f32_16x16x32_bf16 v[8:11], v[168:171], v[216:219], v[8:11]
	v_mfma_f32_16x16x32_bf16 v[60:63], v[164:167], v[196:199], v[60:63]
	v_mfma_f32_16x16x32_bf16 v[56:59], v[172:175], v[196:199], v[56:59]
	v_mfma_f32_16x16x32_bf16 v[44:47], v[164:167], v[204:207], v[44:47]
	v_mfma_f32_16x16x32_bf16 v[40:43], v[172:175], v[204:207], v[40:43]
	v_mfma_f32_16x16x32_bf16 v[28:31], v[164:167], v[212:215], v[28:31]
	v_mfma_f32_16x16x32_bf16 v[24:27], v[172:175], v[212:215], v[24:27]
	v_mfma_f32_16x16x32_bf16 v[12:15], v[164:167], v[224:227], v[12:15]
	v_mfma_f32_16x16x32_bf16 v[8:11], v[172:175], v[224:227], v[8:11]
	s_setprio 0
	s_setprio 1
	v_mfma_f32_16x16x32_bf16 v[52:55], v[176:179], v[192:195], v[52:55]
	v_mfma_f32_16x16x32_bf16 v[48:51], v[184:187], v[192:195], v[48:51]
	v_mfma_f32_16x16x32_bf16 v[36:39], v[176:179], v[200:203], v[36:39]
	v_mfma_f32_16x16x32_bf16 v[32:35], v[184:187], v[200:203], v[32:35]
	v_mfma_f32_16x16x32_bf16 v[20:23], v[176:179], v[208:211], v[20:23]
	v_mfma_f32_16x16x32_bf16 v[16:19], v[184:187], v[208:211], v[16:19]
	v_mfma_f32_16x16x32_bf16 v[4:7], v[176:179], v[216:219], v[4:7]
	v_mfma_f32_16x16x32_bf16 v[0:3], v[184:187], v[216:219], v[0:3]
	v_mfma_f32_16x16x32_bf16 v[52:55], v[180:183], v[196:199], v[52:55]
	v_mfma_f32_16x16x32_bf16 v[48:51], v[188:191], v[196:199], v[48:51]
	v_mfma_f32_16x16x32_bf16 v[36:39], v[180:183], v[204:207], v[36:39]
	v_mfma_f32_16x16x32_bf16 v[32:35], v[188:191], v[204:207], v[32:35]
	v_mfma_f32_16x16x32_bf16 v[20:23], v[180:183], v[212:215], v[20:23]
	v_mfma_f32_16x16x32_bf16 v[16:19], v[188:191], v[212:215], v[16:19]
	v_mfma_f32_16x16x32_bf16 v[4:7], v[180:183], v[224:227], v[4:7]
	v_mfma_f32_16x16x32_bf16 v[0:3], v[188:191], v[224:227], v[0:3]
	s_setprio 0
	s_barrier
	v_add_u32_e32 v172, s78, v147
	v_add_u32_e32 v188, s73, v147
	ds_read_b128 v[140:143], v172
	ds_read_b128 v[164:167], v172 offset:1024
	ds_read_b128 v[168:171], v172 offset:2048
	ds_read_b128 v[172:175], v172 offset:3072
	ds_read_b128 v[176:179], v188
	ds_read_b128 v[180:183], v188 offset:1024
	ds_read_b128 v[184:187], v188 offset:2048
	ds_read_b128 v[188:191], v188 offset:3072
	s_mov_b32 m0, s63
	ds_read_b128 v[192:195], v151 offset:32768
	ds_read_b128 v[196:199], v151 offset:33792
	ds_read_b128 v[200:203], v151 offset:34816
	ds_read_b128 v[204:207], v151 offset:35840
	ds_read_b128 v[208:211], v151 offset:36864
	ds_read_b128 v[212:215], v151 offset:37888
	ds_read_b128 v[216:219], v151 offset:38912
	ds_read_b128 v[224:227], v151 offset:39936
	global_load_lds_dwordx4 v128, s[46:47]
	s_mov_b32 m0, s64
	s_nop 0
	global_load_lds_dwordx4 v130, s[46:47]
	s_waitcnt vmcnt(8)
	s_waitcnt lgkmcnt(0)
	s_barrier
	s_setprio 1
	s_waitcnt lgkmcnt(0)
	v_mfma_f32_16x16x32_bf16 v[124:127], v[140:143], v[192:195], v[124:127]
	v_mfma_f32_16x16x32_bf16 v[120:123], v[168:171], v[192:195], v[120:123]
	v_mfma_f32_16x16x32_bf16 v[108:111], v[140:143], v[200:203], v[108:111]
	v_mfma_f32_16x16x32_bf16 v[104:107], v[168:171], v[200:203], v[104:107]
	v_mfma_f32_16x16x32_bf16 v[92:95], v[140:143], v[208:211], v[92:95]
	v_mfma_f32_16x16x32_bf16 v[88:91], v[168:171], v[208:211], v[88:91]
	v_mfma_f32_16x16x32_bf16 v[84:87], v[140:143], v[216:219], v[84:87]
	v_mfma_f32_16x16x32_bf16 v[72:75], v[168:171], v[216:219], v[72:75]
	v_mfma_f32_16x16x32_bf16 v[124:127], v[164:167], v[196:199], v[124:127]
	v_mfma_f32_16x16x32_bf16 v[120:123], v[172:175], v[196:199], v[120:123]
	v_mfma_f32_16x16x32_bf16 v[108:111], v[164:167], v[204:207], v[108:111]
	v_mfma_f32_16x16x32_bf16 v[104:107], v[172:175], v[204:207], v[104:107]
	v_mfma_f32_16x16x32_bf16 v[92:95], v[164:167], v[212:215], v[92:95]
	v_mfma_f32_16x16x32_bf16 v[88:91], v[172:175], v[212:215], v[88:91]
	v_mfma_f32_16x16x32_bf16 v[84:87], v[164:167], v[224:227], v[84:87]
	v_mfma_f32_16x16x32_bf16 v[72:75], v[172:175], v[224:227], v[72:75]
	s_setprio 0
	s_setprio 1
	v_mfma_f32_16x16x32_bf16 v[116:119], v[176:179], v[192:195], v[116:119]
	v_mfma_f32_16x16x32_bf16 v[112:115], v[184:187], v[192:195], v[112:115]
	v_mfma_f32_16x16x32_bf16 v[100:103], v[176:179], v[200:203], v[100:103]
	v_mfma_f32_16x16x32_bf16 v[96:99], v[184:187], v[200:203], v[96:99]
	v_mfma_f32_16x16x32_bf16 v[80:83], v[176:179], v[208:211], v[80:83]
	v_mfma_f32_16x16x32_bf16 v[76:79], v[184:187], v[208:211], v[76:79]
	v_mfma_f32_16x16x32_bf16 v[68:71], v[176:179], v[216:219], v[68:71]
	v_mfma_f32_16x16x32_bf16 v[64:67], v[184:187], v[216:219], v[64:67]
	v_mfma_f32_16x16x32_bf16 v[116:119], v[180:183], v[196:199], v[116:119]
	v_mfma_f32_16x16x32_bf16 v[112:115], v[188:191], v[196:199], v[112:115]
	v_mfma_f32_16x16x32_bf16 v[100:103], v[180:183], v[204:207], v[100:103]
	v_mfma_f32_16x16x32_bf16 v[96:99], v[188:191], v[204:207], v[96:99]
	v_mfma_f32_16x16x32_bf16 v[80:83], v[180:183], v[212:215], v[80:83]
	v_mfma_f32_16x16x32_bf16 v[76:79], v[188:191], v[212:215], v[76:79]
	v_mfma_f32_16x16x32_bf16 v[68:71], v[180:183], v[224:227], v[68:71]
	v_mfma_f32_16x16x32_bf16 v[64:67], v[188:191], v[224:227], v[64:67]
	s_setprio 0
	s_barrier
; #define PG8_STAGE(bufoff, gbase, voff) do { _Pragma("unroll") for (int _i = 0; _i < 2; ++_i) \
;         __builtin_amdgcn_global_load_lds((const unsigned*)((const char*)(gbase) + (voff)[_i]), (LAS unsigned*)(lds + (bufoff) + ldsw + _i * 8192), 16, 0, 0); } while (0)
; #define PG8_LDA(dst, b, h) do { _Pragma("unroll") for (int m = 0; m < 4; ++m) _Pragma("unroll") for (int k = 0; k < 2; ++k) dst[m][k] = *(const LAS bf16x8*)(lds + PG8_SA(b, h) + aoff + m * 2048 + k * 1024); } while (0)
; #define PG8_LDB(dst, b, h) do { _Pragma("unroll") for (int n = 0; n < 2; ++n) _Pragma("unroll") for (int k = 0; k < 2; ++k) dst[n][k] = *(const LAS bf16x8*)(lds + PG8_SB(b, h) + boff + n * 2048 + k * 1024); } while (0)
; #define PG8_WAIT_V(n) asm volatile("s_waitcnt vmcnt(" #n ")" ::: "memory")
; template <class Epi, class Sched, bool SP2 = PG8_SP2>
; __device__ __forceinline__ void gemm_phase(LAS unsigned char* lds, const Gemm g, const Sched& S, const Epi& E) {
;     ...
;         for (int t = 0; t < nt; t += 2) {
;             const bool last = (t == nt - 2);
;             const char* a1 = cA + (size_t)(t + 1) * kstep;
;             const char* a2 = last ? nA : cA + (size_t)(t + 2) * kstep; const char* b2 = last ? nB : cB + (size_t)(t + 2) * kstep;
;             const char* a3 = a2 + kstep; const char* b3 = b2 + kstep;
;             if constexpr (SP2) {
;             PG8_LDB(B0, 0, 0); PG8_LDB(B1, 0, 1); PG8_SCHED; PG8_LDA(At, 0, 0); PG8_STAGE(PG8_SA(1, 1), a1 + hstepA, voffA);
;             PG8_WAIT_V(8); PG8_WAIT_L(0); PG8_BAR; PG8_MMA(0, 0, At, B0); PG8_MMA(0, 1, At, B1); PG8_BAR; PG8_SCHED;
;             PG8_LDA(At, 0, 1); PG8_STAGE(PG8_SB(0, 0), b2, voffB); PG8_STAGE(PG8_SB(0, 1), b2 + hstepB, voffB); PG8_STAGE(PG8_SA(0, 0), a2, voffA);
;             PG8_WAIT_V(8); PG8_WAIT_L(0); PG8_BAR; PG8_MMA(1, 0, At, B0); PG8_MMA(1, 1, At, B1); PG8_BAR; PG8_SCHED;
;             PG8_LDB(B0, 1, 0); PG8_LDB(B1, 1, 1); PG8_SCHED; PG8_LDA(At, 1, 0); PG8_STAGE(PG8_SA(0, 1), a2 + hstepA, voffA);
;             PG8_WAIT_V(8); PG8_WAIT_L(0); PG8_BAR; PG8_MMA(0, 0, At, B0); PG8_MMA(0, 1, At, B1); PG8_BAR; PG8_SCHED;
;             PG8_LDA(At, 1, 1); PG8_STAGE(PG8_SB(1, 0), b3, voffB); PG8_STAGE(PG8_SB(1, 1), b3 + hstepB, voffB); PG8_STAGE(PG8_SA(1, 0), a3, voffA);
;             PG8_WAIT_V(8); PG8_WAIT_L(0); PG8_BAR; PG8_MMA(1, 0, At, B0); PG8_MMA(1, 1, At, B1); PG8_BAR; PG8_SCHED;
	s_mov_b32 m0, s72
	ds_read_b128 v[192:195], v151 offset:49152
	ds_read_b128 v[196:199], v151 offset:50176
	ds_read_b128 v[200:203], v151 offset:51200
	ds_read_b128 v[204:207], v151 offset:52224
	ds_read_b128 v[208:211], v151 offset:53248
	ds_read_b128 v[212:215], v151 offset:54272
	ds_read_b128 v[216:219], v151 offset:55296
	ds_read_b128 v[224:227], v151 offset:56320
	global_load_lds_dwordx4 v132, s[98:99]
	s_mov_b32 m0, s3
	s_nop 0
	global_load_lds_dwordx4 v134, s[98:99]
	s_mov_b32 m0, s84
	s_nop 0
	global_load_lds_dwordx4 v132, s[44:45]
	s_mov_b32 m0, s83
	s_nop 0
	global_load_lds_dwordx4 v134, s[44:45]
	s_mov_b32 m0, s66
	s_nop 0
	global_load_lds_dwordx4 v128, s[100:101]
	s_mov_b32 m0, s67
	s_nop 0
	global_load_lds_dwordx4 v130, s[100:101]
	s_waitcnt vmcnt(8)
	s_waitcnt lgkmcnt(0)
	s_barrier
	s_setprio 1
	s_waitcnt lgkmcnt(0)
	v_mfma_f32_16x16x32_bf16 v[60:63], v[140:143], v[192:195], v[60:63]
	v_mfma_f32_16x16x32_bf16 v[56:59], v[168:171], v[192:195], v[56:59]
	v_mfma_f32_16x16x32_bf16 v[44:47], v[140:143], v[200:203], v[44:47]
	v_mfma_f32_16x16x32_bf16 v[40:43], v[168:171], v[200:203], v[40:43]
	v_mfma_f32_16x16x32_bf16 v[28:31], v[140:143], v[208:211], v[28:31]
	v_mfma_f32_16x16x32_bf16 v[24:27], v[168:171], v[208:211], v[24:27]
	v_mfma_f32_16x16x32_bf16 v[12:15], v[140:143], v[216:219], v[12:15]
	v_mfma_f32_16x16x32_bf16 v[8:11], v[168:171], v[216:219], v[8:11]
	v_mfma_f32_16x16x32_bf16 v[60:63], v[164:167], v[196:199], v[60:63]
	v_mfma_f32_16x16x32_bf16 v[56:59], v[172:175], v[196:199], v[56:59]
	v_mfma_f32_16x16x32_bf16 v[44:47], v[164:167], v[204:207], v[44:47]
	v_mfma_f32_16x16x32_bf16 v[40:43], v[172:175], v[204:207], v[40:43]
	v_mfma_f32_16x16x32_bf16 v[28:31], v[164:167], v[212:215], v[28:31]
	v_mfma_f32_16x16x32_bf16 v[24:27], v[172:175], v[212:215], v[24:27]
	v_mfma_f32_16x16x32_bf16 v[12:15], v[164:167], v[224:227], v[12:15]
	v_mfma_f32_16x16x32_bf16 v[8:11], v[172:175], v[224:227], v[8:11]
	s_setprio 0
	s_setprio 1
	v_mfma_f32_16x16x32_bf16 v[52:55], v[176:179], v[192:195], v[52:55]
	v_mfma_f32_16x16x32_bf16 v[48:51], v[184:187], v[192:195], v[48:51]
	v_mfma_f32_16x16x32_bf16 v[36:39], v[176:179], v[200:203], v[36:39]
	v_mfma_f32_16x16x32_bf16 v[32:35], v[184:187], v[200:203], v[32:35]
	v_mfma_f32_16x16x32_bf16 v[20:23], v[176:179], v[208:211], v[20:23]
	v_mfma_f32_16x16x32_bf16 v[16:19], v[184:187], v[208:211], v[16:19]
	v_mfma_f32_16x16x32_bf16 v[4:7], v[176:179], v[216:219], v[4:7]
	v_mfma_f32_16x16x32_bf16 v[0:3], v[184:187], v[216:219], v[0:3]
	v_mfma_f32_16x16x32_bf16 v[52:55], v[180:183], v[196:199], v[52:55]
	v_mfma_f32_16x16x32_bf16 v[48:51], v[188:191], v[196:199], v[48:51]
	v_mfma_f32_16x16x32_bf16 v[36:39], v[180:183], v[204:207], v[36:39]
	v_mfma_f32_16x16x32_bf16 v[32:35], v[188:191], v[204:207], v[32:35]
	v_mfma_f32_16x16x32_bf16 v[20:23], v[180:183], v[212:215], v[20:23]
	v_mfma_f32_16x16x32_bf16 v[16:19], v[188:191], v[212:215], v[16:19]
	v_mfma_f32_16x16x32_bf16 v[4:7], v[180:183], v[224:227], v[4:7]
	v_mfma_f32_16x16x32_bf16 v[0:3], v[188:191], v[224:227], v[0:3]
	s_setprio 0
	s_barrier
	s_movk_i32 s3, 0x100
	s_andn2_b64 vcc, exec, s[0:1]
	s_mov_b64 s[44:45], -1
	s_mov_b64 s[0:1], 0
	s_cbranch_vccz .LBB0_359
	s_and_b64 vcc, exec, s[20:21]
	s_cbranch_vccz .LBB0_362
	s_barrier

; #define PG8_STAGE(bufoff, gbase, voff) do { _Pragma("unroll") for (int _i = 0; _i < 2; ++_i) \
;         __builtin_amdgcn_global_load_lds((const unsigned*)((const char*)(gbase) + (voff)[_i]), (LAS unsigned*)(lds + (bufoff) + ldsw + _i * 8192), 16, 0, 0); } while (0)
; #define PG8_LDA(dst, b, h) do { _Pragma("unroll") for (int m = 0; m < 4; ++m) _Pragma("unroll") for (int k = 0; k < 2; ++k) dst[m][k] = *(const LAS bf16x8*)(lds + PG8_SA(b, h) + aoff + m * 2048 + k * 1024); } while (0)
; #define PG8_LDB(dst, b, h) do { _Pragma("unroll") for (int n = 0; n < 2; ++n) _Pragma("unroll") for (int k = 0; k < 2; ++k) dst[n][k] = *(const LAS bf16x8*)(lds + PG8_SB(b, h) + boff + n * 2048 + k * 1024); } while (0)
; #define PG8_WAIT_V(n) asm volatile("s_waitcnt vmcnt(" #n ")" ::: "memory")
; template <class Epi, class Sched, bool SP2 = PG8_SP2>
; __device__ __forceinline__ void gemm_phase(LAS unsigned char* lds, const Gemm g, const Sched& S, const Epi& E) {
;     ...
;         for (int t = 0; t < nt; t += 2) {
;             const bool last = (t == nt - 2);
;             const char* a1 = cA + (size_t)(t + 1) * kstep;
;             const char* a2 = last ? nA : cA + (size_t)(t + 2) * kstep; const char* b2 = last ? nB : cB + (size_t)(t + 2) * kstep;
;             const char* a3 = a2 + kstep; const char* b3 = b2 + kstep;
;             if constexpr (SP2) {
;             PG8_LDB(B0, 0, 0); PG8_LDB(B1, 0, 1); PG8_SCHED; PG8_LDA(At, 0, 0); PG8_STAGE(PG8_SA(1, 1), a1 + hstepA, voffA);
;             PG8_WAIT_V(8); PG8_WAIT_L(0); PG8_BAR; PG8_MMA(0, 0, At, B0); PG8_MMA(0, 1, At, B1); PG8_BAR; PG8_SCHED;
;             PG8_LDA(At, 0, 1); PG8_STAGE(PG8_SB(0, 0), b2, voffB); PG8_STAGE(PG8_SB(0, 1), b2 + hstepB, voffB); PG8_STAGE(PG8_SA(0, 0), a2, voffA);
;             PG8_WAIT_V(8); PG8_WAIT_L(0); PG8_BAR; PG8_MMA(1, 0, At, B0); PG8_MMA(1, 1, At, B1); PG8_BAR; PG8_SCHED;
;             PG8_LDB(B0, 1, 0); PG8_LDB(B1, 1, 1); PG8_SCHED; PG8_LDA(At, 1, 0); PG8_STAGE(PG8_SA(0, 1), a2 + hstepA, voffA);
;             PG8_WAIT_V(8); PG8_WAIT_L(0); PG8_BAR; PG8_MMA(0, 0, At, B0); PG8_MMA(0, 1, At, B1); PG8_BAR; PG8_SCHED;
;             PG8_LDA(At, 1, 1); PG8_STAGE(PG8_SB(1, 0), b3, voffB); PG8_STAGE(PG8_SB(1, 1), b3 + hstepB, voffB); PG8_STAGE(PG8_SA(1, 0), a3, voffA);
;             PG8_WAIT_V(8); PG8_WAIT_L(0); PG8_BAR; PG8_MMA(1, 0, At, B0); PG8_MMA(1, 1, At, B1); PG8_BAR; PG8_SCHED;
.LBB0_395:
	ds_read_b128 v[152:155], v149
	ds_read_b128 v[156:159], v149 offset:1024
	ds_read_b128 v[160:163], v149 offset:2048
	ds_read_b128 v[164:167], v149 offset:3072
	ds_read_b128 v[168:171], v150
	ds_read_b128 v[172:175], v150 offset:1024
	ds_read_b128 v[176:179], v150 offset:2048
	ds_read_b128 v[180:183], v150 offset:3072
	s_add_u32 s3, s0, 0xfffe0080
	s_addc_u32 s36, s1, -1
	s_cmp_eq_u32 s62, 4
	s_cselect_b32 s39, s2, s36
	s_cselect_b32 s38, s27, s3
	s_cselect_b32 s37, s25, s61
	s_cselect_b32 s36, s59, s60
	s_add_i32 m0, s35, 0xc000
	ds_read_b128 v[184:187], v151
	ds_read_b128 v[188:191], v151 offset:1024
	ds_read_b128 v[192:195], v151 offset:2048
	ds_read_b128 v[196:199], v151 offset:3072
	ds_read_b128 v[200:203], v151 offset:4096
	ds_read_b128 v[204:207], v151 offset:5120
	ds_read_b128 v[208:211], v151 offset:6144
	ds_read_b128 v[212:215], v151 offset:7168
	global_load_lds_dwordx4 v136, s[0:1]
	s_add_i32 m0, s35, 0xe000
	s_nop 0
	global_load_lds_dwordx4 v138, s[0:1]
	s_waitcnt vmcnt(8)
	s_waitcnt lgkmcnt(0)
	s_barrier
	s_setprio 1
	s_waitcnt lgkmcnt(0)
	v_mfma_f32_16x16x32_bf16 v[124:127], v[152:155], v[184:187], v[124:127]
	v_mfma_f32_16x16x32_bf16 v[120:123], v[160:163], v[184:187], v[120:123]
	v_mfma_f32_16x16x32_bf16 v[116:119], v[152:155], v[192:195], v[116:119]
	v_mfma_f32_16x16x32_bf16 v[108:111], v[160:163], v[192:195], v[108:111]
	v_mfma_f32_16x16x32_bf16 v[100:103], v[152:155], v[200:203], v[100:103]
	v_mfma_f32_16x16x32_bf16 v[92:95], v[160:163], v[200:203], v[92:95]
	v_mfma_f32_16x16x32_bf16 v[84:87], v[152:155], v[208:211], v[84:87]
	v_mfma_f32_16x16x32_bf16 v[76:79], v[160:163], v[208:211], v[76:79]
	v_mfma_f32_16x16x32_bf16 v[124:127], v[156:159], v[188:191], v[124:127]
	v_mfma_f32_16x16x32_bf16 v[120:123], v[164:167], v[188:191], v[120:123]
	v_mfma_f32_16x16x32_bf16 v[116:119], v[156:159], v[196:199], v[116:119]
	v_mfma_f32_16x16x32_bf16 v[108:111], v[164:167], v[196:199], v[108:111]
	v_mfma_f32_16x16x32_bf16 v[100:103], v[156:159], v[204:207], v[100:103]
	v_mfma_f32_16x16x32_bf16 v[92:95], v[164:167], v[204:207], v[92:95]
	v_mfma_f32_16x16x32_bf16 v[84:87], v[156:159], v[212:215], v[84:87]
	v_mfma_f32_16x16x32_bf16 v[76:79], v[164:167], v[212:215], v[76:79]
	s_setprio 0
	s_setprio 1
	v_mfma_f32_16x16x32_bf16 v[112:115], v[168:171], v[184:187], v[112:115]
	v_mfma_f32_16x16x32_bf16 v[104:107], v[176:179], v[184:187], v[104:107]
	v_mfma_f32_16x16x32_bf16 v[96:99], v[168:171], v[192:195], v[96:99]
	v_mfma_f32_16x16x32_bf16 v[88:91], v[176:179], v[192:195], v[88:91]
	v_mfma_f32_16x16x32_bf16 v[80:83], v[168:171], v[200:203], v[80:83]
	v_mfma_f32_16x16x32_bf16 v[72:75], v[176:179], v[200:203], v[72:75]
	v_mfma_f32_16x16x32_bf16 v[68:71], v[168:171], v[208:211], v[68:71]
	v_mfma_f32_16x16x32_bf16 v[64:67], v[176:179], v[208:211], v[64:67]
	v_mfma_f32_16x16x32_bf16 v[112:115], v[172:175], v[188:191], v[112:115]
	v_mfma_f32_16x16x32_bf16 v[104:107], v[180:183], v[188:191], v[104:107]
	v_mfma_f32_16x16x32_bf16 v[96:99], v[172:175], v[196:199], v[96:99]
	v_mfma_f32_16x16x32_bf16 v[88:91], v[180:183], v[196:199], v[88:91]
	v_mfma_f32_16x16x32_bf16 v[80:83], v[172:175], v[204:207], v[80:83]
	v_mfma_f32_16x16x32_bf16 v[72:75], v[180:183], v[204:207], v[72:75]
	v_mfma_f32_16x16x32_bf16 v[68:71], v[172:175], v[212:215], v[68:71]
	v_mfma_f32_16x16x32_bf16 v[64:67], v[180:183], v[212:215], v[64:67]
	s_setprio 0
	s_barrier
	s_add_i32 s3, s52, s44
	s_add_u32 s98, s36, s12
	s_addc_u32 s99, s37, s13
	s_mov_b32 m0, s3
	ds_read_b128 v[184:187], v151 offset:16384
	ds_read_b128 v[188:191], v151 offset:17408
	ds_read_b128 v[192:195], v151 offset:18432
	ds_read_b128 v[196:199], v151 offset:19456
	ds_read_b128 v[200:203], v151 offset:20480
	ds_read_b128 v[204:207], v151 offset:21504
	ds_read_b128 v[208:211], v151 offset:22528
	ds_read_b128 v[212:215], v151 offset:23552
	global_load_lds_dwordx4 v130, s[36:37]
	s_add_i32 m0, s3, 0x2000
	s_add_u32 s64, s36, 0x20000
	s_addc_u32 s65, s37, 0
	s_add_i32 s3, s53, s44
	global_load_lds_dwordx4 v134, s[36:37]
	s_mov_b32 m0, s3
	s_nop 0
	global_load_lds_dwordx4 v130, s[64:65]
	s_add_i32 m0, s3, 0x2000
	s_nop 0
	global_load_lds_dwordx4 v134, s[64:65]
	s_add_u32 s100, s38, s12
	s_addc_u32 s101, s39, s13
	s_mov_b32 m0, s35
	s_nop 0
	global_load_lds_dwordx4 v128, s[38:39]
	s_mov_b32 m0, s45
	s_nop 0
	global_load_lds_dwordx4 v132, s[38:39]
	s_waitcnt vmcnt(8)
	s_waitcnt lgkmcnt(0)
	s_barrier
	s_setprio 1
	s_waitcnt lgkmcnt(0)
	v_mfma_f32_16x16x32_bf16 v[60:63], v[152:155], v[184:187], v[60:63]
	v_mfma_f32_16x16x32_bf16 v[56:59], v[160:163], v[184:187], v[56:59]
	v_mfma_f32_16x16x32_bf16 v[52:55], v[152:155], v[192:195], v[52:55]
	v_mfma_f32_16x16x32_bf16 v[44:47], v[160:163], v[192:195], v[44:47]
	v_mfma_f32_16x16x32_bf16 v[36:39], v[152:155], v[200:203], v[36:39]
	v_mfma_f32_16x16x32_bf16 v[28:31], v[160:163], v[200:203], v[28:31]
	v_mfma_f32_16x16x32_bf16 v[20:23], v[152:155], v[208:211], v[20:23]
	v_mfma_f32_16x16x32_bf16 v[12:15], v[160:163], v[208:211], v[12:15]
	v_mfma_f32_16x16x32_bf16 v[60:63], v[156:159], v[188:191], v[60:63]
	v_mfma_f32_16x16x32_bf16 v[56:59], v[164:167], v[188:191], v[56:59]
	v_mfma_f32_16x16x32_bf16 v[52:55], v[156:159], v[196:199], v[52:55]
	v_mfma_f32_16x16x32_bf16 v[44:47], v[164:167], v[196:199], v[44:47]
	v_mfma_f32_16x16x32_bf16 v[36:39], v[156:159], v[204:207], v[36:39]
	v_mfma_f32_16x16x32_bf16 v[28:31], v[164:167], v[204:207], v[28:31]
	v_mfma_f32_16x16x32_bf16 v[20:23], v[156:159], v[212:215], v[20:23]
	v_mfma_f32_16x16x32_bf16 v[12:15], v[164:167], v[212:215], v[12:15]
	s_setprio 0
	s_setprio 1
	v_mfma_f32_16x16x32_bf16 v[48:51], v[168:171], v[184:187], v[48:51]
	v_mfma_f32_16x16x32_bf16 v[40:43], v[176:179], v[184:187], v[40:43]
	v_mfma_f32_16x16x32_bf16 v[32:35], v[168:171], v[192:195], v[32:35]
	v_mfma_f32_16x16x32_bf16 v[24:27], v[176:179], v[192:195], v[24:27]
	v_mfma_f32_16x16x32_bf16 v[16:19], v[168:171], v[200:203], v[16:19]
	v_mfma_f32_16x16x32_bf16 v[8:11], v[176:179], v[200:203], v[8:11]
	v_mfma_f32_16x16x32_bf16 v[4:7], v[168:171], v[208:211], v[4:7]
	v_mfma_f32_16x16x32_bf16 v[0:3], v[176:179], v[208:211], v[0:3]
	v_mfma_f32_16x16x32_bf16 v[48:51], v[172:175], v[188:191], v[48:51]
	v_mfma_f32_16x16x32_bf16 v[40:43], v[180:183], v[188:191], v[40:43]
	v_mfma_f32_16x16x32_bf16 v[32:35], v[172:175], v[196:199], v[32:35]
	v_mfma_f32_16x16x32_bf16 v[24:27], v[180:183], v[196:199], v[24:27]
	v_mfma_f32_16x16x32_bf16 v[16:19], v[172:175], v[204:207], v[16:19]
	v_mfma_f32_16x16x32_bf16 v[8:11], v[180:183], v[204:207], v[8:11]
	v_mfma_f32_16x16x32_bf16 v[4:7], v[172:175], v[212:215], v[4:7]
	v_mfma_f32_16x16x32_bf16 v[0:3], v[180:183], v[212:215], v[0:3]
	s_setprio 0
	s_barrier
; #define PG8_STAGE(bufoff, gbase, voff) do { _Pragma("unroll") for (int _i = 0; _i < 2; ++_i) \
;         __builtin_amdgcn_global_load_lds((const unsigned*)((const char*)(gbase) + (voff)[_i]), (LAS unsigned*)(lds + (bufoff) + ldsw + _i * 8192), 16, 0, 0); } while (0)
; #define PG8_LDA(dst, b, h) do { _Pragma("unroll") for (int m = 0; m < 4; ++m) _Pragma("unroll") for (int k = 0; k < 2; ++k) dst[m][k] = *(const LAS bf16x8*)(lds + PG8_SA(b, h) + aoff + m * 2048 + k * 1024); } while (0)
; #define PG8_LDB(dst, b, h) do { _Pragma("unroll") for (int n = 0; n < 2; ++n) _Pragma("unroll") for (int k = 0; k < 2; ++k) dst[n][k] = *(const LAS bf16x8*)(lds + PG8_SB(b, h) + boff + n * 2048 + k * 1024); } while (0)
; #define PG8_WAIT_V(n) asm volatile("s_waitcnt vmcnt(" #n ")" ::: "memory")
; template <class Epi, class Sched, bool SP2 = PG8_SP2>
; __device__ __forceinline__ void gemm_phase(LAS unsigned char* lds, const Gemm g, const Sched& S, const Epi& E) {
;     ...
;         for (int t = 0; t < nt; t += 2) {
;             const bool last = (t == nt - 2);
;             const char* a1 = cA + (size_t)(t + 1) * kstep;
;             const char* a2 = last ? nA : cA + (size_t)(t + 2) * kstep; const char* b2 = last ? nB : cB + (size_t)(t + 2) * kstep;
;             const char* a3 = a2 + kstep; const char* b3 = b2 + kstep;
;             if constexpr (SP2) {
;             PG8_LDB(B0, 0, 0); PG8_LDB(B1, 0, 1); PG8_SCHED; PG8_LDA(At, 0, 0); PG8_STAGE(PG8_SA(1, 1), a1 + hstepA, voffA);
;             PG8_WAIT_V(8); PG8_WAIT_L(0); PG8_BAR; PG8_MMA(0, 0, At, B0); PG8_MMA(0, 1, At, B1); PG8_BAR; PG8_SCHED;
;             PG8_LDA(At, 0, 1); PG8_STAGE(PG8_SB(0, 0), b2, voffB); PG8_STAGE(PG8_SB(0, 1), b2 + hstepB, voffB); PG8_STAGE(PG8_SA(0, 0), a2, voffA);
;             PG8_WAIT_V(8); PG8_WAIT_L(0); PG8_BAR; PG8_MMA(1, 0, At, B0); PG8_MMA(1, 1, At, B1); PG8_BAR; PG8_SCHED;
;             PG8_LDB(B0, 1, 0); PG8_LDB(B1, 1, 1); PG8_SCHED; PG8_LDA(At, 1, 0); PG8_STAGE(PG8_SA(0, 1), a2 + hstepA, voffA);
;             PG8_WAIT_V(8); PG8_WAIT_L(0); PG8_BAR; PG8_MMA(0, 0, At, B0); PG8_MMA(0, 1, At, B1); PG8_BAR; PG8_SCHED;
;             PG8_LDA(At, 1, 1); PG8_STAGE(PG8_SB(1, 0), b3, voffB); PG8_STAGE(PG8_SB(1, 1), b3 + hstepB, voffB); PG8_STAGE(PG8_SA(1, 0), a3, voffA);
;             PG8_WAIT_V(8); PG8_WAIT_L(0); PG8_BAR; PG8_MMA(1, 0, At, B0); PG8_MMA(1, 1, At, B1); PG8_BAR; PG8_SCHED;
	s_add_i32 s3, 0, 0x18000
	s_add_i32 s63, 0, 0x1c000
	v_add_u32_e32 v164, s3, v147
	v_add_u32_e32 v180, s63, v147
	ds_read_b128 v[152:155], v164
	ds_read_b128 v[156:159], v164 offset:1024
	ds_read_b128 v[160:163], v164 offset:2048
	ds_read_b128 v[164:167], v164 offset:3072
	ds_read_b128 v[168:171], v180
	ds_read_b128 v[172:175], v180 offset:1024
	ds_read_b128 v[176:179], v180 offset:2048
	ds_read_b128 v[180:183], v180 offset:3072
	s_add_u32 s38, s38, 0x20000
	s_addc_u32 s39, s39, 0
	s_mov_b32 m0, s46
	ds_read_b128 v[184:187], v151 offset:32768
	ds_read_b128 v[188:191], v151 offset:33792
	ds_read_b128 v[192:195], v151 offset:34816
	ds_read_b128 v[196:199], v151 offset:35840
	ds_read_b128 v[200:203], v151 offset:36864
	ds_read_b128 v[204:207], v151 offset:37888
	ds_read_b128 v[208:211], v151 offset:38912
	ds_read_b128 v[212:215], v151 offset:39936
	global_load_lds_dwordx4 v128, s[38:39]
	s_mov_b32 m0, s47
	s_nop 0
	global_load_lds_dwordx4 v132, s[38:39]
	s_waitcnt vmcnt(8)
	s_waitcnt lgkmcnt(0)
	s_barrier
	s_setprio 1
	s_waitcnt lgkmcnt(0)
	v_mfma_f32_16x16x32_bf16 v[124:127], v[152:155], v[184:187], v[124:127]
	v_mfma_f32_16x16x32_bf16 v[120:123], v[160:163], v[184:187], v[120:123]
	v_mfma_f32_16x16x32_bf16 v[116:119], v[152:155], v[192:195], v[116:119]
	v_mfma_f32_16x16x32_bf16 v[108:111], v[160:163], v[192:195], v[108:111]
	v_mfma_f32_16x16x32_bf16 v[100:103], v[152:155], v[200:203], v[100:103]
	v_mfma_f32_16x16x32_bf16 v[92:95], v[160:163], v[200:203], v[92:95]
	v_mfma_f32_16x16x32_bf16 v[84:87], v[152:155], v[208:211], v[84:87]
	v_mfma_f32_16x16x32_bf16 v[76:79], v[160:163], v[208:211], v[76:79]
	v_mfma_f32_16x16x32_bf16 v[124:127], v[156:159], v[188:191], v[124:127]
	v_mfma_f32_16x16x32_bf16 v[120:123], v[164:167], v[188:191], v[120:123]
	v_mfma_f32_16x16x32_bf16 v[116:119], v[156:159], v[196:199], v[116:119]
	v_mfma_f32_16x16x32_bf16 v[108:111], v[164:167], v[196:199], v[108:111]
	v_mfma_f32_16x16x32_bf16 v[100:103], v[156:159], v[204:207], v[100:103]
	v_mfma_f32_16x16x32_bf16 v[92:95], v[164:167], v[204:207], v[92:95]
	v_mfma_f32_16x16x32_bf16 v[84:87], v[156:159], v[212:215], v[84:87]
	v_mfma_f32_16x16x32_bf16 v[76:79], v[164:167], v[212:215], v[76:79]
	s_setprio 0
	s_setprio 1
	v_mfma_f32_16x16x32_bf16 v[112:115], v[168:171], v[184:187], v[112:115]
	v_mfma_f32_16x16x32_bf16 v[104:107], v[176:179], v[184:187], v[104:107]
	v_mfma_f32_16x16x32_bf16 v[96:99], v[168:171], v[192:195], v[96:99]
	v_mfma_f32_16x16x32_bf16 v[88:91], v[176:179], v[192:195], v[88:91]
	v_mfma_f32_16x16x32_bf16 v[80:83], v[168:171], v[200:203], v[80:83]
	v_mfma_f32_16x16x32_bf16 v[72:75], v[176:179], v[200:203], v[72:75]
	v_mfma_f32_16x16x32_bf16 v[68:71], v[168:171], v[208:211], v[68:71]
	v_mfma_f32_16x16x32_bf16 v[64:67], v[176:179], v[208:211], v[64:67]
	v_mfma_f32_16x16x32_bf16 v[112:115], v[172:175], v[188:191], v[112:115]
	v_mfma_f32_16x16x32_bf16 v[104:107], v[180:183], v[188:191], v[104:107]
	v_mfma_f32_16x16x32_bf16 v[96:99], v[172:175], v[196:199], v[96:99]
	v_mfma_f32_16x16x32_bf16 v[88:91], v[180:183], v[196:199], v[88:91]
	v_mfma_f32_16x16x32_bf16 v[80:83], v[172:175], v[204:207], v[80:83]
	v_mfma_f32_16x16x32_bf16 v[72:75], v[180:183], v[204:207], v[72:75]
	v_mfma_f32_16x16x32_bf16 v[68:71], v[172:175], v[212:215], v[68:71]
	v_mfma_f32_16x16x32_bf16 v[64:67], v[180:183], v[212:215], v[64:67]
	s_setprio 0
	s_barrier
	s_add_i32 s3, s3, s44
	s_mov_b32 m0, s3
	ds_read_b128 v[184:187], v151 offset:49152
	ds_read_b128 v[188:191], v151 offset:50176
	ds_read_b128 v[192:195], v151 offset:51200
	ds_read_b128 v[196:199], v151 offset:52224
	ds_read_b128 v[200:203], v151 offset:53248
	ds_read_b128 v[204:207], v151 offset:54272
	ds_read_b128 v[208:211], v151 offset:55296
	ds_read_b128 v[212:215], v151 offset:56320
	global_load_lds_dwordx4 v130, s[98:99]
	s_add_i32 m0, s3, 0x2000
	s_add_u32 s36, s36, 0x20080
	s_addc_u32 s37, s37, 0
	s_add_i32 s3, s63, s44
	global_load_lds_dwordx4 v134, s[98:99]
	s_mov_b32 m0, s3
	s_nop 0
	global_load_lds_dwordx4 v130, s[36:37]
	s_add_i32 m0, s3, 0x2000
	s_nop 0
	global_load_lds_dwordx4 v134, s[36:37]
	s_mov_b32 m0, s49
	s_nop 0
	global_load_lds_dwordx4 v128, s[100:101]
	s_mov_b32 m0, s50
	s_nop 0
	global_load_lds_dwordx4 v132, s[100:101]
	s_waitcnt vmcnt(8)
	s_waitcnt lgkmcnt(0)
	s_barrier
	s_setprio 1
	s_waitcnt lgkmcnt(0)
	v_mfma_f32_16x16x32_bf16 v[60:63], v[152:155], v[184:187], v[60:63]
	v_mfma_f32_16x16x32_bf16 v[56:59], v[160:163], v[184:187], v[56:59]
	v_mfma_f32_16x16x32_bf16 v[52:55], v[152:155], v[192:195], v[52:55]
	v_mfma_f32_16x16x32_bf16 v[44:47], v[160:163], v[192:195], v[44:47]
	v_mfma_f32_16x16x32_bf16 v[36:39], v[152:155], v[200:203], v[36:39]
	v_mfma_f32_16x16x32_bf16 v[28:31], v[160:163], v[200:203], v[28:31]
	v_mfma_f32_16x16x32_bf16 v[20:23], v[152:155], v[208:211], v[20:23]
	v_mfma_f32_16x16x32_bf16 v[12:15], v[160:163], v[208:211], v[12:15]
	v_mfma_f32_16x16x32_bf16 v[60:63], v[156:159], v[188:191], v[60:63]
	v_mfma_f32_16x16x32_bf16 v[56:59], v[164:167], v[188:191], v[56:59]
	v_mfma_f32_16x16x32_bf16 v[52:55], v[156:159], v[196:199], v[52:55]
	v_mfma_f32_16x16x32_bf16 v[44:47], v[164:167], v[196:199], v[44:47]
	v_mfma_f32_16x16x32_bf16 v[36:39], v[156:159], v[204:207], v[36:39]
	v_mfma_f32_16x16x32_bf16 v[28:31], v[164:167], v[204:207], v[28:31]
	v_mfma_f32_16x16x32_bf16 v[20:23], v[156:159], v[212:215], v[20:23]
	v_mfma_f32_16x16x32_bf16 v[12:15], v[164:167], v[212:215], v[12:15]
	s_setprio 0
	s_setprio 1
	v_mfma_f32_16x16x32_bf16 v[48:51], v[168:171], v[184:187], v[48:51]
	v_mfma_f32_16x16x32_bf16 v[40:43], v[176:179], v[184:187], v[40:43]
	v_mfma_f32_16x16x32_bf16 v[32:35], v[168:171], v[192:195], v[32:35]
	v_mfma_f32_16x16x32_bf16 v[24:27], v[176:179], v[192:195], v[24:27]
	v_mfma_f32_16x16x32_bf16 v[16:19], v[168:171], v[200:203], v[16:19]
	v_mfma_f32_16x16x32_bf16 v[8:11], v[176:179], v[200:203], v[8:11]
	v_mfma_f32_16x16x32_bf16 v[4:7], v[168:171], v[208:211], v[4:7]
	v_mfma_f32_16x16x32_bf16 v[0:3], v[176:179], v[208:211], v[0:3]
	v_mfma_f32_16x16x32_bf16 v[48:51], v[172:175], v[188:191], v[48:51]
	v_mfma_f32_16x16x32_bf16 v[40:43], v[180:183], v[188:191], v[40:43]
	v_mfma_f32_16x16x32_bf16 v[32:35], v[172:175], v[196:199], v[32:35]
	v_mfma_f32_16x16x32_bf16 v[24:27], v[180:183], v[196:199], v[24:27]
	v_mfma_f32_16x16x32_bf16 v[16:19], v[172:175], v[204:207], v[16:19]
	v_mfma_f32_16x16x32_bf16 v[8:11], v[180:183], v[204:207], v[8:11]
	v_mfma_f32_16x16x32_bf16 v[4:7], v[172:175], v[212:215], v[4:7]
	v_mfma_f32_16x16x32_bf16 v[0:3], v[180:183], v[212:215], v[0:3]
	s_setprio 0
	s_barrier
	s_add_i32 s62, s62, 2
	s_add_u32 s0, s0, 0x100
	s_addc_u32 s1, s1, 0
	s_add_u32 s60, s60, 0x100
	s_addc_u32 s61, s61, 0
	s_cmp_gt_u32 s62, 5
	s_cbranch_scc0 .LBB0_395
	s_and_b64 vcc, exec, s[14:15]
	s_cbranch_vccz .LBB0_398
	s_barrier

; #define PG8_STAGE(bufoff, gbase, voff) do { _Pragma("unroll") for (int _i = 0; _i < 2; ++_i) \
;         __builtin_amdgcn_global_load_lds((const unsigned*)((const char*)(gbase) + (voff)[_i]), (LAS unsigned*)(lds + (bufoff) + ldsw + _i * 8192), 16, 0, 0); } while (0)
; #define PG8_LDA(dst, b, h) do { _Pragma("unroll") for (int m = 0; m < 4; ++m) _Pragma("unroll") for (int k = 0; k < 2; ++k) dst[m][k] = *(const LAS bf16x8*)(lds + PG8_SA(b, h) + aoff + m * 2048 + k * 1024); } while (0)
; #define PG8_LDB(dst, b, h) do { _Pragma("unroll") for (int n = 0; n < 2; ++n) _Pragma("unroll") for (int k = 0; k < 2; ++k) dst[n][k] = *(const LAS bf16x8*)(lds + PG8_SB(b, h) + boff + n * 2048 + k * 1024); } while (0)
; #define PG8_WAIT_V(n) asm volatile("s_waitcnt vmcnt(" #n ")" ::: "memory")
; template <class Epi, class Sched, bool SP2 = PG8_SP2>
; __device__ __forceinline__ void gemm_phase(LAS unsigned char* lds, const Gemm g, const Sched& S, const Epi& E) {
;     ...
;         for (int t = 0; t < nt; t += 2) {
;             const bool last = (t == nt - 2);
;             const char* a1 = cA + (size_t)(t + 1) * kstep;
;             const char* a2 = last ? nA : cA + (size_t)(t + 2) * kstep; const char* b2 = last ? nB : cB + (size_t)(t + 2) * kstep;
;             const char* a3 = a2 + kstep; const char* b3 = b2 + kstep;
;             if constexpr (SP2) {
;             PG8_LDB(B0, 0, 0); PG8_LDB(B1, 0, 1); PG8_SCHED; PG8_LDA(At, 0, 0); PG8_STAGE(PG8_SA(1, 1), a1 + hstepA, voffA);
;             PG8_WAIT_V(8); PG8_WAIT_L(0); PG8_BAR; PG8_MMA(0, 0, At, B0); PG8_MMA(0, 1, At, B1); PG8_BAR; PG8_SCHED;
;             PG8_LDA(At, 0, 1); PG8_STAGE(PG8_SB(0, 0), b2, voffB); PG8_STAGE(PG8_SB(0, 1), b2 + hstepB, voffB); PG8_STAGE(PG8_SA(0, 0), a2, voffA);
;             PG8_WAIT_V(8); PG8_WAIT_L(0); PG8_BAR; PG8_MMA(1, 0, At, B0); PG8_MMA(1, 1, At, B1); PG8_BAR; PG8_SCHED;
;             PG8_LDB(B0, 1, 0); PG8_LDB(B1, 1, 1); PG8_SCHED; PG8_LDA(At, 1, 0); PG8_STAGE(PG8_SA(0, 1), a2 + hstepA, voffA);
;             PG8_WAIT_V(8); PG8_WAIT_L(0); PG8_BAR; PG8_MMA(0, 0, At, B0); PG8_MMA(0, 1, At, B1); PG8_BAR; PG8_SCHED;
;             PG8_LDA(At, 1, 1); PG8_STAGE(PG8_SB(1, 0), b3, voffB); PG8_STAGE(PG8_SB(1, 1), b3 + hstepB, voffB); PG8_STAGE(PG8_SA(1, 0), a3, voffA);
;             PG8_WAIT_V(8); PG8_WAIT_L(0); PG8_BAR; PG8_MMA(1, 0, At, B0); PG8_MMA(1, 1, At, B1); PG8_BAR; PG8_SCHED;
.LBB0_845:
	ds_read_b128 v[64:67], v167
	ds_read_b128 v[68:71], v167 offset:1024
	ds_read_b128 v[72:75], v167 offset:2048
	ds_read_b128 v[76:79], v167 offset:3072
	ds_read_b128 v[160:163], v168
	ds_read_b128 v[172:175], v168 offset:1024
	ds_read_b128 v[176:179], v168 offset:2048
	ds_read_b128 v[180:183], v168 offset:3072
	s_add_u32 s3, s0, 0xfff80080
	s_addc_u32 s40, s1, -1
	s_cmp_eq_u32 s60, 28
	s_cselect_b32 s43, s2, s40
	s_cselect_b32 s42, s29, s3
	s_cselect_b32 s41, s27, s59
	s_cselect_b32 s40, s57, s58
	s_add_i32 m0, s37, 0xc000
	ds_read_b128 v[184:187], v169
	ds_read_b128 v[188:191], v169 offset:1024
	ds_read_b128 v[192:195], v169 offset:2048
	ds_read_b128 v[196:199], v169 offset:3072
	ds_read_b128 v[200:203], v169 offset:4096
	ds_read_b128 v[204:207], v169 offset:5120
	ds_read_b128 v[208:211], v169 offset:6144
	ds_read_b128 v[212:215], v169 offset:7168
	global_load_lds_dwordx4 v152, s[0:1]
	s_add_i32 m0, s37, 0xe000
	s_nop 0
	global_load_lds_dwordx4 v154, s[0:1]
	s_waitcnt vmcnt(8)
	s_waitcnt lgkmcnt(0)
	s_barrier
	s_setprio 1
	s_waitcnt lgkmcnt(0)
	v_mfma_f32_16x16x32_bf16 v[140:143], v[64:67], v[184:187], v[140:143]
	v_mfma_f32_16x16x32_bf16 v[136:139], v[72:75], v[184:187], v[136:139]
	v_mfma_f32_16x16x32_bf16 v[124:127], v[64:67], v[192:195], v[124:127]
	v_mfma_f32_16x16x32_bf16 v[120:123], v[72:75], v[192:195], v[120:123]
	v_mfma_f32_16x16x32_bf16 v[108:111], v[64:67], v[200:203], v[108:111]
	v_mfma_f32_16x16x32_bf16 v[104:107], v[72:75], v[200:203], v[104:107]
	v_mfma_f32_16x16x32_bf16 v[92:95], v[64:67], v[208:211], v[92:95]
	v_mfma_f32_16x16x32_bf16 v[88:91], v[72:75], v[208:211], v[88:91]
	v_mfma_f32_16x16x32_bf16 v[140:143], v[68:71], v[188:191], v[140:143]
	v_mfma_f32_16x16x32_bf16 v[136:139], v[76:79], v[188:191], v[136:139]
	v_mfma_f32_16x16x32_bf16 v[124:127], v[68:71], v[196:199], v[124:127]
	v_mfma_f32_16x16x32_bf16 v[120:123], v[76:79], v[196:199], v[120:123]
	v_mfma_f32_16x16x32_bf16 v[108:111], v[68:71], v[204:207], v[108:111]
	v_mfma_f32_16x16x32_bf16 v[104:107], v[76:79], v[204:207], v[104:107]
	v_mfma_f32_16x16x32_bf16 v[92:95], v[68:71], v[212:215], v[92:95]
	v_mfma_f32_16x16x32_bf16 v[88:91], v[76:79], v[212:215], v[88:91]
	s_setprio 0
	s_setprio 1
	v_mfma_f32_16x16x32_bf16 v[132:135], v[160:163], v[184:187], v[132:135]
	v_mfma_f32_16x16x32_bf16 v[128:131], v[176:179], v[184:187], v[128:131]
	v_mfma_f32_16x16x32_bf16 v[116:119], v[160:163], v[192:195], v[116:119]
	v_mfma_f32_16x16x32_bf16 v[112:115], v[176:179], v[192:195], v[112:115]
	v_mfma_f32_16x16x32_bf16 v[100:103], v[160:163], v[200:203], v[100:103]
	v_mfma_f32_16x16x32_bf16 v[96:99], v[176:179], v[200:203], v[96:99]
	v_mfma_f32_16x16x32_bf16 v[84:87], v[160:163], v[208:211], v[84:87]
	v_mfma_f32_16x16x32_bf16 v[80:83], v[176:179], v[208:211], v[80:83]
	v_mfma_f32_16x16x32_bf16 v[132:135], v[172:175], v[188:191], v[132:135]
	v_mfma_f32_16x16x32_bf16 v[128:131], v[180:183], v[188:191], v[128:131]
	v_mfma_f32_16x16x32_bf16 v[116:119], v[172:175], v[196:199], v[116:119]
	v_mfma_f32_16x16x32_bf16 v[112:115], v[180:183], v[196:199], v[112:115]
	v_mfma_f32_16x16x32_bf16 v[100:103], v[172:175], v[204:207], v[100:103]
	v_mfma_f32_16x16x32_bf16 v[96:99], v[180:183], v[204:207], v[96:99]
	v_mfma_f32_16x16x32_bf16 v[84:87], v[172:175], v[212:215], v[84:87]
	v_mfma_f32_16x16x32_bf16 v[80:83], v[180:183], v[212:215], v[80:83]
	s_setprio 0
	s_barrier
	s_add_i32 s3, s55, s47
	s_add_u32 s98, s40, s22
	s_addc_u32 s99, s41, s23
	s_mov_b32 m0, s3
	ds_read_b128 v[184:187], v169 offset:16384
	ds_read_b128 v[188:191], v169 offset:17408
	ds_read_b128 v[192:195], v169 offset:18432
	ds_read_b128 v[196:199], v169 offset:19456
	ds_read_b128 v[200:203], v169 offset:20480
	ds_read_b128 v[204:207], v169 offset:21504
	ds_read_b128 v[208:211], v169 offset:22528
	ds_read_b128 v[212:215], v169 offset:23552
	global_load_lds_dwordx4 v146, s[40:41]
	s_add_i32 m0, s3, 0x2000
	s_add_u32 s62, s40, 0x80000
	s_addc_u32 s63, s41, 0
	s_add_i32 s3, s56, s47
	global_load_lds_dwordx4 v150, s[40:41]
	s_mov_b32 m0, s3
	s_nop 0
	global_load_lds_dwordx4 v146, s[62:63]
	s_add_i32 m0, s3, 0x2000
	s_nop 0
	global_load_lds_dwordx4 v150, s[62:63]
	s_add_u32 s100, s42, s22
	s_addc_u32 s101, s43, s23
	s_mov_b32 m0, s37
	s_nop 0
	global_load_lds_dwordx4 v144, s[42:43]
	s_mov_b32 m0, s39
	s_nop 0
	global_load_lds_dwordx4 v148, s[42:43]
	s_waitcnt vmcnt(8)
	s_waitcnt lgkmcnt(0)
	s_barrier
	s_setprio 1
	s_waitcnt lgkmcnt(0)
	v_mfma_f32_16x16x32_bf16 v[60:63], v[64:67], v[184:187], v[60:63]
	v_mfma_f32_16x16x32_bf16 v[56:59], v[72:75], v[184:187], v[56:59]
	v_mfma_f32_16x16x32_bf16 v[44:47], v[64:67], v[192:195], v[44:47]
	v_mfma_f32_16x16x32_bf16 v[40:43], v[72:75], v[192:195], v[40:43]
	v_mfma_f32_16x16x32_bf16 v[28:31], v[64:67], v[200:203], v[28:31]
	v_mfma_f32_16x16x32_bf16 v[24:27], v[72:75], v[200:203], v[24:27]
	v_mfma_f32_16x16x32_bf16 v[12:15], v[64:67], v[208:211], v[12:15]
	v_mfma_f32_16x16x32_bf16 v[8:11], v[72:75], v[208:211], v[8:11]
	v_mfma_f32_16x16x32_bf16 v[60:63], v[68:71], v[188:191], v[60:63]
	v_mfma_f32_16x16x32_bf16 v[56:59], v[76:79], v[188:191], v[56:59]
	v_mfma_f32_16x16x32_bf16 v[44:47], v[68:71], v[196:199], v[44:47]
	v_mfma_f32_16x16x32_bf16 v[40:43], v[76:79], v[196:199], v[40:43]
	v_mfma_f32_16x16x32_bf16 v[28:31], v[68:71], v[204:207], v[28:31]
	v_mfma_f32_16x16x32_bf16 v[24:27], v[76:79], v[204:207], v[24:27]
	v_mfma_f32_16x16x32_bf16 v[12:15], v[68:71], v[212:215], v[12:15]
	v_mfma_f32_16x16x32_bf16 v[8:11], v[76:79], v[212:215], v[8:11]
	s_setprio 0
	s_setprio 1
	v_mfma_f32_16x16x32_bf16 v[52:55], v[160:163], v[184:187], v[52:55]
	v_mfma_f32_16x16x32_bf16 v[48:51], v[176:179], v[184:187], v[48:51]
	v_mfma_f32_16x16x32_bf16 v[36:39], v[160:163], v[192:195], v[36:39]
	v_mfma_f32_16x16x32_bf16 v[32:35], v[176:179], v[192:195], v[32:35]
	v_mfma_f32_16x16x32_bf16 v[20:23], v[160:163], v[200:203], v[20:23]
	v_mfma_f32_16x16x32_bf16 v[16:19], v[176:179], v[200:203], v[16:19]
	v_mfma_f32_16x16x32_bf16 v[4:7], v[160:163], v[208:211], v[4:7]
	v_mfma_f32_16x16x32_bf16 v[0:3], v[176:179], v[208:211], v[0:3]
	v_mfma_f32_16x16x32_bf16 v[52:55], v[172:175], v[188:191], v[52:55]
	v_mfma_f32_16x16x32_bf16 v[48:51], v[180:183], v[188:191], v[48:51]
	v_mfma_f32_16x16x32_bf16 v[36:39], v[172:175], v[196:199], v[36:39]
	v_mfma_f32_16x16x32_bf16 v[32:35], v[180:183], v[196:199], v[32:35]
	v_mfma_f32_16x16x32_bf16 v[20:23], v[172:175], v[204:207], v[20:23]
	v_mfma_f32_16x16x32_bf16 v[16:19], v[180:183], v[204:207], v[16:19]
	v_mfma_f32_16x16x32_bf16 v[4:7], v[172:175], v[212:215], v[4:7]
	v_mfma_f32_16x16x32_bf16 v[0:3], v[180:183], v[212:215], v[0:3]
	s_setprio 0
	s_barrier
; #define PG8_STAGE(bufoff, gbase, voff) do { _Pragma("unroll") for (int _i = 0; _i < 2; ++_i) \
;         __builtin_amdgcn_global_load_lds((const unsigned*)((const char*)(gbase) + (voff)[_i]), (LAS unsigned*)(lds + (bufoff) + ldsw + _i * 8192), 16, 0, 0); } while (0)
; #define PG8_LDA(dst, b, h) do { _Pragma("unroll") for (int m = 0; m < 4; ++m) _Pragma("unroll") for (int k = 0; k < 2; ++k) dst[m][k] = *(const LAS bf16x8*)(lds + PG8_SA(b, h) + aoff + m * 2048 + k * 1024); } while (0)
; #define PG8_LDB(dst, b, h) do { _Pragma("unroll") for (int n = 0; n < 2; ++n) _Pragma("unroll") for (int k = 0; k < 2; ++k) dst[n][k] = *(const LAS bf16x8*)(lds + PG8_SB(b, h) + boff + n * 2048 + k * 1024); } while (0)
; #define PG8_WAIT_V(n) asm volatile("s_waitcnt vmcnt(" #n ")" ::: "memory")
; template <class Epi, class Sched, bool SP2 = PG8_SP2>
; __device__ __forceinline__ void gemm_phase(LAS unsigned char* lds, const Gemm g, const Sched& S, const Epi& E) {
;     ...
;         for (int t = 0; t < nt; t += 2) {
;             const bool last = (t == nt - 2);
;             const char* a1 = cA + (size_t)(t + 1) * kstep;
;             const char* a2 = last ? nA : cA + (size_t)(t + 2) * kstep; const char* b2 = last ? nB : cB + (size_t)(t + 2) * kstep;
;             const char* a3 = a2 + kstep; const char* b3 = b2 + kstep;
;             if constexpr (SP2) {
;             PG8_LDB(B0, 0, 0); PG8_LDB(B1, 0, 1); PG8_SCHED; PG8_LDA(At, 0, 0); PG8_STAGE(PG8_SA(1, 1), a1 + hstepA, voffA);
;             PG8_WAIT_V(8); PG8_WAIT_L(0); PG8_BAR; PG8_MMA(0, 0, At, B0); PG8_MMA(0, 1, At, B1); PG8_BAR; PG8_SCHED;
;             PG8_LDA(At, 0, 1); PG8_STAGE(PG8_SB(0, 0), b2, voffB); PG8_STAGE(PG8_SB(0, 1), b2 + hstepB, voffB); PG8_STAGE(PG8_SA(0, 0), a2, voffA);
;             PG8_WAIT_V(8); PG8_WAIT_L(0); PG8_BAR; PG8_MMA(1, 0, At, B0); PG8_MMA(1, 1, At, B1); PG8_BAR; PG8_SCHED;
;             PG8_LDB(B0, 1, 0); PG8_LDB(B1, 1, 1); PG8_SCHED; PG8_LDA(At, 1, 0); PG8_STAGE(PG8_SA(0, 1), a2 + hstepA, voffA);
;             PG8_WAIT_V(8); PG8_WAIT_L(0); PG8_BAR; PG8_MMA(0, 0, At, B0); PG8_MMA(0, 1, At, B1); PG8_BAR; PG8_SCHED;
;             PG8_LDA(At, 1, 1); PG8_STAGE(PG8_SB(1, 0), b3, voffB); PG8_STAGE(PG8_SB(1, 1), b3 + hstepB, voffB); PG8_STAGE(PG8_SA(1, 0), a3, voffA);
;             PG8_WAIT_V(8); PG8_WAIT_L(0); PG8_BAR; PG8_MMA(1, 0, At, B0); PG8_MMA(1, 1, At, B1); PG8_BAR; PG8_SCHED;
	s_add_i32 s3, 0, 0x18000
	s_add_i32 s61, 0, 0x1c000
	v_add_u32_e32 v76, s3, v165
	v_add_u32_e32 v171, s61, v165
	ds_read_b128 v[64:67], v76
	ds_read_b128 v[68:71], v76 offset:1024
	ds_read_b128 v[72:75], v76 offset:2048
	ds_read_b128 v[76:79], v76 offset:3072
	ds_read_b128 v[160:163], v171
	ds_read_b128 v[172:175], v171 offset:1024
	ds_read_b128 v[176:179], v171 offset:2048
	ds_read_b128 v[180:183], v171 offset:3072
	s_add_u32 s42, s42, 0x80000
	s_addc_u32 s43, s43, 0
	s_mov_b32 m0, s48
	ds_read_b128 v[184:187], v169 offset:32768
	ds_read_b128 v[188:191], v169 offset:33792
	ds_read_b128 v[192:195], v169 offset:34816
	ds_read_b128 v[196:199], v169 offset:35840
	ds_read_b128 v[200:203], v169 offset:36864
	ds_read_b128 v[204:207], v169 offset:37888
	ds_read_b128 v[208:211], v169 offset:38912
	ds_read_b128 v[212:215], v169 offset:39936
	global_load_lds_dwordx4 v144, s[42:43]
	s_mov_b32 m0, s49
	s_nop 0
	global_load_lds_dwordx4 v148, s[42:43]
	s_waitcnt vmcnt(8)
	s_waitcnt lgkmcnt(0)
	s_barrier
	s_setprio 1
	s_waitcnt lgkmcnt(0)
	v_mfma_f32_16x16x32_bf16 v[140:143], v[64:67], v[184:187], v[140:143]
	v_mfma_f32_16x16x32_bf16 v[136:139], v[72:75], v[184:187], v[136:139]
	v_mfma_f32_16x16x32_bf16 v[124:127], v[64:67], v[192:195], v[124:127]
	v_mfma_f32_16x16x32_bf16 v[120:123], v[72:75], v[192:195], v[120:123]
	v_mfma_f32_16x16x32_bf16 v[108:111], v[64:67], v[200:203], v[108:111]
	v_mfma_f32_16x16x32_bf16 v[104:107], v[72:75], v[200:203], v[104:107]
	v_mfma_f32_16x16x32_bf16 v[92:95], v[64:67], v[208:211], v[92:95]
	v_mfma_f32_16x16x32_bf16 v[88:91], v[72:75], v[208:211], v[88:91]
	v_mfma_f32_16x16x32_bf16 v[140:143], v[68:71], v[188:191], v[140:143]
	v_mfma_f32_16x16x32_bf16 v[136:139], v[76:79], v[188:191], v[136:139]
	v_mfma_f32_16x16x32_bf16 v[124:127], v[68:71], v[196:199], v[124:127]
	v_mfma_f32_16x16x32_bf16 v[120:123], v[76:79], v[196:199], v[120:123]
	v_mfma_f32_16x16x32_bf16 v[108:111], v[68:71], v[204:207], v[108:111]
	v_mfma_f32_16x16x32_bf16 v[104:107], v[76:79], v[204:207], v[104:107]
	v_mfma_f32_16x16x32_bf16 v[92:95], v[68:71], v[212:215], v[92:95]
	v_mfma_f32_16x16x32_bf16 v[88:91], v[76:79], v[212:215], v[88:91]
	s_setprio 0
	s_setprio 1
	v_mfma_f32_16x16x32_bf16 v[132:135], v[160:163], v[184:187], v[132:135]
	v_mfma_f32_16x16x32_bf16 v[128:131], v[176:179], v[184:187], v[128:131]
	v_mfma_f32_16x16x32_bf16 v[116:119], v[160:163], v[192:195], v[116:119]
	v_mfma_f32_16x16x32_bf16 v[112:115], v[176:179], v[192:195], v[112:115]
	v_mfma_f32_16x16x32_bf16 v[100:103], v[160:163], v[200:203], v[100:103]
	v_mfma_f32_16x16x32_bf16 v[96:99], v[176:179], v[200:203], v[96:99]
	v_mfma_f32_16x16x32_bf16 v[84:87], v[160:163], v[208:211], v[84:87]
	v_mfma_f32_16x16x32_bf16 v[80:83], v[176:179], v[208:211], v[80:83]
	v_mfma_f32_16x16x32_bf16 v[132:135], v[172:175], v[188:191], v[132:135]
	v_mfma_f32_16x16x32_bf16 v[128:131], v[180:183], v[188:191], v[128:131]
	v_mfma_f32_16x16x32_bf16 v[116:119], v[172:175], v[196:199], v[116:119]
	v_mfma_f32_16x16x32_bf16 v[112:115], v[180:183], v[196:199], v[112:115]
	v_mfma_f32_16x16x32_bf16 v[100:103], v[172:175], v[204:207], v[100:103]
	v_mfma_f32_16x16x32_bf16 v[96:99], v[180:183], v[204:207], v[96:99]
	v_mfma_f32_16x16x32_bf16 v[84:87], v[172:175], v[212:215], v[84:87]
	v_mfma_f32_16x16x32_bf16 v[80:83], v[180:183], v[212:215], v[80:83]
	s_setprio 0
	s_barrier
	s_add_i32 s3, s3, s47
	s_mov_b32 m0, s3
	ds_read_b128 v[184:187], v169 offset:49152
	ds_read_b128 v[188:191], v169 offset:50176
	ds_read_b128 v[192:195], v169 offset:51200
	ds_read_b128 v[196:199], v169 offset:52224
	ds_read_b128 v[200:203], v169 offset:53248
	ds_read_b128 v[204:207], v169 offset:54272
	ds_read_b128 v[208:211], v169 offset:55296
	ds_read_b128 v[212:215], v169 offset:56320
	global_load_lds_dwordx4 v146, s[98:99]
	s_add_i32 m0, s3, 0x2000
	s_add_u32 s40, s40, 0x80080
	s_addc_u32 s41, s41, 0
	s_add_i32 s3, s61, s47
	global_load_lds_dwordx4 v150, s[98:99]
	s_mov_b32 m0, s3
	s_nop 0
	global_load_lds_dwordx4 v146, s[40:41]
	s_add_i32 m0, s3, 0x2000
	s_nop 0
	global_load_lds_dwordx4 v150, s[40:41]
	s_mov_b32 m0, s51
	s_nop 0
	global_load_lds_dwordx4 v144, s[100:101]
	s_mov_b32 m0, s52
	s_nop 0
	global_load_lds_dwordx4 v148, s[100:101]
	s_waitcnt vmcnt(8)
	s_waitcnt lgkmcnt(0)
	s_barrier
	s_setprio 1
	s_waitcnt lgkmcnt(0)
	v_mfma_f32_16x16x32_bf16 v[60:63], v[64:67], v[184:187], v[60:63]
	v_mfma_f32_16x16x32_bf16 v[56:59], v[72:75], v[184:187], v[56:59]
	v_mfma_f32_16x16x32_bf16 v[44:47], v[64:67], v[192:195], v[44:47]
	v_mfma_f32_16x16x32_bf16 v[40:43], v[72:75], v[192:195], v[40:43]
	v_mfma_f32_16x16x32_bf16 v[28:31], v[64:67], v[200:203], v[28:31]
	v_mfma_f32_16x16x32_bf16 v[24:27], v[72:75], v[200:203], v[24:27]
	v_mfma_f32_16x16x32_bf16 v[12:15], v[64:67], v[208:211], v[12:15]
	v_mfma_f32_16x16x32_bf16 v[8:11], v[72:75], v[208:211], v[8:11]
	v_mfma_f32_16x16x32_bf16 v[60:63], v[68:71], v[188:191], v[60:63]
	v_mfma_f32_16x16x32_bf16 v[56:59], v[76:79], v[188:191], v[56:59]
	v_mfma_f32_16x16x32_bf16 v[44:47], v[68:71], v[196:199], v[44:47]
	v_mfma_f32_16x16x32_bf16 v[40:43], v[76:79], v[196:199], v[40:43]
	v_mfma_f32_16x16x32_bf16 v[28:31], v[68:71], v[204:207], v[28:31]
	v_mfma_f32_16x16x32_bf16 v[24:27], v[76:79], v[204:207], v[24:27]
	v_mfma_f32_16x16x32_bf16 v[12:15], v[68:71], v[212:215], v[12:15]
	v_mfma_f32_16x16x32_bf16 v[8:11], v[76:79], v[212:215], v[8:11]
	s_setprio 0
	s_setprio 1
	v_mfma_f32_16x16x32_bf16 v[52:55], v[160:163], v[184:187], v[52:55]
	v_mfma_f32_16x16x32_bf16 v[48:51], v[176:179], v[184:187], v[48:51]
	v_mfma_f32_16x16x32_bf16 v[36:39], v[160:163], v[192:195], v[36:39]
	v_mfma_f32_16x16x32_bf16 v[32:35], v[176:179], v[192:195], v[32:35]
	v_mfma_f32_16x16x32_bf16 v[20:23], v[160:163], v[200:203], v[20:23]
	v_mfma_f32_16x16x32_bf16 v[16:19], v[176:179], v[200:203], v[16:19]
	v_mfma_f32_16x16x32_bf16 v[4:7], v[160:163], v[208:211], v[4:7]
	v_mfma_f32_16x16x32_bf16 v[0:3], v[176:179], v[208:211], v[0:3]
	v_mfma_f32_16x16x32_bf16 v[52:55], v[172:175], v[188:191], v[52:55]
	v_mfma_f32_16x16x32_bf16 v[48:51], v[180:183], v[188:191], v[48:51]
	v_mfma_f32_16x16x32_bf16 v[36:39], v[172:175], v[196:199], v[36:39]
	v_mfma_f32_16x16x32_bf16 v[32:35], v[180:183], v[196:199], v[32:35]
	v_mfma_f32_16x16x32_bf16 v[20:23], v[172:175], v[204:207], v[20:23]
	v_mfma_f32_16x16x32_bf16 v[16:19], v[180:183], v[204:207], v[16:19]
	v_mfma_f32_16x16x32_bf16 v[4:7], v[172:175], v[212:215], v[4:7]
	v_mfma_f32_16x16x32_bf16 v[0:3], v[180:183], v[212:215], v[0:3]
	s_setprio 0
	s_barrier
	s_add_i32 s60, s60, 2
	s_add_u32 s0, s0, 0x100
	s_addc_u32 s1, s1, 0
	s_add_u32 s58, s58, 0x100
	s_addc_u32 s59, s59, 0
	s_cmp_gt_u32 s60, 29
	s_cbranch_scc0 .LBB0_845
	s_and_b64 vcc, exec, s[24:25]
	s_cbranch_vccz .LBB0_848
	s_barrier

; #define PG8_STAGE(bufoff, gbase, voff) do { _Pragma("unroll") for (int _i = 0; _i < 2; ++_i) \
;         __builtin_amdgcn_global_load_lds((const unsigned*)((const char*)(gbase) + (voff)[_i]), (LAS unsigned*)(lds + (bufoff) + ldsw + _i * 8192), 16, 0, 0); } while (0)
; #define PG8_LDA(dst, b, h) do { _Pragma("unroll") for (int m = 0; m < 4; ++m) _Pragma("unroll") for (int k = 0; k < 2; ++k) dst[m][k] = *(const LAS bf16x8*)(lds + PG8_SA(b, h) + aoff + m * 2048 + k * 1024); } while (0)
; #define PG8_LDB(dst, b, h) do { _Pragma("unroll") for (int n = 0; n < 2; ++n) _Pragma("unroll") for (int k = 0; k < 2; ++k) dst[n][k] = *(const LAS bf16x8*)(lds + PG8_SB(b, h) + boff + n * 2048 + k * 1024); } while (0)
; #define PG8_MMA(ai, bj, At, Bt) do { __builtin_amdgcn_s_setprio(1); _Pragma("unroll") for (int m = 0; m < 4; ++m) _Pragma("unroll") for (int n = 0; n < 2; ++n) _Pragma("unroll") for (int k = 0; k < 2; ++k) \
;         acc[ai][bj][m][n] = __builtin_amdgcn_mfma_f32_16x16x32_bf16(Bt[n][k], At[m][k], acc[ai][bj][m][n], 0, 0, 0); __builtin_amdgcn_s_setprio(0); } while (0)
; #define PG8_WAIT_V(n) asm volatile("s_waitcnt vmcnt(" #n ")" ::: "memory")
; #define PG8_WAIT_L(n) asm volatile("s_waitcnt lgkmcnt(" #n ")" ::: "memory")
; #define PG8_BAR __builtin_amdgcn_s_barrier()
; #define PG8_SCHED __builtin_amdgcn_sched_barrier(0)
; template <class Epi, class Sched, bool SP2 = PG8_SP2>
; __device__ __forceinline__ void gemm_phase(LAS unsigned char* lds, const Gemm g, const Sched& S, const Epi& E) {
;     ...
;             const bool last = (t == nt - 2);
;             const char* a1 = cA + (size_t)(t + 1) * kstep;
;             const char* a2 = last ? nA : cA + (size_t)(t + 2) * kstep; const char* b2 = last ? nB : cB + (size_t)(t + 2) * kstep;
;             const char* a3 = a2 + kstep; const char* b3 = b2 + kstep;
;             if constexpr (SP2) {
;             PG8_LDB(B0, 0, 0); PG8_LDB(B1, 0, 1); PG8_SCHED; PG8_LDA(At, 0, 0); PG8_STAGE(PG8_SA(1, 1), a1 + hstepA, voffA);
;             PG8_WAIT_V(8); PG8_WAIT_L(0); PG8_BAR; PG8_MMA(0, 0, At, B0); PG8_MMA(0, 1, At, B1); PG8_BAR; PG8_SCHED;
;             PG8_LDA(At, 0, 1); PG8_STAGE(PG8_SB(0, 0), b2, voffB); PG8_STAGE(PG8_SB(0, 1), b2 + hstepB, voffB); PG8_STAGE(PG8_SA(0, 0), a2, voffA);
;             PG8_WAIT_V(8); PG8_WAIT_L(0); PG8_BAR; PG8_MMA(1, 0, At, B0); PG8_MMA(1, 1, At, B1); PG8_BAR; PG8_SCHED;
.LBB0_932:
	ds_read_b128 v[144:147], v155
	ds_read_b128 v[148:151], v155 offset:1024
	ds_read_b128 v[160:163], v155 offset:2048
	ds_read_b128 v[164:167], v155 offset:3072
	ds_read_b128 v[168:171], v156
	ds_read_b128 v[172:175], v156 offset:1024
	ds_read_b128 v[176:179], v156 offset:2048
	ds_read_b128 v[180:183], v156 offset:3072
	s_add_u32 s3, s0, 0xfff80080
	s_addc_u32 s28, s1, -1
	s_cmp_eq_u32 s54, 28
	s_cselect_b32 s31, s2, s28
	s_cselect_b32 s30, s21, s3
	s_cselect_b32 s29, s19, s53
	s_cselect_b32 s28, s51, s52
	s_add_i32 m0, s27, 0xc000
	ds_read_b128 v[184:187], v157
	ds_read_b128 v[188:191], v157 offset:1024
	ds_read_b128 v[192:195], v157 offset:2048
	ds_read_b128 v[196:199], v157 offset:3072
	ds_read_b128 v[200:203], v157 offset:4096
	ds_read_b128 v[204:207], v157 offset:5120
	ds_read_b128 v[208:211], v157 offset:6144
	ds_read_b128 v[212:215], v157 offset:7168
	global_load_lds_dwordx4 v136, s[0:1]
	s_add_i32 m0, s27, 0xe000
	s_nop 0
	global_load_lds_dwordx4 v138, s[0:1]
	s_waitcnt vmcnt(8)
	s_waitcnt lgkmcnt(0)
	s_barrier
	s_setprio 1
	s_waitcnt lgkmcnt(0)
	v_mfma_f32_16x16x32_bf16 v[124:127], v[144:147], v[184:187], v[124:127]
	v_mfma_f32_16x16x32_bf16 v[120:123], v[160:163], v[184:187], v[120:123]
	v_mfma_f32_16x16x32_bf16 v[108:111], v[144:147], v[192:195], v[108:111]
	v_mfma_f32_16x16x32_bf16 v[104:107], v[160:163], v[192:195], v[104:107]
	v_mfma_f32_16x16x32_bf16 v[92:95], v[144:147], v[200:203], v[92:95]
	v_mfma_f32_16x16x32_bf16 v[88:91], v[160:163], v[200:203], v[88:91]
	v_mfma_f32_16x16x32_bf16 v[84:87], v[144:147], v[208:211], v[84:87]
	v_mfma_f32_16x16x32_bf16 v[76:79], v[160:163], v[208:211], v[76:79]
	v_mfma_f32_16x16x32_bf16 v[124:127], v[148:151], v[188:191], v[124:127]
	v_mfma_f32_16x16x32_bf16 v[120:123], v[164:167], v[188:191], v[120:123]
	v_mfma_f32_16x16x32_bf16 v[108:111], v[148:151], v[196:199], v[108:111]
	v_mfma_f32_16x16x32_bf16 v[104:107], v[164:167], v[196:199], v[104:107]
	v_mfma_f32_16x16x32_bf16 v[92:95], v[148:151], v[204:207], v[92:95]
	v_mfma_f32_16x16x32_bf16 v[88:91], v[164:167], v[204:207], v[88:91]
	v_mfma_f32_16x16x32_bf16 v[84:87], v[148:151], v[212:215], v[84:87]
	v_mfma_f32_16x16x32_bf16 v[76:79], v[164:167], v[212:215], v[76:79]
	s_setprio 0
	s_setprio 1
	v_mfma_f32_16x16x32_bf16 v[116:119], v[168:171], v[184:187], v[116:119]
	v_mfma_f32_16x16x32_bf16 v[112:115], v[176:179], v[184:187], v[112:115]
	v_mfma_f32_16x16x32_bf16 v[100:103], v[168:171], v[192:195], v[100:103]
	v_mfma_f32_16x16x32_bf16 v[96:99], v[176:179], v[192:195], v[96:99]
	v_mfma_f32_16x16x32_bf16 v[80:83], v[168:171], v[200:203], v[80:83]
	v_mfma_f32_16x16x32_bf16 v[72:75], v[176:179], v[200:203], v[72:75]
	v_mfma_f32_16x16x32_bf16 v[68:71], v[168:171], v[208:211], v[68:71]
	v_mfma_f32_16x16x32_bf16 v[64:67], v[176:179], v[208:211], v[64:67]
	v_mfma_f32_16x16x32_bf16 v[116:119], v[172:175], v[188:191], v[116:119]
	v_mfma_f32_16x16x32_bf16 v[112:115], v[180:183], v[188:191], v[112:115]
	v_mfma_f32_16x16x32_bf16 v[100:103], v[172:175], v[196:199], v[100:103]
	v_mfma_f32_16x16x32_bf16 v[96:99], v[180:183], v[196:199], v[96:99]
	v_mfma_f32_16x16x32_bf16 v[80:83], v[172:175], v[204:207], v[80:83]
	v_mfma_f32_16x16x32_bf16 v[72:75], v[180:183], v[204:207], v[72:75]
	v_mfma_f32_16x16x32_bf16 v[68:71], v[172:175], v[212:215], v[68:71]
	v_mfma_f32_16x16x32_bf16 v[64:67], v[180:183], v[212:215], v[64:67]
	s_setprio 0
	s_barrier
	s_add_i32 s3, s47, s37
	s_add_u32 s98, s28, s14
	s_addc_u32 s99, s29, s15
	s_mov_b32 m0, s3
	ds_read_b128 v[184:187], v157 offset:16384
	ds_read_b128 v[188:191], v157 offset:17408
	ds_read_b128 v[192:195], v157 offset:18432
	ds_read_b128 v[196:199], v157 offset:19456
	ds_read_b128 v[200:203], v157 offset:20480
	ds_read_b128 v[204:207], v157 offset:21504
	ds_read_b128 v[208:211], v157 offset:22528
	ds_read_b128 v[212:215], v157 offset:23552
	global_load_lds_dwordx4 v132, s[28:29]
	s_add_i32 m0, s3, 0x2000
	s_add_u32 s56, s28, 0x80000
	s_addc_u32 s57, s29, 0
	s_add_i32 s3, s48, s37
	global_load_lds_dwordx4 v128, s[28:29]
	s_mov_b32 m0, s3
	s_nop 0
	global_load_lds_dwordx4 v132, s[56:57]
	s_add_i32 m0, s3, 0x2000
	s_nop 0
	global_load_lds_dwordx4 v128, s[56:57]
	s_add_u32 s100, s30, s14
	s_addc_u32 s101, s31, s15
	s_mov_b32 m0, s27
	s_nop 0
	global_load_lds_dwordx4 v134, s[30:31]
	s_mov_b32 m0, s40
	s_nop 0
	global_load_lds_dwordx4 v130, s[30:31]
	s_waitcnt vmcnt(8)
	s_waitcnt lgkmcnt(0)
	s_barrier
	s_setprio 1
	s_waitcnt lgkmcnt(0)
	v_mfma_f32_16x16x32_bf16 v[60:63], v[144:147], v[184:187], v[60:63]
	v_mfma_f32_16x16x32_bf16 v[56:59], v[160:163], v[184:187], v[56:59]
	v_mfma_f32_16x16x32_bf16 v[44:47], v[144:147], v[192:195], v[44:47]
	v_mfma_f32_16x16x32_bf16 v[40:43], v[160:163], v[192:195], v[40:43]
	v_mfma_f32_16x16x32_bf16 v[28:31], v[144:147], v[200:203], v[28:31]
	v_mfma_f32_16x16x32_bf16 v[24:27], v[160:163], v[200:203], v[24:27]
	v_mfma_f32_16x16x32_bf16 v[12:15], v[144:147], v[208:211], v[12:15]
	v_mfma_f32_16x16x32_bf16 v[8:11], v[160:163], v[208:211], v[8:11]
	v_mfma_f32_16x16x32_bf16 v[60:63], v[148:151], v[188:191], v[60:63]
	v_mfma_f32_16x16x32_bf16 v[56:59], v[164:167], v[188:191], v[56:59]
	v_mfma_f32_16x16x32_bf16 v[44:47], v[148:151], v[196:199], v[44:47]
	v_mfma_f32_16x16x32_bf16 v[40:43], v[164:167], v[196:199], v[40:43]
	v_mfma_f32_16x16x32_bf16 v[28:31], v[148:151], v[204:207], v[28:31]
	v_mfma_f32_16x16x32_bf16 v[24:27], v[164:167], v[204:207], v[24:27]
	v_mfma_f32_16x16x32_bf16 v[12:15], v[148:151], v[212:215], v[12:15]
	v_mfma_f32_16x16x32_bf16 v[8:11], v[164:167], v[212:215], v[8:11]
	s_setprio 0
	s_setprio 1
	v_mfma_f32_16x16x32_bf16 v[52:55], v[168:171], v[184:187], v[52:55]
	v_mfma_f32_16x16x32_bf16 v[48:51], v[176:179], v[184:187], v[48:51]
	v_mfma_f32_16x16x32_bf16 v[36:39], v[168:171], v[192:195], v[36:39]
	v_mfma_f32_16x16x32_bf16 v[32:35], v[176:179], v[192:195], v[32:35]
	v_mfma_f32_16x16x32_bf16 v[20:23], v[168:171], v[200:203], v[20:23]
	v_mfma_f32_16x16x32_bf16 v[16:19], v[176:179], v[200:203], v[16:19]
	v_mfma_f32_16x16x32_bf16 v[4:7], v[168:171], v[208:211], v[4:7]
	v_mfma_f32_16x16x32_bf16 v[0:3], v[176:179], v[208:211], v[0:3]
	v_mfma_f32_16x16x32_bf16 v[52:55], v[172:175], v[188:191], v[52:55]
	v_mfma_f32_16x16x32_bf16 v[48:51], v[180:183], v[188:191], v[48:51]
	v_mfma_f32_16x16x32_bf16 v[36:39], v[172:175], v[196:199], v[36:39]
	v_mfma_f32_16x16x32_bf16 v[32:35], v[180:183], v[196:199], v[32:35]
	v_mfma_f32_16x16x32_bf16 v[20:23], v[172:175], v[204:207], v[20:23]
	v_mfma_f32_16x16x32_bf16 v[16:19], v[180:183], v[204:207], v[16:19]
	v_mfma_f32_16x16x32_bf16 v[4:7], v[172:175], v[212:215], v[4:7]
	v_mfma_f32_16x16x32_bf16 v[0:3], v[180:183], v[212:215], v[0:3]
	s_setprio 0
	s_barrier
; #define PG8_STAGE(bufoff, gbase, voff) do { _Pragma("unroll") for (int _i = 0; _i < 2; ++_i) \
;         __builtin_amdgcn_global_load_lds((const unsigned*)((const char*)(gbase) + (voff)[_i]), (LAS unsigned*)(lds + (bufoff) + ldsw + _i * 8192), 16, 0, 0); } while (0)
; #define PG8_LDA(dst, b, h) do { _Pragma("unroll") for (int m = 0; m < 4; ++m) _Pragma("unroll") for (int k = 0; k < 2; ++k) dst[m][k] = *(const LAS bf16x8*)(lds + PG8_SA(b, h) + aoff + m * 2048 + k * 1024); } while (0)
; #define PG8_LDB(dst, b, h) do { _Pragma("unroll") for (int n = 0; n < 2; ++n) _Pragma("unroll") for (int k = 0; k < 2; ++k) dst[n][k] = *(const LAS bf16x8*)(lds + PG8_SB(b, h) + boff + n * 2048 + k * 1024); } while (0)
; #define PG8_WAIT_V(n) asm volatile("s_waitcnt vmcnt(" #n ")" ::: "memory")
; template <class Epi, class Sched, bool SP2 = PG8_SP2>
; __device__ __forceinline__ void gemm_phase(LAS unsigned char* lds, const Gemm g, const Sched& S, const Epi& E) {
;     ...
;         for (int t = 0; t < nt; t += 2) {
;             const bool last = (t == nt - 2);
;             const char* a1 = cA + (size_t)(t + 1) * kstep;
;             const char* a2 = last ? nA : cA + (size_t)(t + 2) * kstep; const char* b2 = last ? nB : cB + (size_t)(t + 2) * kstep;
;             const char* a3 = a2 + kstep; const char* b3 = b2 + kstep;
;             if constexpr (SP2) {
;             PG8_LDB(B0, 0, 0); PG8_LDB(B1, 0, 1); PG8_SCHED; PG8_LDA(At, 0, 0); PG8_STAGE(PG8_SA(1, 1), a1 + hstepA, voffA);
;             PG8_WAIT_V(8); PG8_WAIT_L(0); PG8_BAR; PG8_MMA(0, 0, At, B0); PG8_MMA(0, 1, At, B1); PG8_BAR; PG8_SCHED;
;             PG8_LDA(At, 0, 1); PG8_STAGE(PG8_SB(0, 0), b2, voffB); PG8_STAGE(PG8_SB(0, 1), b2 + hstepB, voffB); PG8_STAGE(PG8_SA(0, 0), a2, voffA);
;             PG8_WAIT_V(8); PG8_WAIT_L(0); PG8_BAR; PG8_MMA(1, 0, At, B0); PG8_MMA(1, 1, At, B1); PG8_BAR; PG8_SCHED;
;             PG8_LDB(B0, 1, 0); PG8_LDB(B1, 1, 1); PG8_SCHED; PG8_LDA(At, 1, 0); PG8_STAGE(PG8_SA(0, 1), a2 + hstepA, voffA);
;             PG8_WAIT_V(8); PG8_WAIT_L(0); PG8_BAR; PG8_MMA(0, 0, At, B0); PG8_MMA(0, 1, At, B1); PG8_BAR; PG8_SCHED;
;             PG8_LDA(At, 1, 1); PG8_STAGE(PG8_SB(1, 0), b3, voffB); PG8_STAGE(PG8_SB(1, 1), b3 + hstepB, voffB); PG8_STAGE(PG8_SA(1, 0), a3, voffA);
;             PG8_WAIT_V(8); PG8_WAIT_L(0); PG8_BAR; PG8_MMA(1, 0, At, B0); PG8_MMA(1, 1, At, B1); PG8_BAR; PG8_SCHED;
	s_add_i32 s3, 0, 0x18000
	v_add_u32_e32 v159, s3, v153
	s_add_i32 s55, 0, 0x1c000
	ds_read_b128 v[144:147], v159
	ds_read_b128 v[148:151], v159 offset:1024
	ds_read_b128 v[160:163], v159 offset:2048
	ds_read_b128 v[164:167], v159 offset:3072
	v_add_u32_e32 v159, s55, v153
	ds_read_b128 v[168:171], v159
	ds_read_b128 v[172:175], v159 offset:1024
	ds_read_b128 v[176:179], v159 offset:2048
	ds_read_b128 v[180:183], v159 offset:3072
	s_add_u32 s30, s30, 0x80000
	s_addc_u32 s31, s31, 0
	s_mov_b32 m0, s41
	ds_read_b128 v[184:187], v157 offset:32768
	ds_read_b128 v[188:191], v157 offset:33792
	ds_read_b128 v[192:195], v157 offset:34816
	ds_read_b128 v[196:199], v157 offset:35840
	ds_read_b128 v[200:203], v157 offset:36864
	ds_read_b128 v[204:207], v157 offset:37888
	ds_read_b128 v[208:211], v157 offset:38912
	ds_read_b128 v[212:215], v157 offset:39936
	global_load_lds_dwordx4 v134, s[30:31]
	s_mov_b32 m0, s42
	s_nop 0
	global_load_lds_dwordx4 v130, s[30:31]
	s_waitcnt vmcnt(8)
	s_waitcnt lgkmcnt(0)
	s_barrier
	s_setprio 1
	s_waitcnt lgkmcnt(0)
	v_mfma_f32_16x16x32_bf16 v[124:127], v[144:147], v[184:187], v[124:127]
	v_mfma_f32_16x16x32_bf16 v[120:123], v[160:163], v[184:187], v[120:123]
	v_mfma_f32_16x16x32_bf16 v[108:111], v[144:147], v[192:195], v[108:111]
	v_mfma_f32_16x16x32_bf16 v[104:107], v[160:163], v[192:195], v[104:107]
	v_mfma_f32_16x16x32_bf16 v[92:95], v[144:147], v[200:203], v[92:95]
	v_mfma_f32_16x16x32_bf16 v[88:91], v[160:163], v[200:203], v[88:91]
	v_mfma_f32_16x16x32_bf16 v[84:87], v[144:147], v[208:211], v[84:87]
	v_mfma_f32_16x16x32_bf16 v[76:79], v[160:163], v[208:211], v[76:79]
	v_mfma_f32_16x16x32_bf16 v[124:127], v[148:151], v[188:191], v[124:127]
	v_mfma_f32_16x16x32_bf16 v[120:123], v[164:167], v[188:191], v[120:123]
	v_mfma_f32_16x16x32_bf16 v[108:111], v[148:151], v[196:199], v[108:111]
	v_mfma_f32_16x16x32_bf16 v[104:107], v[164:167], v[196:199], v[104:107]
	v_mfma_f32_16x16x32_bf16 v[92:95], v[148:151], v[204:207], v[92:95]
	v_mfma_f32_16x16x32_bf16 v[88:91], v[164:167], v[204:207], v[88:91]
	v_mfma_f32_16x16x32_bf16 v[84:87], v[148:151], v[212:215], v[84:87]
	v_mfma_f32_16x16x32_bf16 v[76:79], v[164:167], v[212:215], v[76:79]
	s_setprio 0
	s_setprio 1
	v_mfma_f32_16x16x32_bf16 v[116:119], v[168:171], v[184:187], v[116:119]
	v_mfma_f32_16x16x32_bf16 v[112:115], v[176:179], v[184:187], v[112:115]
	v_mfma_f32_16x16x32_bf16 v[100:103], v[168:171], v[192:195], v[100:103]
	v_mfma_f32_16x16x32_bf16 v[96:99], v[176:179], v[192:195], v[96:99]
	v_mfma_f32_16x16x32_bf16 v[80:83], v[168:171], v[200:203], v[80:83]
	v_mfma_f32_16x16x32_bf16 v[72:75], v[176:179], v[200:203], v[72:75]
	v_mfma_f32_16x16x32_bf16 v[68:71], v[168:171], v[208:211], v[68:71]
	v_mfma_f32_16x16x32_bf16 v[64:67], v[176:179], v[208:211], v[64:67]
	v_mfma_f32_16x16x32_bf16 v[116:119], v[172:175], v[188:191], v[116:119]
	v_mfma_f32_16x16x32_bf16 v[112:115], v[180:183], v[188:191], v[112:115]
	v_mfma_f32_16x16x32_bf16 v[100:103], v[172:175], v[196:199], v[100:103]
	v_mfma_f32_16x16x32_bf16 v[96:99], v[180:183], v[196:199], v[96:99]
	v_mfma_f32_16x16x32_bf16 v[80:83], v[172:175], v[204:207], v[80:83]
	v_mfma_f32_16x16x32_bf16 v[72:75], v[180:183], v[204:207], v[72:75]
	v_mfma_f32_16x16x32_bf16 v[68:71], v[172:175], v[212:215], v[68:71]
	v_mfma_f32_16x16x32_bf16 v[64:67], v[180:183], v[212:215], v[64:67]
	s_setprio 0
	s_barrier
	s_add_i32 s3, s3, s37
	s_mov_b32 m0, s3
	ds_read_b128 v[184:187], v157 offset:49152
	ds_read_b128 v[188:191], v157 offset:50176
	ds_read_b128 v[192:195], v157 offset:51200
	ds_read_b128 v[196:199], v157 offset:52224
	ds_read_b128 v[200:203], v157 offset:53248
	ds_read_b128 v[204:207], v157 offset:54272
	ds_read_b128 v[208:211], v157 offset:55296
	ds_read_b128 v[212:215], v157 offset:56320
	global_load_lds_dwordx4 v132, s[98:99]
	s_add_i32 m0, s3, 0x2000
	s_add_u32 s28, s28, 0x80080
	s_addc_u32 s29, s29, 0
	s_add_i32 s3, s55, s37
	global_load_lds_dwordx4 v128, s[98:99]
	s_mov_b32 m0, s3
	s_nop 0
	global_load_lds_dwordx4 v132, s[28:29]
	s_add_i32 m0, s3, 0x2000
	s_nop 0
	global_load_lds_dwordx4 v128, s[28:29]
	s_mov_b32 m0, s44
	s_nop 0
	global_load_lds_dwordx4 v134, s[100:101]
	s_mov_b32 m0, s45
	s_nop 0
	global_load_lds_dwordx4 v130, s[100:101]
	s_waitcnt vmcnt(8)
	s_waitcnt lgkmcnt(0)
	s_barrier
	s_setprio 1
	s_waitcnt lgkmcnt(0)
	v_mfma_f32_16x16x32_bf16 v[60:63], v[144:147], v[184:187], v[60:63]
	v_mfma_f32_16x16x32_bf16 v[56:59], v[160:163], v[184:187], v[56:59]
	v_mfma_f32_16x16x32_bf16 v[44:47], v[144:147], v[192:195], v[44:47]
	v_mfma_f32_16x16x32_bf16 v[40:43], v[160:163], v[192:195], v[40:43]
	v_mfma_f32_16x16x32_bf16 v[28:31], v[144:147], v[200:203], v[28:31]
	v_mfma_f32_16x16x32_bf16 v[24:27], v[160:163], v[200:203], v[24:27]
	v_mfma_f32_16x16x32_bf16 v[12:15], v[144:147], v[208:211], v[12:15]
	v_mfma_f32_16x16x32_bf16 v[8:11], v[160:163], v[208:211], v[8:11]
	v_mfma_f32_16x16x32_bf16 v[60:63], v[148:151], v[188:191], v[60:63]
	v_mfma_f32_16x16x32_bf16 v[56:59], v[164:167], v[188:191], v[56:59]
	v_mfma_f32_16x16x32_bf16 v[44:47], v[148:151], v[196:199], v[44:47]
	v_mfma_f32_16x16x32_bf16 v[40:43], v[164:167], v[196:199], v[40:43]
	v_mfma_f32_16x16x32_bf16 v[28:31], v[148:151], v[204:207], v[28:31]
	v_mfma_f32_16x16x32_bf16 v[24:27], v[164:167], v[204:207], v[24:27]
	v_mfma_f32_16x16x32_bf16 v[12:15], v[148:151], v[212:215], v[12:15]
	v_mfma_f32_16x16x32_bf16 v[8:11], v[164:167], v[212:215], v[8:11]
	s_setprio 0
	s_setprio 1
	v_mfma_f32_16x16x32_bf16 v[52:55], v[168:171], v[184:187], v[52:55]
	v_mfma_f32_16x16x32_bf16 v[48:51], v[176:179], v[184:187], v[48:51]
	v_mfma_f32_16x16x32_bf16 v[36:39], v[168:171], v[192:195], v[36:39]
	v_mfma_f32_16x16x32_bf16 v[32:35], v[176:179], v[192:195], v[32:35]
	v_mfma_f32_16x16x32_bf16 v[20:23], v[168:171], v[200:203], v[20:23]
	v_mfma_f32_16x16x32_bf16 v[16:19], v[176:179], v[200:203], v[16:19]
	v_mfma_f32_16x16x32_bf16 v[4:7], v[168:171], v[208:211], v[4:7]
	v_mfma_f32_16x16x32_bf16 v[0:3], v[176:179], v[208:211], v[0:3]
	v_mfma_f32_16x16x32_bf16 v[52:55], v[172:175], v[188:191], v[52:55]
	v_mfma_f32_16x16x32_bf16 v[48:51], v[180:183], v[188:191], v[48:51]
	v_mfma_f32_16x16x32_bf16 v[36:39], v[172:175], v[196:199], v[36:39]
	v_mfma_f32_16x16x32_bf16 v[32:35], v[180:183], v[196:199], v[32:35]
	v_mfma_f32_16x16x32_bf16 v[20:23], v[172:175], v[204:207], v[20:23]
	v_mfma_f32_16x16x32_bf16 v[16:19], v[180:183], v[204:207], v[16:19]
	v_mfma_f32_16x16x32_bf16 v[4:7], v[172:175], v[212:215], v[4:7]
	v_mfma_f32_16x16x32_bf16 v[0:3], v[180:183], v[212:215], v[0:3]
	s_setprio 0
	s_barrier
	s_add_i32 s54, s54, 2
	s_add_u32 s0, s0, 0x100
	s_addc_u32 s1, s1, 0
	s_add_u32 s52, s52, 0x100
	s_addc_u32 s53, s53, 0
	s_cmp_gt_u32 s54, 29
	s_cbranch_scc0 .LBB0_932
	s_and_b64 vcc, exec, s[16:17]
	s_cbranch_vccz .LBB0_935
	s_barrier

; #define PG8_STAGE(bufoff, gbase, voff) do { _Pragma("unroll") for (int _i = 0; _i < 2; ++_i) \
;         __builtin_amdgcn_global_load_lds((const unsigned*)((const char*)(gbase) + (voff)[_i]), (LAS unsigned*)(lds + (bufoff) + ldsw + _i * 8192), 16, 0, 0); } while (0)
; #define PG8_LDA(dst, b, h) do { _Pragma("unroll") for (int m = 0; m < 4; ++m) _Pragma("unroll") for (int k = 0; k < 2; ++k) dst[m][k] = *(const LAS bf16x8*)(lds + PG8_SA(b, h) + aoff + m * 2048 + k * 1024); } while (0)
; #define PG8_LDB(dst, b, h) do { _Pragma("unroll") for (int n = 0; n < 2; ++n) _Pragma("unroll") for (int k = 0; k < 2; ++k) dst[n][k] = *(const LAS bf16x8*)(lds + PG8_SB(b, h) + boff + n * 2048 + k * 1024); } while (0)
; #define PG8_MMA(ai, bj, At, Bt) do { __builtin_amdgcn_s_setprio(1); _Pragma("unroll") for (int m = 0; m < 4; ++m) _Pragma("unroll") for (int n = 0; n < 2; ++n) _Pragma("unroll") for (int k = 0; k < 2; ++k) \
;         acc[ai][bj][m][n] = __builtin_amdgcn_mfma_f32_16x16x32_bf16(Bt[n][k], At[m][k], acc[ai][bj][m][n], 0, 0, 0); __builtin_amdgcn_s_setprio(0); } while (0)
; #define PG8_WAIT_V(n) asm volatile("s_waitcnt vmcnt(" #n ")" ::: "memory")
; #define PG8_WAIT_L(n) asm volatile("s_waitcnt lgkmcnt(" #n ")" ::: "memory")
; #define PG8_BAR __builtin_amdgcn_s_barrier()
; #define PG8_SCHED __builtin_amdgcn_sched_barrier(0)
; template <class Epi, class Sched, bool SP2 = PG8_SP2>
; __device__ __forceinline__ void gemm_phase(LAS unsigned char* lds, const Gemm g, const Sched& S, const Epi& E) {
;     ...
;             const bool last = (t == nt - 2);
;             const char* a1 = cA + (size_t)(t + 1) * kstep;
;             const char* a2 = last ? nA : cA + (size_t)(t + 2) * kstep; const char* b2 = last ? nB : cB + (size_t)(t + 2) * kstep;
;             const char* a3 = a2 + kstep; const char* b3 = b2 + kstep;
;             if constexpr (SP2) {
;             PG8_LDB(B0, 0, 0); PG8_LDB(B1, 0, 1); PG8_SCHED; PG8_LDA(At, 0, 0); PG8_STAGE(PG8_SA(1, 1), a1 + hstepA, voffA);
;             PG8_WAIT_V(8); PG8_WAIT_L(0); PG8_BAR; PG8_MMA(0, 0, At, B0); PG8_MMA(0, 1, At, B1); PG8_BAR; PG8_SCHED;
;             PG8_LDA(At, 0, 1); PG8_STAGE(PG8_SB(0, 0), b2, voffB); PG8_STAGE(PG8_SB(0, 1), b2 + hstepB, voffB); PG8_STAGE(PG8_SA(0, 0), a2, voffA);
;             PG8_WAIT_V(8); PG8_WAIT_L(0); PG8_BAR; PG8_MMA(1, 0, At, B0); PG8_MMA(1, 1, At, B1); PG8_BAR; PG8_SCHED;
.LBB0_1003:
	ds_read_b128 v[96:99], v226
	ds_read_b128 v[100:103], v226 offset:1024
	ds_read_b128 v[104:107], v226 offset:2048
	ds_read_b128 v[108:111], v226 offset:3072
	ds_read_b128 v[112:115], v227
	ds_read_b128 v[116:119], v227 offset:1024
	ds_read_b128 v[154:157], v227 offset:2048
	ds_read_b128 v[158:161], v227 offset:3072
	s_add_u32 s3, s0, 0xfff80080
	s_addc_u32 s8, s1, -1
	s_cmp_eq_u32 s66, 28
	s_cselect_b32 s37, s2, s8
	s_cselect_b32 s36, s39, s3
	s_cselect_b32 s9, s35, s65
	s_cselect_b32 s8, s63, s64
	s_add_i32 m0, s50, 0xc000
	ds_read_b128 v[162:165], v228
	ds_read_b128 v[166:169], v228 offset:1024
	ds_read_b128 v[170:173], v228 offset:2048
	ds_read_b128 v[174:177], v228 offset:3072
	ds_read_b128 v[178:181], v228 offset:4096
	ds_read_b128 v[182:185], v228 offset:5120
	ds_read_b128 v[202:205], v228 offset:6144
	ds_read_b128 v[206:209], v228 offset:7168
	global_load_lds_dwordx4 v194, s[0:1]
	s_add_i32 m0, s50, 0xe000
	s_nop 0
	global_load_lds_dwordx4 v196, s[0:1]
	s_waitcnt vmcnt(8)
	s_waitcnt lgkmcnt(0)
	s_barrier
	s_setprio 1
	s_waitcnt lgkmcnt(0)
	v_mfma_f32_16x16x32_bf16 v[150:153], v[96:99], v[162:165], v[150:153]
	v_mfma_f32_16x16x32_bf16 v[146:149], v[104:107], v[162:165], v[146:149]
	v_mfma_f32_16x16x32_bf16 v[142:145], v[96:99], v[170:173], v[142:145]
	v_mfma_f32_16x16x32_bf16 v[138:141], v[104:107], v[170:173], v[138:141]
	v_mfma_f32_16x16x32_bf16 v[134:137], v[96:99], v[178:181], v[134:137]
	v_mfma_f32_16x16x32_bf16 v[130:133], v[104:107], v[178:181], v[130:133]
	v_mfma_f32_16x16x32_bf16 v[126:129], v[96:99], v[202:205], v[126:129]
	v_mfma_f32_16x16x32_bf16 v[120:123], v[104:107], v[202:205], v[122:125]
	v_mfma_f32_16x16x32_bf16 v[150:153], v[100:103], v[166:169], v[150:153]
	v_mfma_f32_16x16x32_bf16 v[146:149], v[108:111], v[166:169], v[146:149]
	v_mfma_f32_16x16x32_bf16 v[142:145], v[100:103], v[174:177], v[142:145]
	v_mfma_f32_16x16x32_bf16 v[138:141], v[108:111], v[174:177], v[138:141]
	v_mfma_f32_16x16x32_bf16 v[134:137], v[100:103], v[182:185], v[134:137]
	v_mfma_f32_16x16x32_bf16 v[130:133], v[108:111], v[182:185], v[130:133]
	v_mfma_f32_16x16x32_bf16 v[126:129], v[100:103], v[206:209], v[126:129]
	v_mfma_f32_16x16x32_bf16 v[120:123], v[108:111], v[206:209], v[120:123]
	s_setprio 0
	s_setprio 1
	v_mfma_f32_16x16x32_bf16 v[60:63], v[112:115], v[162:165], v[60:63]
	v_mfma_f32_16x16x32_bf16 v[56:59], v[154:157], v[162:165], v[56:59]
	v_mfma_f32_16x16x32_bf16 v[52:55], v[112:115], v[170:173], v[52:55]
	v_mfma_f32_16x16x32_bf16 v[48:51], v[154:157], v[170:173], v[48:51]
	v_mfma_f32_16x16x32_bf16 v[44:47], v[112:115], v[178:181], v[44:47]
	v_mfma_f32_16x16x32_bf16 v[40:43], v[154:157], v[178:181], v[40:43]
	v_mfma_f32_16x16x32_bf16 v[36:39], v[112:115], v[202:205], v[36:39]
	v_mfma_f32_16x16x32_bf16 v[32:35], v[154:157], v[202:205], v[32:35]
	v_mfma_f32_16x16x32_bf16 v[60:63], v[116:119], v[166:169], v[60:63]
	v_mfma_f32_16x16x32_bf16 v[56:59], v[158:161], v[166:169], v[56:59]
	v_mfma_f32_16x16x32_bf16 v[52:55], v[116:119], v[174:177], v[52:55]
	v_mfma_f32_16x16x32_bf16 v[48:51], v[158:161], v[174:177], v[48:51]
	v_mfma_f32_16x16x32_bf16 v[44:47], v[116:119], v[182:185], v[44:47]
	v_mfma_f32_16x16x32_bf16 v[40:43], v[158:161], v[182:185], v[40:43]
	v_mfma_f32_16x16x32_bf16 v[36:39], v[116:119], v[206:209], v[36:39]
	v_mfma_f32_16x16x32_bf16 v[32:35], v[158:161], v[206:209], v[32:35]
	s_setprio 0
	s_barrier
	s_add_i32 s3, s58, s47
	s_add_u32 s98, s8, s24
	s_addc_u32 s99, s9, s25
	s_mov_b32 m0, s3
	ds_read_b128 v[162:165], v228 offset:16384
	ds_read_b128 v[166:169], v228 offset:17408
	ds_read_b128 v[170:173], v228 offset:18432
	ds_read_b128 v[174:177], v228 offset:19456
	ds_read_b128 v[178:181], v228 offset:20480
	ds_read_b128 v[182:185], v228 offset:21504
	ds_read_b128 v[202:205], v228 offset:22528
	ds_read_b128 v[206:209], v228 offset:23552
	global_load_lds_dwordx4 v190, s[8:9]
	s_add_i32 m0, s3, 0x2000
	s_add_u32 s68, s8, 0x80000
	s_addc_u32 s69, s9, 0
	s_add_i32 s3, s59, s47
	global_load_lds_dwordx4 v186, s[8:9]
	s_mov_b32 m0, s3
	s_add_u32 s100, s36, s24
	s_addc_u32 s101, s37, s25
	global_load_lds_dwordx4 v190, s[68:69]
	s_add_i32 m0, s3, 0x2000
	s_nop 0
	global_load_lds_dwordx4 v186, s[68:69]
	s_mov_b32 m0, s50
	s_nop 0
	global_load_lds_dwordx4 v192, s[36:37]
	s_mov_b32 m0, s51
	s_nop 0
	global_load_lds_dwordx4 v188, s[36:37]
	s_waitcnt vmcnt(8)
	s_waitcnt lgkmcnt(0)
	s_barrier
	s_setprio 1
	s_waitcnt lgkmcnt(0)
	v_mfma_f32_16x16x32_bf16 v[92:95], v[96:99], v[162:165], v[92:95]
	v_mfma_f32_16x16x32_bf16 v[88:91], v[104:107], v[162:165], v[88:91]
	v_mfma_f32_16x16x32_bf16 v[84:87], v[96:99], v[170:173], v[84:87]
	v_mfma_f32_16x16x32_bf16 v[80:83], v[104:107], v[170:173], v[80:83]
	v_mfma_f32_16x16x32_bf16 v[76:79], v[96:99], v[178:181], v[76:79]
	v_mfma_f32_16x16x32_bf16 v[72:75], v[104:107], v[178:181], v[72:75]
	v_mfma_f32_16x16x32_bf16 v[68:71], v[96:99], v[202:205], v[68:71]
	v_mfma_f32_16x16x32_bf16 v[64:67], v[104:107], v[202:205], v[64:67]
	v_mfma_f32_16x16x32_bf16 v[92:95], v[100:103], v[166:169], v[92:95]
	v_mfma_f32_16x16x32_bf16 v[88:91], v[108:111], v[166:169], v[88:91]
	v_mfma_f32_16x16x32_bf16 v[84:87], v[100:103], v[174:177], v[84:87]
	v_mfma_f32_16x16x32_bf16 v[80:83], v[108:111], v[174:177], v[80:83]
	v_mfma_f32_16x16x32_bf16 v[76:79], v[100:103], v[182:185], v[76:79]
	v_mfma_f32_16x16x32_bf16 v[72:75], v[108:111], v[182:185], v[72:75]
	v_mfma_f32_16x16x32_bf16 v[68:71], v[100:103], v[206:209], v[68:71]
	v_mfma_f32_16x16x32_bf16 v[64:67], v[108:111], v[206:209], v[64:67]
	s_setprio 0
	s_setprio 1
	v_mfma_f32_16x16x32_bf16 v[28:31], v[112:115], v[162:165], v[28:31]
	v_mfma_f32_16x16x32_bf16 v[24:27], v[154:157], v[162:165], v[24:27]
	v_mfma_f32_16x16x32_bf16 v[20:23], v[112:115], v[170:173], v[20:23]
	v_mfma_f32_16x16x32_bf16 v[16:19], v[154:157], v[170:173], v[16:19]
	v_mfma_f32_16x16x32_bf16 v[12:15], v[112:115], v[178:181], v[12:15]
	v_mfma_f32_16x16x32_bf16 v[8:11], v[154:157], v[178:181], v[8:11]
	v_mfma_f32_16x16x32_bf16 v[4:7], v[112:115], v[202:205], v[4:7]
	v_mfma_f32_16x16x32_bf16 v[0:3], v[154:157], v[202:205], v[0:3]
	v_mfma_f32_16x16x32_bf16 v[28:31], v[116:119], v[166:169], v[28:31]
	v_mfma_f32_16x16x32_bf16 v[24:27], v[158:161], v[166:169], v[24:27]
	v_mfma_f32_16x16x32_bf16 v[20:23], v[116:119], v[174:177], v[20:23]
	v_mfma_f32_16x16x32_bf16 v[16:19], v[158:161], v[174:177], v[16:19]
	v_mfma_f32_16x16x32_bf16 v[12:15], v[116:119], v[182:185], v[12:15]
	v_mfma_f32_16x16x32_bf16 v[8:11], v[158:161], v[182:185], v[8:11]
	v_mfma_f32_16x16x32_bf16 v[4:7], v[116:119], v[206:209], v[4:7]
	v_mfma_f32_16x16x32_bf16 v[0:3], v[158:161], v[206:209], v[0:3]
	s_setprio 0
	s_barrier
; #define PG8_STAGE(bufoff, gbase, voff) do { _Pragma("unroll") for (int _i = 0; _i < 2; ++_i) \
;         __builtin_amdgcn_global_load_lds((const unsigned*)((const char*)(gbase) + (voff)[_i]), (LAS unsigned*)(lds + (bufoff) + ldsw + _i * 8192), 16, 0, 0); } while (0)
; #define PG8_LDA(dst, b, h) do { _Pragma("unroll") for (int m = 0; m < 4; ++m) _Pragma("unroll") for (int k = 0; k < 2; ++k) dst[m][k] = *(const LAS bf16x8*)(lds + PG8_SA(b, h) + aoff + m * 2048 + k * 1024); } while (0)
; #define PG8_LDB(dst, b, h) do { _Pragma("unroll") for (int n = 0; n < 2; ++n) _Pragma("unroll") for (int k = 0; k < 2; ++k) dst[n][k] = *(const LAS bf16x8*)(lds + PG8_SB(b, h) + boff + n * 2048 + k * 1024); } while (0)
; #define PG8_WAIT_V(n) asm volatile("s_waitcnt vmcnt(" #n ")" ::: "memory")
; template <class Epi, class Sched, bool SP2 = PG8_SP2>
; __device__ __forceinline__ void gemm_phase(LAS unsigned char* lds, const Gemm g, const Sched& S, const Epi& E) {
;     ...
;         for (int t = 0; t < nt; t += 2) {
;             const bool last = (t == nt - 2);
;             const char* a1 = cA + (size_t)(t + 1) * kstep;
;             const char* a2 = last ? nA : cA + (size_t)(t + 2) * kstep; const char* b2 = last ? nB : cB + (size_t)(t + 2) * kstep;
;             const char* a3 = a2 + kstep; const char* b3 = b2 + kstep;
;             if constexpr (SP2) {
;             PG8_LDB(B0, 0, 0); PG8_LDB(B1, 0, 1); PG8_SCHED; PG8_LDA(At, 0, 0); PG8_STAGE(PG8_SA(1, 1), a1 + hstepA, voffA);
;             PG8_WAIT_V(8); PG8_WAIT_L(0); PG8_BAR; PG8_MMA(0, 0, At, B0); PG8_MMA(0, 1, At, B1); PG8_BAR; PG8_SCHED;
;             PG8_LDA(At, 0, 1); PG8_STAGE(PG8_SB(0, 0), b2, voffB); PG8_STAGE(PG8_SB(0, 1), b2 + hstepB, voffB); PG8_STAGE(PG8_SA(0, 0), a2, voffA);
;             PG8_WAIT_V(8); PG8_WAIT_L(0); PG8_BAR; PG8_MMA(1, 0, At, B0); PG8_MMA(1, 1, At, B1); PG8_BAR; PG8_SCHED;
;             PG8_LDB(B0, 1, 0); PG8_LDB(B1, 1, 1); PG8_SCHED; PG8_LDA(At, 1, 0); PG8_STAGE(PG8_SA(0, 1), a2 + hstepA, voffA);
;             PG8_WAIT_V(8); PG8_WAIT_L(0); PG8_BAR; PG8_MMA(0, 0, At, B0); PG8_MMA(0, 1, At, B1); PG8_BAR; PG8_SCHED;
;             PG8_LDA(At, 1, 1); PG8_STAGE(PG8_SB(1, 0), b3, voffB); PG8_STAGE(PG8_SB(1, 1), b3 + hstepB, voffB); PG8_STAGE(PG8_SA(1, 0), a3, voffA);
;             PG8_WAIT_V(8); PG8_WAIT_L(0); PG8_BAR; PG8_MMA(1, 0, At, B0); PG8_MMA(1, 1, At, B1); PG8_BAR; PG8_SCHED;
	s_add_i32 s3, 0, 0x18000
	s_add_i32 s67, 0, 0x1c000
	v_add_u32_e32 v108, s3, v224
	v_add_u32_e32 v124, s67, v224
	ds_read_b128 v[96:99], v108
	ds_read_b128 v[100:103], v108 offset:1024
	ds_read_b128 v[104:107], v108 offset:2048
	ds_read_b128 v[108:111], v108 offset:3072
	ds_read_b128 v[112:115], v124
	ds_read_b128 v[116:119], v124 offset:1024
	ds_read_b128 v[154:157], v124 offset:2048
	ds_read_b128 v[158:161], v124 offset:3072
	s_add_u32 s36, s36, 0x80000
	s_addc_u32 s37, s37, 0
	s_mov_b32 m0, s52
	ds_read_b128 v[162:165], v228 offset:32768
	ds_read_b128 v[166:169], v228 offset:33792
	ds_read_b128 v[170:173], v228 offset:34816
	ds_read_b128 v[174:177], v228 offset:35840
	ds_read_b128 v[178:181], v228 offset:36864
	ds_read_b128 v[182:185], v228 offset:37888
	ds_read_b128 v[202:205], v228 offset:38912
	ds_read_b128 v[206:209], v228 offset:39936
	global_load_lds_dwordx4 v192, s[36:37]
	s_mov_b32 m0, s53
	s_nop 0
	global_load_lds_dwordx4 v188, s[36:37]
	s_waitcnt vmcnt(8)
	s_waitcnt lgkmcnt(0)
	s_barrier
	s_setprio 1
	s_waitcnt lgkmcnt(0)
	v_mfma_f32_16x16x32_bf16 v[150:153], v[96:99], v[162:165], v[150:153]
	v_mfma_f32_16x16x32_bf16 v[146:149], v[104:107], v[162:165], v[146:149]
	v_mfma_f32_16x16x32_bf16 v[142:145], v[96:99], v[170:173], v[142:145]
	v_mfma_f32_16x16x32_bf16 v[138:141], v[104:107], v[170:173], v[138:141]
	v_mfma_f32_16x16x32_bf16 v[134:137], v[96:99], v[178:181], v[134:137]
	v_mfma_f32_16x16x32_bf16 v[130:133], v[104:107], v[178:181], v[130:133]
	v_mfma_f32_16x16x32_bf16 v[124:127], v[96:99], v[202:205], v[126:129]
	v_mfma_f32_16x16x32_bf16 v[120:123], v[104:107], v[202:205], v[120:123]
	v_mfma_f32_16x16x32_bf16 v[150:153], v[100:103], v[166:169], v[150:153]
	v_mfma_f32_16x16x32_bf16 v[146:149], v[108:111], v[166:169], v[146:149]
	v_mfma_f32_16x16x32_bf16 v[142:145], v[100:103], v[174:177], v[142:145]
	v_mfma_f32_16x16x32_bf16 v[138:141], v[108:111], v[174:177], v[138:141]
	v_mfma_f32_16x16x32_bf16 v[134:137], v[100:103], v[182:185], v[134:137]
	v_mfma_f32_16x16x32_bf16 v[130:133], v[108:111], v[182:185], v[130:133]
	v_mfma_f32_16x16x32_bf16 v[126:129], v[100:103], v[206:209], v[124:127]
	v_mfma_f32_16x16x32_bf16 v[122:125], v[108:111], v[206:209], v[120:123]
	s_setprio 0
	s_setprio 1
	v_mfma_f32_16x16x32_bf16 v[60:63], v[112:115], v[162:165], v[60:63]
	v_mfma_f32_16x16x32_bf16 v[56:59], v[154:157], v[162:165], v[56:59]
	v_mfma_f32_16x16x32_bf16 v[52:55], v[112:115], v[170:173], v[52:55]
	v_mfma_f32_16x16x32_bf16 v[48:51], v[154:157], v[170:173], v[48:51]
	v_mfma_f32_16x16x32_bf16 v[44:47], v[112:115], v[178:181], v[44:47]
	v_mfma_f32_16x16x32_bf16 v[40:43], v[154:157], v[178:181], v[40:43]
	v_mfma_f32_16x16x32_bf16 v[36:39], v[112:115], v[202:205], v[36:39]
	v_mfma_f32_16x16x32_bf16 v[32:35], v[154:157], v[202:205], v[32:35]
	v_mfma_f32_16x16x32_bf16 v[60:63], v[116:119], v[166:169], v[60:63]
	v_mfma_f32_16x16x32_bf16 v[56:59], v[158:161], v[166:169], v[56:59]
	v_mfma_f32_16x16x32_bf16 v[52:55], v[116:119], v[174:177], v[52:55]
	v_mfma_f32_16x16x32_bf16 v[48:51], v[158:161], v[174:177], v[48:51]
	v_mfma_f32_16x16x32_bf16 v[44:47], v[116:119], v[182:185], v[44:47]
	v_mfma_f32_16x16x32_bf16 v[40:43], v[158:161], v[182:185], v[40:43]
	v_mfma_f32_16x16x32_bf16 v[36:39], v[116:119], v[206:209], v[36:39]
	v_mfma_f32_16x16x32_bf16 v[32:35], v[158:161], v[206:209], v[32:35]
	s_setprio 0
	s_barrier
	s_add_i32 s3, s3, s47
	s_mov_b32 m0, s3
	ds_read_b128 v[162:165], v228 offset:49152
	ds_read_b128 v[166:169], v228 offset:50176
	ds_read_b128 v[170:173], v228 offset:51200
	ds_read_b128 v[174:177], v228 offset:52224
	ds_read_b128 v[178:181], v228 offset:53248
	ds_read_b128 v[182:185], v228 offset:54272
	ds_read_b128 v[202:205], v228 offset:55296
	ds_read_b128 v[206:209], v228 offset:56320
	global_load_lds_dwordx4 v190, s[98:99]
	s_add_i32 m0, s3, 0x2000
	s_add_u32 s8, s8, 0x80080
	s_addc_u32 s9, s9, 0
	s_add_i32 s3, s67, s47
	global_load_lds_dwordx4 v186, s[98:99]
	s_mov_b32 m0, s3
	s_nop 0
	global_load_lds_dwordx4 v190, s[8:9]
	s_add_i32 m0, s3, 0x2000
	s_nop 0
	global_load_lds_dwordx4 v186, s[8:9]
	s_mov_b32 m0, s55
	s_nop 0
	global_load_lds_dwordx4 v192, s[100:101]
	s_mov_b32 m0, s56
	s_nop 0
	global_load_lds_dwordx4 v188, s[100:101]
	s_waitcnt vmcnt(8)
	s_waitcnt lgkmcnt(0)
	s_barrier
	s_setprio 1
	s_waitcnt lgkmcnt(0)
	v_mfma_f32_16x16x32_bf16 v[92:95], v[96:99], v[162:165], v[92:95]
	v_mfma_f32_16x16x32_bf16 v[88:91], v[104:107], v[162:165], v[88:91]
	v_mfma_f32_16x16x32_bf16 v[84:87], v[96:99], v[170:173], v[84:87]
	v_mfma_f32_16x16x32_bf16 v[80:83], v[104:107], v[170:173], v[80:83]
	v_mfma_f32_16x16x32_bf16 v[76:79], v[96:99], v[178:181], v[76:79]
	v_mfma_f32_16x16x32_bf16 v[72:75], v[104:107], v[178:181], v[72:75]
	v_mfma_f32_16x16x32_bf16 v[68:71], v[96:99], v[202:205], v[68:71]
	v_mfma_f32_16x16x32_bf16 v[64:67], v[104:107], v[202:205], v[64:67]
	v_mfma_f32_16x16x32_bf16 v[92:95], v[100:103], v[166:169], v[92:95]
	v_mfma_f32_16x16x32_bf16 v[88:91], v[108:111], v[166:169], v[88:91]
	v_mfma_f32_16x16x32_bf16 v[84:87], v[100:103], v[174:177], v[84:87]
	v_mfma_f32_16x16x32_bf16 v[80:83], v[108:111], v[174:177], v[80:83]
	v_mfma_f32_16x16x32_bf16 v[76:79], v[100:103], v[182:185], v[76:79]
	v_mfma_f32_16x16x32_bf16 v[72:75], v[108:111], v[182:185], v[72:75]
	v_mfma_f32_16x16x32_bf16 v[68:71], v[100:103], v[206:209], v[68:71]
	v_mfma_f32_16x16x32_bf16 v[64:67], v[108:111], v[206:209], v[64:67]
	s_setprio 0
	s_setprio 1
	v_mfma_f32_16x16x32_bf16 v[28:31], v[112:115], v[162:165], v[28:31]
	v_mfma_f32_16x16x32_bf16 v[24:27], v[154:157], v[162:165], v[24:27]
	v_mfma_f32_16x16x32_bf16 v[20:23], v[112:115], v[170:173], v[20:23]
	v_mfma_f32_16x16x32_bf16 v[16:19], v[154:157], v[170:173], v[16:19]
	v_mfma_f32_16x16x32_bf16 v[12:15], v[112:115], v[178:181], v[12:15]
	v_mfma_f32_16x16x32_bf16 v[8:11], v[154:157], v[178:181], v[8:11]
	v_mfma_f32_16x16x32_bf16 v[4:7], v[112:115], v[202:205], v[4:7]
	v_mfma_f32_16x16x32_bf16 v[0:3], v[154:157], v[202:205], v[0:3]
	v_mfma_f32_16x16x32_bf16 v[28:31], v[116:119], v[166:169], v[28:31]
	v_mfma_f32_16x16x32_bf16 v[24:27], v[158:161], v[166:169], v[24:27]
	v_mfma_f32_16x16x32_bf16 v[20:23], v[116:119], v[174:177], v[20:23]
	v_mfma_f32_16x16x32_bf16 v[16:19], v[158:161], v[174:177], v[16:19]
	v_mfma_f32_16x16x32_bf16 v[12:15], v[116:119], v[182:185], v[12:15]
	v_mfma_f32_16x16x32_bf16 v[8:11], v[158:161], v[182:185], v[8:11]
	v_mfma_f32_16x16x32_bf16 v[4:7], v[116:119], v[206:209], v[4:7]
	v_mfma_f32_16x16x32_bf16 v[0:3], v[158:161], v[206:209], v[0:3]
	s_setprio 0
	s_barrier
	s_add_i32 s66, s66, 2
	s_add_u32 s0, s0, 0x100
	s_addc_u32 s1, s1, 0
	s_add_u32 s64, s64, 0x100
	s_addc_u32 s65, s65, 0
	s_cmp_gt_u32 s66, 29
	s_cbranch_scc0 .LBB0_1003
	s_and_b64 vcc, exec, s[26:27]
	s_cbranch_vccz .LBB0_1006
	s_barrier

; #define PG8_STAGE(bufoff, gbase, voff) do { _Pragma("unroll") for (int _i = 0; _i < 2; ++_i) \
;         __builtin_amdgcn_global_load_lds((const unsigned*)((const char*)(gbase) + (voff)[_i]), (LAS unsigned*)(lds + (bufoff) + ldsw + _i * 8192), 16, 0, 0); } while (0)
; #define PG8_LDA(dst, b, h) do { _Pragma("unroll") for (int m = 0; m < 4; ++m) _Pragma("unroll") for (int k = 0; k < 2; ++k) dst[m][k] = *(const LAS bf16x8*)(lds + PG8_SA(b, h) + aoff + m * 2048 + k * 1024); } while (0)
; #define PG8_LDB(dst, b, h) do { _Pragma("unroll") for (int n = 0; n < 2; ++n) _Pragma("unroll") for (int k = 0; k < 2; ++k) dst[n][k] = *(const LAS bf16x8*)(lds + PG8_SB(b, h) + boff + n * 2048 + k * 1024); } while (0)
; #define PG8_MMA(ai, bj, At, Bt) do { __builtin_amdgcn_s_setprio(1); _Pragma("unroll") for (int m = 0; m < 4; ++m) _Pragma("unroll") for (int n = 0; n < 2; ++n) _Pragma("unroll") for (int k = 0; k < 2; ++k) \
;         acc[ai][bj][m][n] = __builtin_amdgcn_mfma_f32_16x16x32_bf16(Bt[n][k], At[m][k], acc[ai][bj][m][n], 0, 0, 0); __builtin_amdgcn_s_setprio(0); } while (0)
; #define PG8_WAIT_V(n) asm volatile("s_waitcnt vmcnt(" #n ")" ::: "memory")
; #define PG8_WAIT_L(n) asm volatile("s_waitcnt lgkmcnt(" #n ")" ::: "memory")
; #define PG8_BAR __builtin_amdgcn_s_barrier()
; #define PG8_SCHED __builtin_amdgcn_sched_barrier(0)
; template <class Epi, class Sched, bool SP2 = PG8_SP2>
; __device__ __forceinline__ void gemm_phase(LAS unsigned char* lds, const Gemm g, const Sched& S, const Epi& E) {
;     ...
;             const bool last = (t == nt - 2);
;             const char* a1 = cA + (size_t)(t + 1) * kstep;
;             const char* a2 = last ? nA : cA + (size_t)(t + 2) * kstep; const char* b2 = last ? nB : cB + (size_t)(t + 2) * kstep;
;             const char* a3 = a2 + kstep; const char* b3 = b2 + kstep;
;             if constexpr (SP2) {
;             PG8_LDB(B0, 0, 0); PG8_LDB(B1, 0, 1); PG8_SCHED; PG8_LDA(At, 0, 0); PG8_STAGE(PG8_SA(1, 1), a1 + hstepA, voffA);
;             PG8_WAIT_V(8); PG8_WAIT_L(0); PG8_BAR; PG8_MMA(0, 0, At, B0); PG8_MMA(0, 1, At, B1); PG8_BAR; PG8_SCHED;
;             PG8_LDA(At, 0, 1); PG8_STAGE(PG8_SB(0, 0), b2, voffB); PG8_STAGE(PG8_SB(0, 1), b2 + hstepB, voffB); PG8_STAGE(PG8_SA(0, 0), a2, voffA);
;             PG8_WAIT_V(8); PG8_WAIT_L(0); PG8_BAR; PG8_MMA(1, 0, At, B0); PG8_MMA(1, 1, At, B1); PG8_BAR; PG8_SCHED;
.LBB0_1090:
	ds_read_b128 v[148:151], v145
	ds_read_b128 v[152:155], v145 offset:1024
	ds_read_b128 v[156:159], v145 offset:2048
	ds_read_b128 v[160:163], v145 offset:3072
	ds_read_b128 v[164:167], v146
	ds_read_b128 v[168:171], v146 offset:1024
	ds_read_b128 v[172:175], v146 offset:2048
	ds_read_b128 v[176:179], v146 offset:3072
	s_add_u32 s3, s24, 0xffea0080
	s_addc_u32 s26, s25, -1
	s_cmpk_eq_i32 s56, 0x54
	s_cselect_b32 s29, s5, s26
	s_cselect_b32 s28, s4, s3
	s_cselect_b32 s27, s23, s55
	s_cselect_b32 s26, s22, s2
	s_add_i32 m0, s37, 0xc000
	ds_read_b128 v[180:183], v147
	ds_read_b128 v[184:187], v147 offset:1024
	ds_read_b128 v[188:191], v147 offset:2048
	ds_read_b128 v[192:195], v147 offset:3072
	ds_read_b128 v[196:199], v147 offset:4096
	ds_read_b128 v[200:203], v147 offset:5120
	ds_read_b128 v[204:207], v147 offset:6144
	ds_read_b128 v[208:211], v147 offset:7168
	global_load_lds_dwordx4 v132, s[24:25]
	s_add_i32 m0, s37, 0xe000
	s_nop 0
	global_load_lds_dwordx4 v134, s[24:25]
	s_waitcnt vmcnt(8)
	s_waitcnt lgkmcnt(0)
	s_barrier
	s_setprio 1
	s_waitcnt lgkmcnt(0)
	v_mfma_f32_16x16x32_bf16 v[124:127], v[148:151], v[180:183], v[124:127]
	v_mfma_f32_16x16x32_bf16 v[120:123], v[156:159], v[180:183], v[120:123]
	v_mfma_f32_16x16x32_bf16 v[116:119], v[148:151], v[188:191], v[116:119]
	v_mfma_f32_16x16x32_bf16 v[112:115], v[156:159], v[188:191], v[112:115]
	v_mfma_f32_16x16x32_bf16 v[92:95], v[148:151], v[196:199], v[92:95]
	v_mfma_f32_16x16x32_bf16 v[88:91], v[156:159], v[196:199], v[88:91]
	v_mfma_f32_16x16x32_bf16 v[84:87], v[148:151], v[204:207], v[84:87]
	v_mfma_f32_16x16x32_bf16 v[80:83], v[156:159], v[204:207], v[80:83]
	v_mfma_f32_16x16x32_bf16 v[124:127], v[152:155], v[184:187], v[124:127]
	v_mfma_f32_16x16x32_bf16 v[120:123], v[160:163], v[184:187], v[120:123]
	v_mfma_f32_16x16x32_bf16 v[116:119], v[152:155], v[192:195], v[116:119]
	v_mfma_f32_16x16x32_bf16 v[112:115], v[160:163], v[192:195], v[112:115]
	v_mfma_f32_16x16x32_bf16 v[92:95], v[152:155], v[200:203], v[92:95]
	v_mfma_f32_16x16x32_bf16 v[88:91], v[160:163], v[200:203], v[88:91]
	v_mfma_f32_16x16x32_bf16 v[84:87], v[152:155], v[208:211], v[84:87]
	v_mfma_f32_16x16x32_bf16 v[80:83], v[160:163], v[208:211], v[80:83]
	s_setprio 0
	s_setprio 1
	v_mfma_f32_16x16x32_bf16 v[108:111], v[164:167], v[180:183], v[108:111]
	v_mfma_f32_16x16x32_bf16 v[104:107], v[172:175], v[180:183], v[104:107]
	v_mfma_f32_16x16x32_bf16 v[100:103], v[164:167], v[188:191], v[100:103]
	v_mfma_f32_16x16x32_bf16 v[96:99], v[172:175], v[188:191], v[96:99]
	v_mfma_f32_16x16x32_bf16 v[76:79], v[164:167], v[196:199], v[76:79]
	v_mfma_f32_16x16x32_bf16 v[72:75], v[172:175], v[196:199], v[72:75]
	v_mfma_f32_16x16x32_bf16 v[68:71], v[164:167], v[204:207], v[68:71]
	v_mfma_f32_16x16x32_bf16 v[64:67], v[172:175], v[204:207], v[64:67]
	v_mfma_f32_16x16x32_bf16 v[108:111], v[168:171], v[184:187], v[108:111]
	v_mfma_f32_16x16x32_bf16 v[104:107], v[176:179], v[184:187], v[104:107]
	v_mfma_f32_16x16x32_bf16 v[100:103], v[168:171], v[192:195], v[100:103]
	v_mfma_f32_16x16x32_bf16 v[96:99], v[176:179], v[192:195], v[96:99]
	v_mfma_f32_16x16x32_bf16 v[76:79], v[168:171], v[200:203], v[76:79]
	v_mfma_f32_16x16x32_bf16 v[72:75], v[176:179], v[200:203], v[72:75]
	v_mfma_f32_16x16x32_bf16 v[68:71], v[168:171], v[208:211], v[68:71]
	v_mfma_f32_16x16x32_bf16 v[64:67], v[176:179], v[208:211], v[64:67]
	s_setprio 0
	s_barrier
	s_add_i32 s3, s45, s36
	s_add_u32 s98, s26, s12
	s_addc_u32 s99, s27, s13
	s_mov_b32 m0, s3
	ds_read_b128 v[180:183], v147 offset:16384
	ds_read_b128 v[184:187], v147 offset:17408
	ds_read_b128 v[188:191], v147 offset:18432
	ds_read_b128 v[192:195], v147 offset:19456
	ds_read_b128 v[196:199], v147 offset:20480
	ds_read_b128 v[200:203], v147 offset:21504
	ds_read_b128 v[204:207], v147 offset:22528
	ds_read_b128 v[208:211], v147 offset:23552
	global_load_lds_dwordx4 v128, s[26:27]
	s_add_i32 m0, s3, 0x2000
	s_add_u32 s58, s26, 0x160000
	s_addc_u32 s59, s27, 0
	s_add_i32 s3, s46, s36
	global_load_lds_dwordx4 v130, s[26:27]
	s_mov_b32 m0, s3
	s_nop 0
	global_load_lds_dwordx4 v128, s[58:59]
	s_add_i32 m0, s3, 0x2000
	s_nop 0
	global_load_lds_dwordx4 v130, s[58:59]
	s_add_u32 s100, s28, s12
	s_addc_u32 s101, s29, s13
	s_mov_b32 m0, s37
	s_nop 0
	global_load_lds_dwordx4 v128, s[28:29]
	s_mov_b32 m0, s38
	s_nop 0
	global_load_lds_dwordx4 v130, s[28:29]
	s_waitcnt vmcnt(8)
	s_waitcnt lgkmcnt(0)
	s_barrier
	s_setprio 1
	s_waitcnt lgkmcnt(0)
	v_mfma_f32_16x16x32_bf16 v[60:63], v[148:151], v[180:183], v[60:63]
	v_mfma_f32_16x16x32_bf16 v[56:59], v[156:159], v[180:183], v[56:59]
	v_mfma_f32_16x16x32_bf16 v[52:55], v[148:151], v[188:191], v[52:55]
	v_mfma_f32_16x16x32_bf16 v[48:51], v[156:159], v[188:191], v[48:51]
	v_mfma_f32_16x16x32_bf16 v[28:31], v[148:151], v[196:199], v[28:31]
	v_mfma_f32_16x16x32_bf16 v[24:27], v[156:159], v[196:199], v[24:27]
	v_mfma_f32_16x16x32_bf16 v[20:23], v[148:151], v[204:207], v[20:23]
	v_mfma_f32_16x16x32_bf16 v[16:19], v[156:159], v[204:207], v[16:19]
	v_mfma_f32_16x16x32_bf16 v[60:63], v[152:155], v[184:187], v[60:63]
	v_mfma_f32_16x16x32_bf16 v[56:59], v[160:163], v[184:187], v[56:59]
	v_mfma_f32_16x16x32_bf16 v[52:55], v[152:155], v[192:195], v[52:55]
	v_mfma_f32_16x16x32_bf16 v[48:51], v[160:163], v[192:195], v[48:51]
	v_mfma_f32_16x16x32_bf16 v[28:31], v[152:155], v[200:203], v[28:31]
	v_mfma_f32_16x16x32_bf16 v[24:27], v[160:163], v[200:203], v[24:27]
	v_mfma_f32_16x16x32_bf16 v[20:23], v[152:155], v[208:211], v[20:23]
	v_mfma_f32_16x16x32_bf16 v[16:19], v[160:163], v[208:211], v[16:19]
	s_setprio 0
	s_setprio 1
	v_mfma_f32_16x16x32_bf16 v[44:47], v[164:167], v[180:183], v[44:47]
	v_mfma_f32_16x16x32_bf16 v[40:43], v[172:175], v[180:183], v[40:43]
	v_mfma_f32_16x16x32_bf16 v[36:39], v[164:167], v[188:191], v[36:39]
	v_mfma_f32_16x16x32_bf16 v[32:35], v[172:175], v[188:191], v[32:35]
	v_mfma_f32_16x16x32_bf16 v[12:15], v[164:167], v[196:199], v[12:15]
	v_mfma_f32_16x16x32_bf16 v[8:11], v[172:175], v[196:199], v[8:11]
	v_mfma_f32_16x16x32_bf16 v[4:7], v[164:167], v[204:207], v[4:7]
	v_mfma_f32_16x16x32_bf16 v[0:3], v[172:175], v[204:207], v[0:3]
	v_mfma_f32_16x16x32_bf16 v[44:47], v[168:171], v[184:187], v[44:47]
	v_mfma_f32_16x16x32_bf16 v[40:43], v[176:179], v[184:187], v[40:43]
	v_mfma_f32_16x16x32_bf16 v[36:39], v[168:171], v[192:195], v[36:39]
	v_mfma_f32_16x16x32_bf16 v[32:35], v[176:179], v[192:195], v[32:35]
	v_mfma_f32_16x16x32_bf16 v[12:15], v[168:171], v[200:203], v[12:15]
	v_mfma_f32_16x16x32_bf16 v[8:11], v[176:179], v[200:203], v[8:11]
	v_mfma_f32_16x16x32_bf16 v[4:7], v[168:171], v[208:211], v[4:7]
	v_mfma_f32_16x16x32_bf16 v[0:3], v[176:179], v[208:211], v[0:3]
	s_setprio 0
	s_barrier
; #define PG8_STAGE(bufoff, gbase, voff) do { _Pragma("unroll") for (int _i = 0; _i < 2; ++_i) \
;         __builtin_amdgcn_global_load_lds((const unsigned*)((const char*)(gbase) + (voff)[_i]), (LAS unsigned*)(lds + (bufoff) + ldsw + _i * 8192), 16, 0, 0); } while (0)
; #define PG8_LDA(dst, b, h) do { _Pragma("unroll") for (int m = 0; m < 4; ++m) _Pragma("unroll") for (int k = 0; k < 2; ++k) dst[m][k] = *(const LAS bf16x8*)(lds + PG8_SA(b, h) + aoff + m * 2048 + k * 1024); } while (0)
; #define PG8_LDB(dst, b, h) do { _Pragma("unroll") for (int n = 0; n < 2; ++n) _Pragma("unroll") for (int k = 0; k < 2; ++k) dst[n][k] = *(const LAS bf16x8*)(lds + PG8_SB(b, h) + boff + n * 2048 + k * 1024); } while (0)
; #define PG8_WAIT_V(n) asm volatile("s_waitcnt vmcnt(" #n ")" ::: "memory")
; template <class Epi, class Sched, bool SP2 = PG8_SP2>
; __device__ __forceinline__ void gemm_phase(LAS unsigned char* lds, const Gemm g, const Sched& S, const Epi& E) {
;     ...
;         for (int t = 0; t < nt; t += 2) {
;             const bool last = (t == nt - 2);
;             const char* a1 = cA + (size_t)(t + 1) * kstep;
;             const char* a2 = last ? nA : cA + (size_t)(t + 2) * kstep; const char* b2 = last ? nB : cB + (size_t)(t + 2) * kstep;
;             const char* a3 = a2 + kstep; const char* b3 = b2 + kstep;
;             if constexpr (SP2) {
;             PG8_LDB(B0, 0, 0); PG8_LDB(B1, 0, 1); PG8_SCHED; PG8_LDA(At, 0, 0); PG8_STAGE(PG8_SA(1, 1), a1 + hstepA, voffA);
;             PG8_WAIT_V(8); PG8_WAIT_L(0); PG8_BAR; PG8_MMA(0, 0, At, B0); PG8_MMA(0, 1, At, B1); PG8_BAR; PG8_SCHED;
;             PG8_LDA(At, 0, 1); PG8_STAGE(PG8_SB(0, 0), b2, voffB); PG8_STAGE(PG8_SB(0, 1), b2 + hstepB, voffB); PG8_STAGE(PG8_SA(0, 0), a2, voffA);
;             PG8_WAIT_V(8); PG8_WAIT_L(0); PG8_BAR; PG8_MMA(1, 0, At, B0); PG8_MMA(1, 1, At, B1); PG8_BAR; PG8_SCHED;
;             PG8_LDB(B0, 1, 0); PG8_LDB(B1, 1, 1); PG8_SCHED; PG8_LDA(At, 1, 0); PG8_STAGE(PG8_SA(0, 1), a2 + hstepA, voffA);
;             PG8_WAIT_V(8); PG8_WAIT_L(0); PG8_BAR; PG8_MMA(0, 0, At, B0); PG8_MMA(0, 1, At, B1); PG8_BAR; PG8_SCHED;
;             PG8_LDA(At, 1, 1); PG8_STAGE(PG8_SB(1, 0), b3, voffB); PG8_STAGE(PG8_SB(1, 1), b3 + hstepB, voffB); PG8_STAGE(PG8_SA(1, 0), a3, voffA);
;             PG8_WAIT_V(8); PG8_WAIT_L(0); PG8_BAR; PG8_MMA(1, 0, At, B0); PG8_MMA(1, 1, At, B1); PG8_BAR; PG8_SCHED;
	s_add_i32 s3, 0, 0x18000
	s_add_i32 s57, 0, 0x1c000
	v_add_u32_e32 v160, s3, v143
	v_add_u32_e32 v176, s57, v143
	ds_read_b128 v[148:151], v160
	ds_read_b128 v[152:155], v160 offset:1024
	ds_read_b128 v[156:159], v160 offset:2048
	ds_read_b128 v[160:163], v160 offset:3072
	ds_read_b128 v[164:167], v176
	ds_read_b128 v[168:171], v176 offset:1024
	ds_read_b128 v[172:175], v176 offset:2048
	ds_read_b128 v[176:179], v176 offset:3072
	s_add_u32 s28, s28, 0x160000
	s_addc_u32 s29, s29, 0
	s_mov_b32 m0, s39
	ds_read_b128 v[180:183], v147 offset:32768
	ds_read_b128 v[184:187], v147 offset:33792
	ds_read_b128 v[188:191], v147 offset:34816
	ds_read_b128 v[192:195], v147 offset:35840
	ds_read_b128 v[196:199], v147 offset:36864
	ds_read_b128 v[200:203], v147 offset:37888
	ds_read_b128 v[204:207], v147 offset:38912
	ds_read_b128 v[208:211], v147 offset:39936
	global_load_lds_dwordx4 v128, s[28:29]
	s_mov_b32 m0, s40
	s_nop 0
	global_load_lds_dwordx4 v130, s[28:29]
	s_waitcnt vmcnt(8)
	s_waitcnt lgkmcnt(0)
	s_barrier
	s_setprio 1
	s_waitcnt lgkmcnt(0)
	v_mfma_f32_16x16x32_bf16 v[124:127], v[148:151], v[180:183], v[124:127]
	v_mfma_f32_16x16x32_bf16 v[120:123], v[156:159], v[180:183], v[120:123]
	v_mfma_f32_16x16x32_bf16 v[116:119], v[148:151], v[188:191], v[116:119]
	v_mfma_f32_16x16x32_bf16 v[112:115], v[156:159], v[188:191], v[112:115]
	v_mfma_f32_16x16x32_bf16 v[92:95], v[148:151], v[196:199], v[92:95]
	v_mfma_f32_16x16x32_bf16 v[88:91], v[156:159], v[196:199], v[88:91]
	v_mfma_f32_16x16x32_bf16 v[84:87], v[148:151], v[204:207], v[84:87]
	v_mfma_f32_16x16x32_bf16 v[80:83], v[156:159], v[204:207], v[80:83]
	v_mfma_f32_16x16x32_bf16 v[124:127], v[152:155], v[184:187], v[124:127]
	v_mfma_f32_16x16x32_bf16 v[120:123], v[160:163], v[184:187], v[120:123]
	v_mfma_f32_16x16x32_bf16 v[116:119], v[152:155], v[192:195], v[116:119]
	v_mfma_f32_16x16x32_bf16 v[112:115], v[160:163], v[192:195], v[112:115]
	v_mfma_f32_16x16x32_bf16 v[92:95], v[152:155], v[200:203], v[92:95]
	v_mfma_f32_16x16x32_bf16 v[88:91], v[160:163], v[200:203], v[88:91]
	v_mfma_f32_16x16x32_bf16 v[84:87], v[152:155], v[208:211], v[84:87]
	v_mfma_f32_16x16x32_bf16 v[80:83], v[160:163], v[208:211], v[80:83]
	s_setprio 0
	s_setprio 1
	v_mfma_f32_16x16x32_bf16 v[108:111], v[164:167], v[180:183], v[108:111]
	v_mfma_f32_16x16x32_bf16 v[104:107], v[172:175], v[180:183], v[104:107]
	v_mfma_f32_16x16x32_bf16 v[100:103], v[164:167], v[188:191], v[100:103]
	v_mfma_f32_16x16x32_bf16 v[96:99], v[172:175], v[188:191], v[96:99]
	v_mfma_f32_16x16x32_bf16 v[76:79], v[164:167], v[196:199], v[76:79]
	v_mfma_f32_16x16x32_bf16 v[72:75], v[172:175], v[196:199], v[72:75]
	v_mfma_f32_16x16x32_bf16 v[68:71], v[164:167], v[204:207], v[68:71]
	v_mfma_f32_16x16x32_bf16 v[64:67], v[172:175], v[204:207], v[64:67]
	v_mfma_f32_16x16x32_bf16 v[108:111], v[168:171], v[184:187], v[108:111]
	v_mfma_f32_16x16x32_bf16 v[104:107], v[176:179], v[184:187], v[104:107]
	v_mfma_f32_16x16x32_bf16 v[100:103], v[168:171], v[192:195], v[100:103]
	v_mfma_f32_16x16x32_bf16 v[96:99], v[176:179], v[192:195], v[96:99]
	v_mfma_f32_16x16x32_bf16 v[76:79], v[168:171], v[200:203], v[76:79]
	v_mfma_f32_16x16x32_bf16 v[72:75], v[176:179], v[200:203], v[72:75]
	v_mfma_f32_16x16x32_bf16 v[68:71], v[168:171], v[208:211], v[68:71]
	v_mfma_f32_16x16x32_bf16 v[64:67], v[176:179], v[208:211], v[64:67]
	s_setprio 0
	s_barrier
	s_add_i32 s3, s3, s36
	s_mov_b32 m0, s3
	ds_read_b128 v[180:183], v147 offset:49152
	ds_read_b128 v[184:187], v147 offset:50176
	ds_read_b128 v[188:191], v147 offset:51200
	ds_read_b128 v[192:195], v147 offset:52224
	ds_read_b128 v[196:199], v147 offset:53248
	ds_read_b128 v[200:203], v147 offset:54272
	ds_read_b128 v[204:207], v147 offset:55296
	ds_read_b128 v[208:211], v147 offset:56320
	global_load_lds_dwordx4 v128, s[98:99]
	s_add_i32 m0, s3, 0x2000
	s_add_u32 s26, s26, 0x160080
	s_addc_u32 s27, s27, 0
	s_add_i32 s3, s57, s36
	global_load_lds_dwordx4 v130, s[98:99]
	s_mov_b32 m0, s3
	s_nop 0
	global_load_lds_dwordx4 v128, s[26:27]
	s_add_i32 m0, s3, 0x2000
	s_nop 0
	global_load_lds_dwordx4 v130, s[26:27]
	s_mov_b32 m0, s42
	s_nop 0
	global_load_lds_dwordx4 v128, s[100:101]
	s_mov_b32 m0, s43
	s_nop 0
	global_load_lds_dwordx4 v130, s[100:101]
	s_waitcnt vmcnt(8)
	s_waitcnt lgkmcnt(0)
	s_barrier
	s_setprio 1
	s_waitcnt lgkmcnt(0)
	v_mfma_f32_16x16x32_bf16 v[60:63], v[148:151], v[180:183], v[60:63]
	v_mfma_f32_16x16x32_bf16 v[56:59], v[156:159], v[180:183], v[56:59]
	v_mfma_f32_16x16x32_bf16 v[52:55], v[148:151], v[188:191], v[52:55]
	v_mfma_f32_16x16x32_bf16 v[48:51], v[156:159], v[188:191], v[48:51]
	v_mfma_f32_16x16x32_bf16 v[28:31], v[148:151], v[196:199], v[28:31]
	v_mfma_f32_16x16x32_bf16 v[24:27], v[156:159], v[196:199], v[24:27]
	v_mfma_f32_16x16x32_bf16 v[20:23], v[148:151], v[204:207], v[20:23]
	v_mfma_f32_16x16x32_bf16 v[16:19], v[156:159], v[204:207], v[16:19]
	v_mfma_f32_16x16x32_bf16 v[60:63], v[152:155], v[184:187], v[60:63]
	v_mfma_f32_16x16x32_bf16 v[56:59], v[160:163], v[184:187], v[56:59]
	v_mfma_f32_16x16x32_bf16 v[52:55], v[152:155], v[192:195], v[52:55]
	v_mfma_f32_16x16x32_bf16 v[48:51], v[160:163], v[192:195], v[48:51]
	v_mfma_f32_16x16x32_bf16 v[28:31], v[152:155], v[200:203], v[28:31]
	v_mfma_f32_16x16x32_bf16 v[24:27], v[160:163], v[200:203], v[24:27]
	v_mfma_f32_16x16x32_bf16 v[20:23], v[152:155], v[208:211], v[20:23]
	v_mfma_f32_16x16x32_bf16 v[16:19], v[160:163], v[208:211], v[16:19]
	s_setprio 0
	s_setprio 1
	v_mfma_f32_16x16x32_bf16 v[44:47], v[164:167], v[180:183], v[44:47]
	v_mfma_f32_16x16x32_bf16 v[40:43], v[172:175], v[180:183], v[40:43]
	v_mfma_f32_16x16x32_bf16 v[36:39], v[164:167], v[188:191], v[36:39]
	v_mfma_f32_16x16x32_bf16 v[32:35], v[172:175], v[188:191], v[32:35]
	v_mfma_f32_16x16x32_bf16 v[12:15], v[164:167], v[196:199], v[12:15]
	v_mfma_f32_16x16x32_bf16 v[8:11], v[172:175], v[196:199], v[8:11]
	v_mfma_f32_16x16x32_bf16 v[4:7], v[164:167], v[204:207], v[4:7]
	v_mfma_f32_16x16x32_bf16 v[0:3], v[172:175], v[204:207], v[0:3]
	v_mfma_f32_16x16x32_bf16 v[44:47], v[168:171], v[184:187], v[44:47]
	v_mfma_f32_16x16x32_bf16 v[40:43], v[176:179], v[184:187], v[40:43]
	v_mfma_f32_16x16x32_bf16 v[36:39], v[168:171], v[192:195], v[36:39]
	v_mfma_f32_16x16x32_bf16 v[32:35], v[176:179], v[192:195], v[32:35]
	v_mfma_f32_16x16x32_bf16 v[12:15], v[168:171], v[200:203], v[12:15]
	v_mfma_f32_16x16x32_bf16 v[8:11], v[176:179], v[200:203], v[8:11]
	v_mfma_f32_16x16x32_bf16 v[4:7], v[168:171], v[208:211], v[4:7]
	v_mfma_f32_16x16x32_bf16 v[0:3], v[176:179], v[208:211], v[0:3]
	s_setprio 0
	s_barrier
	s_add_i32 s56, s56, 2
	s_add_u32 s24, s24, 0x100
	s_addc_u32 s25, s25, 0
	s_add_u32 s2, s2, 0x100
	s_addc_u32 s55, s55, 0
	s_cmpk_gt_u32 s56, 0x55
	s_cbranch_scc0 .LBB0_1090
	s_and_b64 vcc, exec, s[14:15]
	s_cbranch_vccz .LBB0_1093
	s_barrier

; #define LAS __attribute__((address_space(3)))
; __global__ void __launch_bounds__(512, 2) mk_fwd(Params p) {
;     extern __shared__ __attribute__((aligned(16))) unsigned char lds[];
;     Frame F;
;     F.lds = (LAS unsigned char*)lds;
;     F.tid = threadIdx.x; F.lane = F.tid & 63; F.wave = __builtin_amdgcn_readfirstlane(F.tid >> 6);
;     F.G = gridDim.x; { const int bx = blockIdx.x; F.vcu = (F.G % 8 == 0) ? (bx % 8) * (F.G / 8) + bx / 8 : bx; }
;     unsigned char* ws = p.ws;
;     const int lo = p.ph_lo, hi = p.ph_hi;
;     volatile LAS unsigned* MISC = (volatile LAS unsigned*)(F.lds + 131072 + 320);
;     if (F.tid < 32) MISC[F.tid] = 0u;
;     __syncthreads();
;     XcdBarrier bar = xcd_barrier_post((unsigned*)ws, MISC + 8);
	.amdhsa_kernel _Z6mk_fwd6Params
		.amdhsa_group_segment_fixed_size 0
		.amdhsa_private_segment_fixed_size 0
		.amdhsa_kernarg_size 592
		.amdhsa_user_sgpr_count 2
		.amdhsa_user_sgpr_dispatch_ptr 0
		.amdhsa_user_sgpr_queue_ptr 0
		.amdhsa_user_sgpr_kernarg_segment_ptr 1
		.amdhsa_user_sgpr_dispatch_id 0
		.amdhsa_user_sgpr_kernarg_preload_length 0
		.amdhsa_user_sgpr_kernarg_preload_offset 0
		.amdhsa_user_sgpr_private_segment_size 0
		.amdhsa_uses_dynamic_stack 0
		.amdhsa_enable_private_segment 0
		.amdhsa_system_sgpr_workgroup_id_x 1
		.amdhsa_system_sgpr_workgroup_id_y 0
		.amdhsa_system_sgpr_workgroup_id_z 0
		.amdhsa_system_sgpr_workgroup_info 0
		.amdhsa_system_vgpr_workitem_id 2
		.amdhsa_next_free_vgpr 241
		.amdhsa_next_free_sgpr 102
		.amdhsa_accum_offset 244
		.amdhsa_reserve_vcc 1
		.amdhsa_float_round_mode_32 0
		.amdhsa_float_round_mode_16_64 0
		.amdhsa_float_denorm_mode_32 3
		.amdhsa_float_denorm_mode_16_64 3
		.amdhsa_dx10_clamp 1
		.amdhsa_ieee_mode 1
		.amdhsa_fp16_overflow 0
		.amdhsa_tg_split 0
		.amdhsa_exception_fp_ieee_invalid_op 0
		.amdhsa_exception_fp_denorm_src 0
		.amdhsa_exception_fp_ieee_div_zero 0
		.amdhsa_exception_fp_ieee_overflow 0
		.amdhsa_exception_fp_ieee_underflow 0
		.amdhsa_exception_fp_ieee_inexact 0
		.amdhsa_exception_int_div_zero 0
	.end_amdhsa_kernel

; #define LAS __attribute__((address_space(3)))
; __global__ void __launch_bounds__(512, 2) mk_fwd(Params p) {
;     extern __shared__ __attribute__((aligned(16))) unsigned char lds[];
;     Frame F;
;     F.lds = (LAS unsigned char*)lds;
;     F.tid = threadIdx.x; F.lane = F.tid & 63; F.wave = __builtin_amdgcn_readfirstlane(F.tid >> 6);
;     F.G = gridDim.x; { const int bx = blockIdx.x; F.vcu = (F.G % 8 == 0) ? (bx % 8) * (F.G / 8) + bx / 8 : bx; }
;     unsigned char* ws = p.ws;
;     const int lo = p.ph_lo, hi = p.ph_hi;
;     volatile LAS unsigned* MISC = (volatile LAS unsigned*)(F.lds + 131072 + 320);
;     if (F.tid < 32) MISC[F.tid] = 0u;
;     __syncthreads();
;     XcdBarrier bar = xcd_barrier_post((unsigned*)ws, MISC + 8);
amdhsa.kernels:
  - .agpr_count:     0
    .args:
      - .offset:         0
        .size:           336
        .value_kind:     by_value
      - .offset:         336
        .size:           4
        .value_kind:     hidden_block_count_x
      - .offset:         340
        .size:           4
        .value_kind:     hidden_block_count_y
      - .offset:         344
        .size:           4
        .value_kind:     hidden_block_count_z
      - .offset:         348
        .size:           2
        .value_kind:     hidden_group_size_x
      - .offset:         350
        .size:           2
        .value_kind:     hidden_group_size_y
      - .offset:         352
        .size:           2
        .value_kind:     hidden_group_size_z
      - .offset:         354
        .size:           2
        .value_kind:     hidden_remainder_x
      - .offset:         356
        .size:           2
        .value_kind:     hidden_remainder_y
      - .offset:         358
        .size:           2
        .value_kind:     hidden_remainder_z
      - .offset:         376
        .size:           8
        .value_kind:     hidden_global_offset_x
      - .offset:         384
        .size:           8
        .value_kind:     hidden_global_offset_y
      - .offset:         392
        .size:           8
        .value_kind:     hidden_global_offset_z
      - .offset:         400
        .size:           2
        .value_kind:     hidden_grid_dims
      - .offset:         424
        .size:           8
        .value_kind:     hidden_multigrid_sync_arg
      - .offset:         456
        .size:           4
        .value_kind:     hidden_dynamic_lds_size
    .group_segment_fixed_size: 0
    .kernarg_segment_align: 8
    .kernarg_segment_size: 592
    .language:       OpenCL C
    .language_version:
      - 2
      - 0
    .max_flat_workgroup_size: 512
    .name:           _Z6mk_fwd6Params
    .private_segment_fixed_size: 0
    .sgpr_count:     108
    .sgpr_spill_count: 36
    .symbol:         _Z6mk_fwd6Params.kd
    .uniform_work_group_size: 1
    .uses_dynamic_stack: false
    .vgpr_count:     241
    .vgpr_spill_count: 0
    .wavefront_size: 64
